# batched serialized global loads: conv y-loop, gmlp row stats, outproj residual epilogue, transpose_tile; dot8 VOP3P zero-init; NA bias gathers batched
# speedup vs baseline: 1.0538x; 1.0351x over previous
.LBB0_59:
	s_mul_hi_i32 s0, s6, 0x66666667
	s_lshr_b32 s1, s0, 31
	s_ashr_i32 s0, s0, 8
	s_add_i32 s0, s0, s1
	s_mul_i32 s1, s0, 0xfffffd80
	s_add_i32 s1, s6, s1
	s_mul_i32 s2, s1, 0x6667
	s_lshr_b32 s3, s2, 31
	s_ashr_i32 s2, s2, 20
	s_add_i32 s2, s2, s3
	s_sext_i32_i16 s4, s2
	s_mul_i32 s2, s2, 40
	s_sub_i32 s1, s1, s2
	s_sext_i32_i16 s5, s1
	s_mul_hi_i32 s1, s0, 0x280000
	s_mul_i32 s0, s0, 0x280000
	s_lshl_b64 s[2:3], s[0:1], 2
	s_add_u32 s7, s76, s2
	s_addc_u32 s3, s77, s3
	s_lshl_b64 s[0:1], s[0:1], 1
	s_add_u32 s0, s94, s0
	s_addc_u32 s1, s95, s1
	s_lshl_b32 s2, s4, 6
	s_lshl_b32 s4, s5, 6
	s_ashr_i32 s5, s4, 31
	v_mov_b32_e32 v6, v218
	s_lshl_b64 s[8:9], s[4:5], 2
	s_add_u32 s8, s7, s8
	v_lshlrev_b32_e32 v0, 2, v6
	v_ashrrev_i32_e32 v7, 6, v6
	s_addc_u32 s9, s3, s9
	v_and_b32_e32 v0, 0xfc, v0
	v_lshl_add_u64 v[2:3], s[8:9], 0, v[0:1]
	v_add_u32_e32 v10, s2, v7
	v_mad_i64_i32 v[4:5], s[8:9], v10, s38, v[2:3]
	global_load_dword v100, v[4:5], off
	v_mad_u64_u32 v[4:5], s[8:9], v7, s10, v[0:1]
	v_add_u32_e32 v0, 4, v10
	s_ashr_i32 s3, s2, 31
	s_add_i32 s6, s6, s18
	s_cmpk_gt_i32 s6, 0x27f
	v_mad_i64_i32 v[8:9], s[8:9], v0, s38, v[2:3]
	global_load_dword v101, v[8:9], off
	v_add_u32_e32 v0, 8, v10
	v_mad_i64_i32 v[8:9], s[8:9], v0, s38, v[2:3]
	global_load_dword v102, v[8:9], off
	v_add_u32_e32 v0, 12, v10
	v_mad_i64_i32 v[8:9], s[8:9], v0, s38, v[2:3]
	global_load_dword v103, v[8:9], off
	v_add_u32_e32 v0, 16, v10
	v_mad_i64_i32 v[8:9], s[8:9], v0, s38, v[2:3]
	global_load_dword v104, v[8:9], off
	v_add_u32_e32 v0, 20, v10
	v_mad_i64_i32 v[8:9], s[8:9], v0, s38, v[2:3]
	global_load_dword v105, v[8:9], off
	v_add_u32_e32 v0, 24, v10
	v_mad_i64_i32 v[8:9], s[8:9], v0, s38, v[2:3]
	global_load_dword v106, v[8:9], off
	v_add_u32_e32 v0, 28, v10
	v_mad_i64_i32 v[8:9], s[8:9], v0, s38, v[2:3]
	global_load_dword v107, v[8:9], off
	v_add_u32_e32 v0, 32, v10
	v_mad_i64_i32 v[8:9], s[8:9], v0, s38, v[2:3]
	global_load_dword v108, v[8:9], off
	v_add_u32_e32 v0, 36, v10
	v_mad_i64_i32 v[8:9], s[8:9], v0, s38, v[2:3]
	global_load_dword v109, v[8:9], off
	v_add_u32_e32 v0, 40, v10
	v_mad_i64_i32 v[8:9], s[8:9], v0, s38, v[2:3]
	global_load_dword v110, v[8:9], off
	v_add_u32_e32 v0, 44, v10
	v_mad_i64_i32 v[8:9], s[8:9], v0, s38, v[2:3]
	global_load_dword v111, v[8:9], off
	v_add_u32_e32 v0, 48, v10
	v_mad_i64_i32 v[8:9], s[8:9], v0, s38, v[2:3]
	global_load_dword v112, v[8:9], off
	v_add_u32_e32 v0, 52, v10
	v_mad_i64_i32 v[8:9], s[8:9], v0, s38, v[2:3]
	global_load_dword v113, v[8:9], off
	v_add_u32_e32 v0, 56, v10
	v_mad_i64_i32 v[8:9], s[8:9], v0, s38, v[2:3]
	global_load_dword v114, v[8:9], off
	v_add_u32_e32 v0, 60, v10
	v_mad_i64_i32 v[2:3], s[8:9], v0, s38, v[2:3]
	global_load_dword v115, v[2:3], off
	v_lshlrev_b32_e32 v2, 4, v6
	v_and_b32_e32 v22, 48, v2
	v_and_b32_e32 v2, -4, v6
	v_mad_u32_u24 v14, v22, s10, v2
	v_add_u32_e32 v8, 0x400, v14
	v_add_u32_e32 v12, 0x800, v14
	v_add_u32_e32 v16, 0xc00, v14
	s_waitcnt vmcnt(0)
	ds_write_b32 v4, v100
	ds_write_b32 v4, v101 offset:1040
	ds_write_b32 v4, v102 offset:2080
	ds_write_b32 v4, v103 offset:3120
	ds_write_b32 v4, v104 offset:4160
	ds_write_b32 v4, v105 offset:5200
	ds_write_b32 v4, v106 offset:6240
	ds_write_b32 v4, v107 offset:7280
	ds_write_b32 v4, v108 offset:8320
	ds_write_b32 v4, v109 offset:9360
	ds_write_b32 v4, v110 offset:10400
	ds_write_b32 v4, v111 offset:11440
	ds_write_b32 v4, v112 offset:12480
	ds_write_b32 v4, v113 offset:13520
	ds_write_b32 v4, v114 offset:14560
	ds_write_b32 v4, v115 offset:15600
	v_ashrrev_i32_e32 v0, 2, v6
	s_waitcnt lgkmcnt(0)
	s_barrier
	ds_read2_b32 v[2:3], v14 offset1:65
	ds_read2_b32 v[4:5], v14 offset0:130 offset1:195
	ds_read2_b32 v[6:7], v8 offset0:4 offset1:69
	ds_read2_b32 v[8:9], v8 offset0:134 offset1:199
	v_add_u32_e32 v20, s4, v0
	ds_read2_b32 v[10:11], v12 offset0:8 offset1:73
	ds_read2_b32 v[12:13], v12 offset0:138 offset1:203
	ds_read2_b32 v[14:15], v16 offset0:12 offset1:77
	ds_read2_b32 v[16:17], v16 offset0:142 offset1:207
	v_ashrrev_i32_e32 v21, 31, v20
	v_lshlrev_b64 v[20:21], 11, v[20:21]
	v_lshl_add_u64 v[20:21], s[0:1], 0, v[20:21]
	v_lshl_add_u64 v[20:21], s[2:3], 1, v[20:21]
	v_lshlrev_b32_e32 v0, 1, v22
	v_lshl_add_u64 v[20:21], v[20:21], 0, v[0:1]
	s_waitcnt lgkmcnt(7)
	v_cvt_pk_bf16_f32 v2, v2, v3
	s_waitcnt lgkmcnt(6)
	v_cvt_pk_bf16_f32 v3, v4, v5
	s_waitcnt lgkmcnt(5)
	v_cvt_pk_bf16_f32 v4, v6, v7
	s_waitcnt lgkmcnt(4)
	v_cvt_pk_bf16_f32 v5, v8, v9
	global_store_dwordx4 v[20:21], v[2:5], off
	s_waitcnt lgkmcnt(3)
	s_nop 0
	v_cvt_pk_bf16_f32 v2, v10, v11
	s_waitcnt lgkmcnt(2)
	v_cvt_pk_bf16_f32 v3, v12, v13
	s_waitcnt lgkmcnt(1)
	v_cvt_pk_bf16_f32 v4, v14, v15
	s_waitcnt lgkmcnt(0)
	v_cvt_pk_bf16_f32 v5, v16, v17
	global_store_dwordx4 v[20:21], v[2:5], off offset:16
	s_barrier
	s_cbranch_scc0 .LBB0_59

.LBB0_100:
	v_readlane_b32 s6, v254, 14
	s_nop 3
	s_add_i32 s9, s9, s6
	v_readlane_b32 s6, v254, 18
	s_nop 3
	s_add_i32 s8, s8, s6
	s_and_b64 vcc, exec, s[4:5]
	v_readlane_b32 s7, v254, 15
	s_cbranch_vccnz .LBB0_236

.LBB0_109:
	ds_write2_b32 v149, v50, v34 offset1:32
	ds_write2_b32 v149, v51, v35 offset0:132 offset1:164
	v_add_u32_e32 v34, 0x400, v149
	ds_write2_b32 v34, v52, v36 offset0:8 offset1:40
	ds_write2_b32 v34, v53, v37 offset0:140 offset1:172
	v_add_u32_e32 v34, 0x1000, v149
	ds_write2_b32 v34, v54, v38 offset0:32 offset1:64
	ds_write2_b32 v34, v55, v39 offset0:164 offset1:196
	v_add_u32_e32 v34, 0x1400, v149
	ds_write2_b32 v34, v56, v40 offset0:40 offset1:72
	ds_write2_b32 v34, v57, v41 offset0:172 offset1:204
	v_add_u32_e32 v34, 0x2000, v149
	ds_write2_b32 v34, v58, v42 offset0:64 offset1:96
	ds_write2_b32 v34, v59, v43 offset0:196 offset1:228
	v_add_u32_e32 v34, 0x2400, v149
	ds_write2_b32 v34, v60, v44 offset0:72 offset1:104
	ds_write2_b32 v34, v61, v45 offset0:204 offset1:236
	v_add_u32_e32 v34, 0x3000, v149
	ds_write2_b32 v34, v62, v46 offset0:96 offset1:128
	v_add_u32_e32 v34, 0x3200, v149
	ds_write2_b32 v34, v63, v47 offset0:100 offset1:132
	v_add_u32_e32 v34, 0x3400, v149
	ds_write2_b32 v34, v64, v48 offset0:104 offset1:136
	v_add_u32_e32 v34, 0x3600, v149
	ds_write2_b32 v34, v65, v49 offset0:108 offset1:140
	v_add_u32_e32 v34, 0x4000, v149
	s_lshl_b32 s6, s11, 4
	ds_write2_b32 v34, v18, v2 offset0:128 offset1:160
	v_add_u32_e32 v2, 0x4400, v149
	s_and_b32 s12, s6, 0xffffff80
	s_addk_i32 s6, 0xe000
	ds_write2_b32 v2, v19, v3 offset0:4 offset1:36
	ds_write2_b32 v2, v20, v4 offset0:136 offset1:168
	v_add_u32_e32 v2, 0x4800, v149
	s_lshl_b32 s7, s11, 7
	s_lshr_b32 s6, s6, 12
	ds_write2_b32 v2, v21, v5 offset0:12 offset1:44
	v_add_u32_e32 v2, 0x5000, v149
	s_and_b32 s7, s7, 0x380
	s_add_i32 s6, s6, 1
	ds_write2_b32 v2, v22, v6 offset0:160 offset1:192
	v_add_u32_e32 v2, 0x5400, v149
	s_cmpk_gt_i32 s12, 0x1fff
	ds_write2_b32 v2, v23, v7 offset0:36 offset1:68
	ds_write2_b32 v2, v24, v8 offset0:168 offset1:200
	v_add_u32_e32 v2, 0x5800, v149
	s_cselect_b32 s6, s6, 0
	s_mul_i32 s11, s60, 3
	ds_write2_b32 v2, v25, v9 offset0:44 offset1:76
	v_add_u32_e32 v2, 0x6000, v149
	s_add_i32 s6, s6, s11
	ds_write2_b32 v2, v26, v10 offset0:192 offset1:224
	v_add_u32_e32 v2, 0x6400, v149
	s_mul_hi_i32 s11, s6, 0x6000
	s_mulk_i32 s6, 0x6000
	ds_write2_b32 v2, v27, v11 offset0:68 offset1:100
	ds_write2_b32 v2, v28, v12 offset0:200 offset1:232
	v_add_u32_e32 v2, 0x6800, v149
	s_add_u32 s6, s94, s6
	ds_write2_b32 v2, v29, v13 offset0:76 offset1:108
	v_add_u32_e32 v2, 0x7200, v149
	s_addc_u32 s11, s95, s11
	ds_write2_b32 v2, v30, v14 offset0:96 offset1:128
	v_add_u32_e32 v2, 0x7400, v149
	s_lshl_b32 s56, s7, 2
	ds_write2_b32 v2, v31, v15 offset0:100 offset1:132
	v_add_u32_e32 v2, 0x7600, v149
	s_add_u32 s6, s6, s56
	ds_write2_b32 v2, v32, v16 offset0:104 offset1:136
	v_add_u32_e32 v2, 0x7800, v149
	s_addc_u32 s7, s11, 0
	ds_write2_b32 v2, v33, v17 offset0:108 offset1:140
	v_lshl_add_u64 v[2:3], s[6:7], 0, v[0:1]
	v_add_co_u32_e32 v2, vcc, 0x9662000, v2
	s_waitcnt lgkmcnt(0)
	s_nop 0
	v_addc_co_u32_e32 v3, vcc, 0, v3, vcc
	s_barrier
	global_load_dwordx4 v[2:5], v[2:3], off
	s_cmp_lg_u64 s[0:1], 0
	s_cbranch_scc1 .Lop_l1
	s_cmpk_gt_i32 s12, 0x1fff
	s_cbranch_scc1 .Lop_in1
	v_readlane_b32 s6, v250, 2
	v_readlane_b32 s7, v250, 3
	s_mov_b32 s13, s12
	s_branch .Lop_base
.Lop_in1:
	v_readlane_b32 s6, v250, 4
	v_readlane_b32 s7, v250, 5
	s_add_i32 s13, s12, 0xffffe000
	s_branch .Lop_base
.Lop_l1:
	v_readlane_b32 s6, v254, 1
	v_readlane_b32 s7, v254, 2
	s_mov_b32 s13, s12
.Lop_base:
	s_nop 3
	s_lshl_b32 s14, s13, 12
	s_add_u32 s14, s14, s56
	s_add_u32 s6, s6, s14
	s_addc_u32 s7, s7, 0
	v_lshl_add_u32 v110, v150, 12, v0
	global_load_dwordx4 v[6:9], v110, s[6:7]
	s_add_u32 s6, s6, 0x8000
	s_addc_u32 s7, s7, 0
	global_load_dwordx4 v[10:13], v110, s[6:7]
	s_add_u32 s6, s6, 0x8000
	s_addc_u32 s7, s7, 0
	global_load_dwordx4 v[14:17], v110, s[6:7]
	s_add_u32 s6, s6, 0x8000
	s_addc_u32 s7, s7, 0
	global_load_dwordx4 v[18:21], v110, s[6:7]
	s_add_u32 s6, s6, 0x8000
	s_addc_u32 s7, s7, 0
	global_load_dwordx4 v[22:25], v110, s[6:7]
	s_add_u32 s6, s6, 0x8000
	s_addc_u32 s7, s7, 0
	global_load_dwordx4 v[26:29], v110, s[6:7]
	s_add_u32 s6, s6, 0x8000
	s_addc_u32 s7, s7, 0
	global_load_dwordx4 v[30:33], v110, s[6:7]
	s_add_u32 s6, s6, 0x8000
	s_addc_u32 s7, s7, 0
	global_load_dwordx4 v[34:37], v110, s[6:7]
	s_add_u32 s6, s6, 0x8000
	s_addc_u32 s7, s7, 0
	global_load_dwordx4 v[38:41], v110, s[6:7]
	s_add_u32 s6, s6, 0x8000
	s_addc_u32 s7, s7, 0
	global_load_dwordx4 v[42:45], v110, s[6:7]
	s_add_u32 s6, s6, 0x8000
	s_addc_u32 s7, s7, 0
	global_load_dwordx4 v[46:49], v110, s[6:7]
	s_add_u32 s6, s6, 0x8000
	s_addc_u32 s7, s7, 0
	global_load_dwordx4 v[50:53], v110, s[6:7]
	s_add_u32 s6, s6, 0x8000
	s_addc_u32 s7, s7, 0
	global_load_dwordx4 v[54:57], v110, s[6:7]
	s_add_u32 s6, s6, 0x8000
	s_addc_u32 s7, s7, 0
	global_load_dwordx4 v[58:61], v110, s[6:7]
	s_add_u32 s6, s6, 0x8000
	s_addc_u32 s7, s7, 0
	global_load_dwordx4 v[62:65], v110, s[6:7]
	s_add_u32 s6, s6, 0x8000
	s_addc_u32 s7, s7, 0
	global_load_dwordx4 v[98:101], v110, s[6:7]
	v_add_u32_e32 v114, s12, v150
	v_mov_b32_e32 v115, 0
	v_lshlrev_b64 v[114:115], 12, v[114:115]
	v_lshl_add_u64 v[112:113], v[136:137], 0, s[56:57]
	v_lshl_add_u64 v[112:113], v[112:113], 0, v[114:115]
	s_mov_b32 s98, 0x8000
	s_mov_b32 s99, 0
	ds_read_b128 v[102:105], v151
	ds_read_b128 v[106:109], v151 offset:4224
	s_waitcnt vmcnt(15) lgkmcnt(1)
	v_pk_fma_f32 v[6:7], v[2:3], v[102:103], v[6:7]
	v_pk_fma_f32 v[8:9], v[4:5], v[104:105], v[8:9]
	global_store_dwordx4 v[112:113], v[6:9], off
	v_lshl_add_u64 v[112:113], v[112:113], 0, s[98:99]
	ds_read_b128 v[102:105], v151 offset:8448
	s_waitcnt vmcnt(15) lgkmcnt(1)
	v_pk_fma_f32 v[10:11], v[2:3], v[106:107], v[10:11]
	v_pk_fma_f32 v[12:13], v[4:5], v[108:109], v[12:13]
	global_store_dwordx4 v[112:113], v[10:13], off
	v_lshl_add_u64 v[112:113], v[112:113], 0, s[98:99]
	ds_read_b128 v[106:109], v151 offset:12672
	s_waitcnt vmcnt(15) lgkmcnt(1)
	v_pk_fma_f32 v[14:15], v[2:3], v[102:103], v[14:15]
	v_pk_fma_f32 v[16:17], v[4:5], v[104:105], v[16:17]
	global_store_dwordx4 v[112:113], v[14:17], off
	v_lshl_add_u64 v[112:113], v[112:113], 0, s[98:99]
	ds_read_b128 v[102:105], v151 offset:16896
	s_waitcnt vmcnt(15) lgkmcnt(1)
	v_pk_fma_f32 v[18:19], v[2:3], v[106:107], v[18:19]
	v_pk_fma_f32 v[20:21], v[4:5], v[108:109], v[20:21]
	global_store_dwordx4 v[112:113], v[18:21], off
	v_lshl_add_u64 v[112:113], v[112:113], 0, s[98:99]
	ds_read_b128 v[106:109], v151 offset:21120
	s_waitcnt vmcnt(15) lgkmcnt(1)
	v_pk_fma_f32 v[22:23], v[2:3], v[102:103], v[22:23]
	v_pk_fma_f32 v[24:25], v[4:5], v[104:105], v[24:25]
	global_store_dwordx4 v[112:113], v[22:25], off
	v_lshl_add_u64 v[112:113], v[112:113], 0, s[98:99]
	ds_read_b128 v[102:105], v151 offset:25344
	s_waitcnt vmcnt(15) lgkmcnt(1)
	v_pk_fma_f32 v[26:27], v[2:3], v[106:107], v[26:27]
	v_pk_fma_f32 v[28:29], v[4:5], v[108:109], v[28:29]
	global_store_dwordx4 v[112:113], v[26:29], off
	v_lshl_add_u64 v[112:113], v[112:113], 0, s[98:99]
	ds_read_b128 v[106:109], v151 offset:29568
	s_waitcnt vmcnt(15) lgkmcnt(1)
	v_pk_fma_f32 v[30:31], v[2:3], v[102:103], v[30:31]
	v_pk_fma_f32 v[32:33], v[4:5], v[104:105], v[32:33]
	global_store_dwordx4 v[112:113], v[30:33], off
	v_lshl_add_u64 v[112:113], v[112:113], 0, s[98:99]
	ds_read_b128 v[102:105], v151 offset:33792
	s_waitcnt vmcnt(15) lgkmcnt(1)
	v_pk_fma_f32 v[34:35], v[2:3], v[106:107], v[34:35]
	v_pk_fma_f32 v[36:37], v[4:5], v[108:109], v[36:37]
	global_store_dwordx4 v[112:113], v[34:37], off
	v_lshl_add_u64 v[112:113], v[112:113], 0, s[98:99]
	ds_read_b128 v[106:109], v151 offset:38016
	s_waitcnt vmcnt(15) lgkmcnt(1)
	v_pk_fma_f32 v[38:39], v[2:3], v[102:103], v[38:39]
	v_pk_fma_f32 v[40:41], v[4:5], v[104:105], v[40:41]
	global_store_dwordx4 v[112:113], v[38:41], off
	v_lshl_add_u64 v[112:113], v[112:113], 0, s[98:99]
	ds_read_b128 v[102:105], v151 offset:42240
	s_waitcnt vmcnt(15) lgkmcnt(1)
	v_pk_fma_f32 v[42:43], v[2:3], v[106:107], v[42:43]
	v_pk_fma_f32 v[44:45], v[4:5], v[108:109], v[44:45]
	global_store_dwordx4 v[112:113], v[42:45], off
	v_lshl_add_u64 v[112:113], v[112:113], 0, s[98:99]
	ds_read_b128 v[106:109], v151 offset:46464
	s_waitcnt vmcnt(15) lgkmcnt(1)
	v_pk_fma_f32 v[46:47], v[2:3], v[102:103], v[46:47]
	v_pk_fma_f32 v[48:49], v[4:5], v[104:105], v[48:49]
	global_store_dwordx4 v[112:113], v[46:49], off
	v_lshl_add_u64 v[112:113], v[112:113], 0, s[98:99]
	ds_read_b128 v[102:105], v151 offset:50688
	s_waitcnt vmcnt(15) lgkmcnt(1)
	v_pk_fma_f32 v[50:51], v[2:3], v[106:107], v[50:51]
	v_pk_fma_f32 v[52:53], v[4:5], v[108:109], v[52:53]
	global_store_dwordx4 v[112:113], v[50:53], off
	v_lshl_add_u64 v[112:113], v[112:113], 0, s[98:99]
	ds_read_b128 v[106:109], v151 offset:54912
	s_waitcnt vmcnt(15) lgkmcnt(1)
	v_pk_fma_f32 v[54:55], v[2:3], v[102:103], v[54:55]
	v_pk_fma_f32 v[56:57], v[4:5], v[104:105], v[56:57]
	global_store_dwordx4 v[112:113], v[54:57], off
	v_lshl_add_u64 v[112:113], v[112:113], 0, s[98:99]
	ds_read_b128 v[102:105], v151 offset:59136
	s_waitcnt vmcnt(15) lgkmcnt(1)
	v_pk_fma_f32 v[58:59], v[2:3], v[106:107], v[58:59]
	v_pk_fma_f32 v[60:61], v[4:5], v[108:109], v[60:61]
	global_store_dwordx4 v[112:113], v[58:61], off
	v_lshl_add_u64 v[112:113], v[112:113], 0, s[98:99]
	ds_read_b128 v[106:109], v151 offset:63360
	s_waitcnt vmcnt(15) lgkmcnt(1)
	v_pk_fma_f32 v[62:63], v[2:3], v[102:103], v[62:63]
	v_pk_fma_f32 v[64:65], v[4:5], v[104:105], v[64:65]
	global_store_dwordx4 v[112:113], v[62:65], off
	v_lshl_add_u64 v[112:113], v[112:113], 0, s[98:99]
	s_waitcnt vmcnt(15) lgkmcnt(0)
	v_pk_fma_f32 v[98:99], v[2:3], v[106:107], v[98:99]
	v_pk_fma_f32 v[100:101], v[4:5], v[108:109], v[100:101]
	global_store_dwordx4 v[112:113], v[98:101], off
	s_branch .LBB0_100

.LBB0_257:
	s_add_i32 s0, s6, s7
	s_add_i32 s1, s0, 0xffffd404
	s_cmpk_lt_i32 s1, 0x200
	s_movk_i32 s1, 0x500
	s_cselect_b32 s1, s1, 0x80
	s_add_i32 s2, s0, s1
	s_add_i32 s4, s2, 0xffffd404
	s_cmpk_lt_i32 s4, 0x500
	s_cselect_b64 s[0:1], -1, 0
	s_add_i32 s5, s2, 0xffffcf04
	s_and_b64 s[2:3], s[0:1], exec
	s_cselect_b32 s2, s4, s5
	s_movk_i32 s3, 0xa00
	s_cselect_b32 s4, 0, 0xa00000
	s_cselect_b32 s3, s3, 0x400
	s_add_u32 s10, s94, s4
	s_addc_u32 s11, s95, 0
	s_and_b64 s[0:1], s[0:1], exec
	s_cselect_b32 s9, s17, s21
	s_cselect_b32 s8, s16, s20
	s_lshr_b32 s0, s3, 2
	s_abs_i32 s12, s0
	v_cvt_f32_u32_e32 v0, s12
	s_sub_i32 s13, 0, s12
	s_abs_i32 s5, s2
	s_xor_b32 s1, s2, s0
	v_rcp_iflag_f32_e32 v0, v0
	s_lshr_b32 s4, s3, 6
	s_ashr_i32 s1, s1, 31
	v_mov_b32_e32 v6, v218
	v_mul_f32_e32 v0, 0x4f7ffffe, v0
	v_cvt_u32_f32_e32 v0, v0
	s_nop 0
	v_ashrrev_i32_e32 v7, 6, v6
	v_readfirstlane_b32 s14, v0
	s_mul_i32 s13, s13, s14
	s_mul_hi_u32 s13, s14, s13
	s_add_i32 s14, s14, s13
	s_mul_hi_u32 s13, s5, s14
	s_mul_i32 s14, s13, s12
	s_sub_i32 s5, s5, s14
	s_add_i32 s14, s13, 1
	s_sub_i32 s15, s5, s12
	s_cmp_ge_u32 s5, s12
	s_cselect_b32 s13, s14, s13
	s_cselect_b32 s5, s15, s5
	s_add_i32 s14, s13, 1
	s_cmp_ge_u32 s5, s12
	s_cselect_b32 s5, s14, s13
	s_xor_b32 s5, s5, s1
	s_sub_i32 s5, s5, s1
	s_mul_i32 s0, s5, s0
	s_sub_i32 s2, s2, s0
	s_sext_i32_i16 s0, s4
	v_cvt_f32_i32_e32 v2, s0
	v_cvt_f32_i32_e32 v0, s2
	s_xor_b32 s1, s2, s0
	s_ashr_i32 s1, s1, 30
	v_rcp_iflag_f32_e32 v3, v2
	s_or_b32 s12, s1, 1
	v_mul_f32_e32 v3, v0, v3
	v_trunc_f32_e32 v3, v3
	v_fma_f32 v0, -v3, v2, v0
	v_cvt_i32_f32_e32 v3, v3
	v_cmp_ge_f32_e64 s[0:1], |v0|, |v2|
	s_and_b64 s[0:1], s[0:1], exec
	s_cselect_b32 s0, s12, 0
	v_readfirstlane_b32 s1, v3
	s_add_i32 s0, s1, s0
	s_sext_i32_i16 s12, s0
	s_mul_i32 s0, s0, s4
	s_sub_i32 s0, s2, s0
	s_sext_i32_i16 s13, s0
	s_mul_hi_i32 s1, s5, s3
	s_mul_i32 s0, s5, s3
	s_lshl_b64 s[4:5], s[0:1], 12
	s_add_u32 s8, s8, s4
	s_addc_u32 s9, s9, s5
	s_lshl_b64 s[0:1], s[0:1], 11
	s_add_u32 s0, s10, s0
	s_addc_u32 s1, s11, s1
	s_lshl_b32 s4, s13, 6
	s_ashr_i32 s5, s4, 31
	s_lshl_b32 s2, s12, 6
	s_lshl_b64 s[10:11], s[4:5], 2
	s_add_u32 s8, s8, s10
	v_lshlrev_b32_e32 v0, 2, v6
	s_addc_u32 s9, s9, s11
	v_and_b32_e32 v0, 0xfc, v0
	v_add_u32_e32 v10, s2, v7
	v_lshl_add_u64 v[2:3], s[8:9], 0, v[0:1]
	v_mad_i64_i32 v[4:5], s[8:9], v10, s3, 0
	v_lshl_add_u64 v[4:5], v[4:5], 2, v[2:3]
	global_load_dword v100, v[4:5], off
	v_mad_u64_u32 v[4:5], s[8:9], v7, s18, v[0:1]
	v_add_u32_e32 v0, 4, v10
	v_mad_i64_i32 v[8:9], s[8:9], v0, s3, 0
	v_lshl_add_u64 v[8:9], v[8:9], 2, v[2:3]
	global_load_dword v101, v[8:9], off
	v_add_u32_e32 v0, 8, v10
	v_mad_i64_i32 v[8:9], s[8:9], v0, s3, 0
	v_lshl_add_u64 v[8:9], v[8:9], 2, v[2:3]
	global_load_dword v102, v[8:9], off
	v_add_u32_e32 v0, 12, v10
	v_mad_i64_i32 v[8:9], s[8:9], v0, s3, 0
	v_lshl_add_u64 v[8:9], v[8:9], 2, v[2:3]
	global_load_dword v103, v[8:9], off
	v_add_u32_e32 v0, 16, v10
	v_mad_i64_i32 v[8:9], s[8:9], v0, s3, 0
	v_lshl_add_u64 v[8:9], v[8:9], 2, v[2:3]
	global_load_dword v104, v[8:9], off
	v_add_u32_e32 v0, 20, v10
	v_mad_i64_i32 v[8:9], s[8:9], v0, s3, 0
	v_lshl_add_u64 v[8:9], v[8:9], 2, v[2:3]
	global_load_dword v105, v[8:9], off
	v_add_u32_e32 v0, 24, v10
	v_mad_i64_i32 v[8:9], s[8:9], v0, s3, 0
	v_lshl_add_u64 v[8:9], v[8:9], 2, v[2:3]
	global_load_dword v106, v[8:9], off
	v_add_u32_e32 v0, 28, v10
	v_mad_i64_i32 v[8:9], s[8:9], v0, s3, 0
	v_lshl_add_u64 v[8:9], v[8:9], 2, v[2:3]
	global_load_dword v107, v[8:9], off
	v_add_u32_e32 v0, 32, v10
	v_mad_i64_i32 v[8:9], s[8:9], v0, s3, 0
	v_lshl_add_u64 v[8:9], v[8:9], 2, v[2:3]
	global_load_dword v108, v[8:9], off
	v_add_u32_e32 v0, 36, v10
	v_mad_i64_i32 v[8:9], s[8:9], v0, s3, 0
	v_lshl_add_u64 v[8:9], v[8:9], 2, v[2:3]
	global_load_dword v109, v[8:9], off
	v_add_u32_e32 v0, 40, v10
	v_mad_i64_i32 v[8:9], s[8:9], v0, s3, 0
	v_lshl_add_u64 v[8:9], v[8:9], 2, v[2:3]
	global_load_dword v110, v[8:9], off
	v_add_u32_e32 v0, 44, v10
	v_mad_i64_i32 v[8:9], s[8:9], v0, s3, 0
	v_lshl_add_u64 v[8:9], v[8:9], 2, v[2:3]
	global_load_dword v111, v[8:9], off
	v_add_u32_e32 v0, 48, v10
	v_mad_i64_i32 v[8:9], s[8:9], v0, s3, 0
	v_lshl_add_u64 v[8:9], v[8:9], 2, v[2:3]
	global_load_dword v112, v[8:9], off
	v_add_u32_e32 v0, 52, v10
	v_mad_i64_i32 v[8:9], s[8:9], v0, s3, 0
	v_lshl_add_u64 v[8:9], v[8:9], 2, v[2:3]
	global_load_dword v113, v[8:9], off
	v_add_u32_e32 v0, 56, v10
	v_mad_i64_i32 v[8:9], s[8:9], v0, s3, 0
	v_lshl_add_u64 v[8:9], v[8:9], 2, v[2:3]
	global_load_dword v114, v[8:9], off
	v_add_u32_e32 v0, 60, v10
	v_mad_i64_i32 v[8:9], s[8:9], v0, s3, 0
	v_lshl_add_u64 v[2:3], v[8:9], 2, v[2:3]
	global_load_dword v115, v[2:3], off
	v_lshlrev_b32_e32 v2, 4, v6
	v_and_b32_e32 v20, 48, v2
	v_and_b32_e32 v2, -4, v6
	v_mad_u32_u24 v14, v20, s18, v2
	v_add_u32_e32 v8, 0x400, v14
	v_add_u32_e32 v12, 0x800, v14
	v_add_u32_e32 v16, 0xc00, v14
	s_ashr_i32 s3, s2, 31
	s_waitcnt vmcnt(0)
	ds_write_b32 v4, v100
	ds_write_b32 v4, v101 offset:1040
	ds_write_b32 v4, v102 offset:2080
	ds_write_b32 v4, v103 offset:3120
	ds_write_b32 v4, v104 offset:4160
	ds_write_b32 v4, v105 offset:5200
	ds_write_b32 v4, v106 offset:6240
	ds_write_b32 v4, v107 offset:7280
	ds_write_b32 v4, v108 offset:8320
	ds_write_b32 v4, v109 offset:9360
	ds_write_b32 v4, v110 offset:10400
	ds_write_b32 v4, v111 offset:11440
	ds_write_b32 v4, v112 offset:12480
	ds_write_b32 v4, v113 offset:13520
	ds_write_b32 v4, v114 offset:14560
	ds_write_b32 v4, v115 offset:15600
	v_ashrrev_i32_e32 v0, 2, v6
	s_waitcnt lgkmcnt(0)
	s_barrier
	ds_read2_b32 v[2:3], v14 offset1:65
	ds_read2_b32 v[4:5], v14 offset0:130 offset1:195
	ds_read2_b32 v[6:7], v8 offset0:4 offset1:69
	ds_read2_b32 v[8:9], v8 offset0:134 offset1:199
	v_add_u32_e32 v18, s4, v0
	ds_read2_b32 v[10:11], v12 offset0:8 offset1:73
	ds_read2_b32 v[12:13], v12 offset0:138 offset1:203
	ds_read2_b32 v[14:15], v16 offset0:12 offset1:77
	ds_read2_b32 v[16:17], v16 offset0:142 offset1:207
	v_ashrrev_i32_e32 v19, 31, v18
	v_lshlrev_b64 v[18:19], 11, v[18:19]
	v_lshl_add_u64 v[18:19], s[0:1], 0, v[18:19]
	v_lshl_add_u64 v[18:19], s[2:3], 1, v[18:19]
	v_lshlrev_b32_e32 v0, 1, v20
	v_lshl_add_u64 v[18:19], v[18:19], 0, v[0:1]
	s_waitcnt lgkmcnt(7)
	v_cvt_pk_bf16_f32 v2, v2, v3
	s_waitcnt lgkmcnt(6)
	v_cvt_pk_bf16_f32 v3, v4, v5
	s_waitcnt lgkmcnt(5)
	v_cvt_pk_bf16_f32 v4, v6, v7
	s_waitcnt lgkmcnt(4)
	v_cvt_pk_bf16_f32 v5, v8, v9
	v_add_co_u32_e64 v0, s[0:1], s7, 1
	global_store_dwordx4 v[18:19], v[2:5], off
	v_readfirstlane_b32 s7, v0
	s_and_b64 vcc, exec, s[0:1]
	s_waitcnt lgkmcnt(3)
	v_cvt_pk_bf16_f32 v2, v10, v11
	s_waitcnt lgkmcnt(2)
	v_cvt_pk_bf16_f32 v3, v12, v13
	s_waitcnt lgkmcnt(1)
	v_cvt_pk_bf16_f32 v4, v14, v15
	s_waitcnt lgkmcnt(0)
	v_cvt_pk_bf16_f32 v5, v16, v17
	global_store_dwordx4 v[18:19], v[2:5], off offset:16
	s_barrier
	s_cbranch_vccz .LBB0_257
	s_mov_b64 s[0:1], 0
	s_mov_b64 s[6:7], 0

.LBB0_293:
	s_add_i32 s0, s40, 0xfffffa00
	s_lshl_b32 s2, s0, 5
	s_cmpk_lt_u32 s0, 0x100
	s_movk_i32 s0, 0x1f00
	s_cselect_b32 s1, s0, 0x3000
	s_movk_i32 s0, 0xfe0
	v_mov_b32_e32 v2, v218
	s_cselect_b32 s3, 0xe0, s0
	s_movk_i32 s0, 0x1000
	v_readlane_b32 s6, v251, 21
	s_cselect_b32 s0, 0x100, s0
	s_and_b32 s1, s1, s2
	s_and_b32 s2, s3, s2
	v_lshlrev_b32_e32 v0, 2, v2
	v_ashrrev_i32_e32 v3, 31, v2
	s_mov_b32 s3, 0
	v_readlane_b32 s7, v251, 22
	v_lshlrev_b32_e32 v4, 1, v2
	v_readlane_b32 s4, v251, 23
	v_readlane_b32 s5, v251, 24
	s_add_i32 s98, s1, s2
	s_add_i32 s98, s98, -15
	s_ashr_i32 s99, s98, 31
	s_lshl_b64 s[98:99], s[98:99], 9
	s_add_u32 s4, s4, s98
	s_addc_u32 s5, s5, s99
	s_add_u32 s98, s6, s98
	s_addc_u32 s99, s7, s99
	v_mov_b32_e32 v6, 0
	v_mov_b32_e32 v68, 0
	v_mov_b32_e32 v7, 0
	v_mov_b32_e32 v69, 0
	v_mov_b32_e32 v8, 0
	v_mov_b32_e32 v70, 0
	v_mov_b32_e32 v9, 0
	v_mov_b32_e32 v71, 0
	v_mov_b32_e32 v10, 0
	v_mov_b32_e32 v72, 0
	v_mov_b32_e32 v11, 0
	v_mov_b32_e32 v73, 0
	v_mov_b32_e32 v12, 0
	v_mov_b32_e32 v74, 0
	v_mov_b32_e32 v13, 0
	v_mov_b32_e32 v75, 0
	v_mov_b32_e32 v14, 0
	v_mov_b32_e32 v76, 0
	v_mov_b32_e32 v15, 0
	v_mov_b32_e32 v77, 0
	v_mov_b32_e32 v16, 0
	v_mov_b32_e32 v78, 0
	v_mov_b32_e32 v17, 0
	v_mov_b32_e32 v79, 0
	v_mov_b32_e32 v18, 0
	v_mov_b32_e32 v80, 0
	v_mov_b32_e32 v19, 0
	v_mov_b32_e32 v81, 0
	v_mov_b32_e32 v20, 0
	v_mov_b32_e32 v82, 0
	v_mov_b32_e32 v21, 0
	v_mov_b32_e32 v83, 0
	v_mov_b32_e32 v22, 0
	v_mov_b32_e32 v84, 0
	v_mov_b32_e32 v23, 0
	v_mov_b32_e32 v85, 0
	v_mov_b32_e32 v24, 0
	v_mov_b32_e32 v86, 0
	v_mov_b32_e32 v25, 0
	v_mov_b32_e32 v87, 0
	v_mov_b32_e32 v26, 0
	v_mov_b32_e32 v88, 0
	v_mov_b32_e32 v27, 0
	v_mov_b32_e32 v89, 0
	v_mov_b32_e32 v28, 0
	v_mov_b32_e32 v90, 0
	v_mov_b32_e32 v29, 0
	v_mov_b32_e32 v91, 0
	v_mov_b32_e32 v30, 0
	v_mov_b32_e32 v92, 0
	v_mov_b32_e32 v31, 0
	v_mov_b32_e32 v93, 0
	v_mov_b32_e32 v32, 0
	v_mov_b32_e32 v94, 0
	v_mov_b32_e32 v33, 0
	v_mov_b32_e32 v95, 0
	v_mov_b32_e32 v34, 0
	v_mov_b32_e32 v96, 0
	v_mov_b32_e32 v35, 0
	v_mov_b32_e32 v97, 0
	v_mov_b32_e32 v36, 0
	v_mov_b32_e32 v98, 0
	v_mov_b32_e32 v37, 0
	v_mov_b32_e32 v99, 0
	v_mov_b32_e32 v38, 0
	v_mov_b32_e32 v100, 0
	v_mov_b32_e32 v39, 0
	v_mov_b32_e32 v101, 0
	v_mov_b32_e32 v40, 0
	v_mov_b32_e32 v102, 0
	v_mov_b32_e32 v41, 0
	v_mov_b32_e32 v103, 0
	v_mov_b32_e32 v42, 0
	v_mov_b32_e32 v104, 0
	v_mov_b32_e32 v43, 0
	v_mov_b32_e32 v105, 0
	v_mov_b32_e32 v44, 0
	v_mov_b32_e32 v106, 0
	v_mov_b32_e32 v45, 0
	v_mov_b32_e32 v107, 0
	v_mov_b32_e32 v46, 0
	v_mov_b32_e32 v108, 0
	v_mov_b32_e32 v47, 0
	v_mov_b32_e32 v109, 0
	v_mov_b32_e32 v48, 0
	v_mov_b32_e32 v110, 0
	v_mov_b32_e32 v49, 0
	v_mov_b32_e32 v111, 0
	v_mov_b32_e32 v50, 0
	v_mov_b32_e32 v112, 0
	v_mov_b32_e32 v51, 0
	v_mov_b32_e32 v113, 0
	v_mov_b32_e32 v52, 0
	v_mov_b32_e32 v114, 0
	v_mov_b32_e32 v53, 0
	v_mov_b32_e32 v115, 0
	v_mov_b32_e32 v54, 0
	v_mov_b32_e32 v116, 0
	v_mov_b32_e32 v55, 0
	v_mov_b32_e32 v117, 0
	v_mov_b32_e32 v56, 0
	v_mov_b32_e32 v118, 0
	v_mov_b32_e32 v57, 0
	v_mov_b32_e32 v119, 0
	v_mov_b32_e32 v58, 0
	v_mov_b32_e32 v120, 0
	v_mov_b32_e32 v59, 0
	v_mov_b32_e32 v121, 0
	v_mov_b32_e32 v60, 0
	v_mov_b32_e32 v122, 0
	v_mov_b32_e32 v61, 0
	v_mov_b32_e32 v123, 0
	v_mov_b32_e32 v62, 0
	v_mov_b32_e32 v124, 0
	v_mov_b32_e32 v63, 0
	v_mov_b32_e32 v125, 0
	v_mov_b32_e32 v64, 0
	v_mov_b32_e32 v126, 0
	v_mov_b32_e32 v65, 0
	v_mov_b32_e32 v127, 0
	v_mov_b32_e32 v66, 0
	v_mov_b32_e32 v128, 0
	v_mov_b32_e32 v67, 0
	v_mov_b32_e32 v129, 0
	s_add_i32 s3, s2, -15
	s_cmp_ge_u32 s3, s0
	s_cbranch_scc1 .Lcv_skip_0
	global_load_ushort v6, v4, s[98:99]
	global_load_ushort v68, v4, s[4:5]
.Lcv_skip_0:
	s_add_i32 s3, s2, -14
	s_cmp_ge_u32 s3, s0
	s_cbranch_scc1 .Lcv_skip_1
	global_load_ushort v7, v4, s[98:99] offset:512
	global_load_ushort v69, v4, s[4:5] offset:512
.Lcv_skip_1:
	s_add_i32 s3, s2, -13
	s_cmp_ge_u32 s3, s0
	s_cbranch_scc1 .Lcv_skip_2
	global_load_ushort v8, v4, s[98:99] offset:1024
	global_load_ushort v70, v4, s[4:5] offset:1024
.Lcv_skip_2:
	s_add_i32 s3, s2, -12
	s_cmp_ge_u32 s3, s0
	s_cbranch_scc1 .Lcv_skip_3
	global_load_ushort v9, v4, s[98:99] offset:1536
	global_load_ushort v71, v4, s[4:5] offset:1536
.Lcv_skip_3:
	s_add_i32 s3, s2, -11
	s_cmp_ge_u32 s3, s0
	s_cbranch_scc1 .Lcv_skip_4
	global_load_ushort v10, v4, s[98:99] offset:2048
	global_load_ushort v72, v4, s[4:5] offset:2048
.Lcv_skip_4:
	s_add_i32 s3, s2, -10
	s_cmp_ge_u32 s3, s0
	s_cbranch_scc1 .Lcv_skip_5
	global_load_ushort v11, v4, s[98:99] offset:2560
	global_load_ushort v73, v4, s[4:5] offset:2560
.Lcv_skip_5:
	s_add_i32 s3, s2, -9
	s_cmp_ge_u32 s3, s0
	s_cbranch_scc1 .Lcv_skip_6
	global_load_ushort v12, v4, s[98:99] offset:3072
	global_load_ushort v74, v4, s[4:5] offset:3072
.Lcv_skip_6:
	s_add_i32 s3, s2, -8
	s_cmp_ge_u32 s3, s0
	s_cbranch_scc1 .Lcv_skip_7
	global_load_ushort v13, v4, s[98:99] offset:3584
	global_load_ushort v75, v4, s[4:5] offset:3584
.Lcv_skip_7:
	s_add_u32 s98, s98, 0x1000
	s_addc_u32 s99, s99, 0
	s_add_u32 s4, s4, 0x1000
	s_addc_u32 s5, s5, 0
	s_add_i32 s3, s2, -7
	s_cmp_ge_u32 s3, s0
	s_cbranch_scc1 .Lcv_skip_8
	global_load_ushort v14, v4, s[98:99]
	global_load_ushort v76, v4, s[4:5]
.Lcv_skip_8:
	s_add_i32 s3, s2, -6
	s_cmp_ge_u32 s3, s0
	s_cbranch_scc1 .Lcv_skip_9
	global_load_ushort v15, v4, s[98:99] offset:512
	global_load_ushort v77, v4, s[4:5] offset:512
.Lcv_skip_9:
	s_add_i32 s3, s2, -5
	s_cmp_ge_u32 s3, s0
	s_cbranch_scc1 .Lcv_skip_10
	global_load_ushort v16, v4, s[98:99] offset:1024
	global_load_ushort v78, v4, s[4:5] offset:1024
.Lcv_skip_10:
	s_add_i32 s3, s2, -4
	s_cmp_ge_u32 s3, s0
	s_cbranch_scc1 .Lcv_skip_11
	global_load_ushort v17, v4, s[98:99] offset:1536
	global_load_ushort v79, v4, s[4:5] offset:1536
.Lcv_skip_11:
	s_add_i32 s3, s2, -3
	s_cmp_ge_u32 s3, s0
	s_cbranch_scc1 .Lcv_skip_12
	global_load_ushort v18, v4, s[98:99] offset:2048
	global_load_ushort v80, v4, s[4:5] offset:2048
.Lcv_skip_12:
	s_add_i32 s3, s2, -2
	s_cmp_ge_u32 s3, s0
	s_cbranch_scc1 .Lcv_skip_13
	global_load_ushort v19, v4, s[98:99] offset:2560
	global_load_ushort v81, v4, s[4:5] offset:2560
.Lcv_skip_13:
	s_add_i32 s3, s2, -1
	s_cmp_ge_u32 s3, s0
	s_cbranch_scc1 .Lcv_skip_14
	global_load_ushort v20, v4, s[98:99] offset:3072
	global_load_ushort v82, v4, s[4:5] offset:3072
.Lcv_skip_14:
	s_add_i32 s3, s2, 0
	s_cmp_ge_u32 s3, s0
	s_cbranch_scc1 .Lcv_skip_15
	global_load_ushort v21, v4, s[98:99] offset:3584
	global_load_ushort v83, v4, s[4:5] offset:3584
.Lcv_skip_15:
	s_add_u32 s98, s98, 0x1000
	s_addc_u32 s99, s99, 0
	s_add_u32 s4, s4, 0x1000
	s_addc_u32 s5, s5, 0
	s_add_i32 s3, s2, 1
	s_cmp_ge_u32 s3, s0
	s_cbranch_scc1 .Lcv_skip_16
	global_load_ushort v22, v4, s[98:99]
	global_load_ushort v84, v4, s[4:5]
.Lcv_skip_16:
	s_add_i32 s3, s2, 2
	s_cmp_ge_u32 s3, s0
	s_cbranch_scc1 .Lcv_skip_17
	global_load_ushort v23, v4, s[98:99] offset:512
	global_load_ushort v85, v4, s[4:5] offset:512
.Lcv_skip_17:
	s_add_i32 s3, s2, 3
	s_cmp_ge_u32 s3, s0
	s_cbranch_scc1 .Lcv_skip_18
	global_load_ushort v24, v4, s[98:99] offset:1024
	global_load_ushort v86, v4, s[4:5] offset:1024
.Lcv_skip_18:
	s_add_i32 s3, s2, 4
	s_cmp_ge_u32 s3, s0
	s_cbranch_scc1 .Lcv_skip_19
	global_load_ushort v25, v4, s[98:99] offset:1536
	global_load_ushort v87, v4, s[4:5] offset:1536
.Lcv_skip_19:
	s_add_i32 s3, s2, 5
	s_cmp_ge_u32 s3, s0
	s_cbranch_scc1 .Lcv_skip_20
	global_load_ushort v26, v4, s[98:99] offset:2048
	global_load_ushort v88, v4, s[4:5] offset:2048
.Lcv_skip_20:
	s_add_i32 s3, s2, 6
	s_cmp_ge_u32 s3, s0
	s_cbranch_scc1 .Lcv_skip_21
	global_load_ushort v27, v4, s[98:99] offset:2560
	global_load_ushort v89, v4, s[4:5] offset:2560
.Lcv_skip_21:
	s_add_i32 s3, s2, 7
	s_cmp_ge_u32 s3, s0
	s_cbranch_scc1 .Lcv_skip_22
	global_load_ushort v28, v4, s[98:99] offset:3072
	global_load_ushort v90, v4, s[4:5] offset:3072
.Lcv_skip_22:
	s_add_i32 s3, s2, 8
	s_cmp_ge_u32 s3, s0
	s_cbranch_scc1 .Lcv_skip_23
	global_load_ushort v29, v4, s[98:99] offset:3584
	global_load_ushort v91, v4, s[4:5] offset:3584
.Lcv_skip_23:
	s_add_u32 s98, s98, 0x1000
	s_addc_u32 s99, s99, 0
	s_add_u32 s4, s4, 0x1000
	s_addc_u32 s5, s5, 0
	s_add_i32 s3, s2, 9
	s_cmp_ge_u32 s3, s0
	s_cbranch_scc1 .Lcv_skip_24
	global_load_ushort v30, v4, s[98:99]
	global_load_ushort v92, v4, s[4:5]
.Lcv_skip_24:
	s_add_i32 s3, s2, 10
	s_cmp_ge_u32 s3, s0
	s_cbranch_scc1 .Lcv_skip_25
	global_load_ushort v31, v4, s[98:99] offset:512
	global_load_ushort v93, v4, s[4:5] offset:512
.Lcv_skip_25:
	s_add_i32 s3, s2, 11
	s_cmp_ge_u32 s3, s0
	s_cbranch_scc1 .Lcv_skip_26
	global_load_ushort v32, v4, s[98:99] offset:1024
	global_load_ushort v94, v4, s[4:5] offset:1024
.Lcv_skip_26:
	s_add_i32 s3, s2, 12
	s_cmp_ge_u32 s3, s0
	s_cbranch_scc1 .Lcv_skip_27
	global_load_ushort v33, v4, s[98:99] offset:1536
	global_load_ushort v95, v4, s[4:5] offset:1536
.Lcv_skip_27:
	s_add_i32 s3, s2, 13
	s_cmp_ge_u32 s3, s0
	s_cbranch_scc1 .Lcv_skip_28
	global_load_ushort v34, v4, s[98:99] offset:2048
	global_load_ushort v96, v4, s[4:5] offset:2048
.Lcv_skip_28:
	s_add_i32 s3, s2, 14
	s_cmp_ge_u32 s3, s0
	s_cbranch_scc1 .Lcv_skip_29
	global_load_ushort v35, v4, s[98:99] offset:2560
	global_load_ushort v97, v4, s[4:5] offset:2560
.Lcv_skip_29:
	s_add_i32 s3, s2, 15
	s_cmp_ge_u32 s3, s0
	s_cbranch_scc1 .Lcv_skip_30
	global_load_ushort v36, v4, s[98:99] offset:3072
	global_load_ushort v98, v4, s[4:5] offset:3072
.Lcv_skip_30:
	s_add_i32 s3, s2, 16
	s_cmp_ge_u32 s3, s0
	s_cbranch_scc1 .Lcv_skip_31
	global_load_ushort v37, v4, s[98:99] offset:3584
	global_load_ushort v99, v4, s[4:5] offset:3584
.Lcv_skip_31:
	s_add_u32 s98, s98, 0x1000
	s_addc_u32 s99, s99, 0
	s_add_u32 s4, s4, 0x1000
	s_addc_u32 s5, s5, 0
	s_add_i32 s3, s2, 17
	s_cmp_ge_u32 s3, s0
	s_cbranch_scc1 .Lcv_skip_32
	global_load_ushort v38, v4, s[98:99]
	global_load_ushort v100, v4, s[4:5]
.Lcv_skip_32:
	s_add_i32 s3, s2, 18
	s_cmp_ge_u32 s3, s0
	s_cbranch_scc1 .Lcv_skip_33
	global_load_ushort v39, v4, s[98:99] offset:512
	global_load_ushort v101, v4, s[4:5] offset:512
.Lcv_skip_33:
	s_add_i32 s3, s2, 19
	s_cmp_ge_u32 s3, s0
	s_cbranch_scc1 .Lcv_skip_34
	global_load_ushort v40, v4, s[98:99] offset:1024
	global_load_ushort v102, v4, s[4:5] offset:1024
.Lcv_skip_34:
	s_add_i32 s3, s2, 20
	s_cmp_ge_u32 s3, s0
	s_cbranch_scc1 .Lcv_skip_35
	global_load_ushort v41, v4, s[98:99] offset:1536
	global_load_ushort v103, v4, s[4:5] offset:1536
.Lcv_skip_35:
	s_add_i32 s3, s2, 21
	s_cmp_ge_u32 s3, s0
	s_cbranch_scc1 .Lcv_skip_36
	global_load_ushort v42, v4, s[98:99] offset:2048
	global_load_ushort v104, v4, s[4:5] offset:2048
.Lcv_skip_36:
	s_add_i32 s3, s2, 22
	s_cmp_ge_u32 s3, s0
	s_cbranch_scc1 .Lcv_skip_37
	global_load_ushort v43, v4, s[98:99] offset:2560
	global_load_ushort v105, v4, s[4:5] offset:2560
.Lcv_skip_37:
	s_add_i32 s3, s2, 23
	s_cmp_ge_u32 s3, s0
	s_cbranch_scc1 .Lcv_skip_38
	global_load_ushort v44, v4, s[98:99] offset:3072
	global_load_ushort v106, v4, s[4:5] offset:3072
.Lcv_skip_38:
	s_add_i32 s3, s2, 24
	s_cmp_ge_u32 s3, s0
	s_cbranch_scc1 .Lcv_skip_39
	global_load_ushort v45, v4, s[98:99] offset:3584
	global_load_ushort v107, v4, s[4:5] offset:3584
.Lcv_skip_39:
	s_add_u32 s98, s98, 0x1000
	s_addc_u32 s99, s99, 0
	s_add_u32 s4, s4, 0x1000
	s_addc_u32 s5, s5, 0
	s_add_i32 s3, s2, 25
	s_cmp_ge_u32 s3, s0
	s_cbranch_scc1 .Lcv_skip_40
	global_load_ushort v46, v4, s[98:99]
	global_load_ushort v108, v4, s[4:5]
.Lcv_skip_40:
	s_add_i32 s3, s2, 26
	s_cmp_ge_u32 s3, s0
	s_cbranch_scc1 .Lcv_skip_41
	global_load_ushort v47, v4, s[98:99] offset:512
	global_load_ushort v109, v4, s[4:5] offset:512
.Lcv_skip_41:
	s_add_i32 s3, s2, 27
	s_cmp_ge_u32 s3, s0
	s_cbranch_scc1 .Lcv_skip_42
	global_load_ushort v48, v4, s[98:99] offset:1024
	global_load_ushort v110, v4, s[4:5] offset:1024
.Lcv_skip_42:
	s_add_i32 s3, s2, 28
	s_cmp_ge_u32 s3, s0
	s_cbranch_scc1 .Lcv_skip_43
	global_load_ushort v49, v4, s[98:99] offset:1536
	global_load_ushort v111, v4, s[4:5] offset:1536
.Lcv_skip_43:
	s_add_i32 s3, s2, 29
	s_cmp_ge_u32 s3, s0
	s_cbranch_scc1 .Lcv_skip_44
	global_load_ushort v50, v4, s[98:99] offset:2048
	global_load_ushort v112, v4, s[4:5] offset:2048
.Lcv_skip_44:
	s_add_i32 s3, s2, 30
	s_cmp_ge_u32 s3, s0
	s_cbranch_scc1 .Lcv_skip_45
	global_load_ushort v51, v4, s[98:99] offset:2560
	global_load_ushort v113, v4, s[4:5] offset:2560
.Lcv_skip_45:
	s_add_i32 s3, s2, 31
	s_cmp_ge_u32 s3, s0
	s_cbranch_scc1 .Lcv_skip_46
	global_load_ushort v52, v4, s[98:99] offset:3072
	global_load_ushort v114, v4, s[4:5] offset:3072
.Lcv_skip_46:
	s_add_i32 s3, s2, 32
	s_cmp_ge_u32 s3, s0
	s_cbranch_scc1 .Lcv_skip_47
	global_load_ushort v53, v4, s[98:99] offset:3584
	global_load_ushort v115, v4, s[4:5] offset:3584
.Lcv_skip_47:
	s_add_u32 s98, s98, 0x1000
	s_addc_u32 s99, s99, 0
	s_add_u32 s4, s4, 0x1000
	s_addc_u32 s5, s5, 0
	s_add_i32 s3, s2, 33
	s_cmp_ge_u32 s3, s0
	s_cbranch_scc1 .Lcv_skip_48
	global_load_ushort v54, v4, s[98:99]
	global_load_ushort v116, v4, s[4:5]
.Lcv_skip_48:
	s_add_i32 s3, s2, 34
	s_cmp_ge_u32 s3, s0
	s_cbranch_scc1 .Lcv_skip_49
	global_load_ushort v55, v4, s[98:99] offset:512
	global_load_ushort v117, v4, s[4:5] offset:512
.Lcv_skip_49:
	s_add_i32 s3, s2, 35
	s_cmp_ge_u32 s3, s0
	s_cbranch_scc1 .Lcv_skip_50
	global_load_ushort v56, v4, s[98:99] offset:1024
	global_load_ushort v118, v4, s[4:5] offset:1024
.Lcv_skip_50:
	s_add_i32 s3, s2, 36
	s_cmp_ge_u32 s3, s0
	s_cbranch_scc1 .Lcv_skip_51
	global_load_ushort v57, v4, s[98:99] offset:1536
	global_load_ushort v119, v4, s[4:5] offset:1536
.Lcv_skip_51:
	s_add_i32 s3, s2, 37
	s_cmp_ge_u32 s3, s0
	s_cbranch_scc1 .Lcv_skip_52
	global_load_ushort v58, v4, s[98:99] offset:2048
	global_load_ushort v120, v4, s[4:5] offset:2048
.Lcv_skip_52:
	s_add_i32 s3, s2, 38
	s_cmp_ge_u32 s3, s0
	s_cbranch_scc1 .Lcv_skip_53
	global_load_ushort v59, v4, s[98:99] offset:2560
	global_load_ushort v121, v4, s[4:5] offset:2560
.Lcv_skip_53:
	s_add_i32 s3, s2, 39
	s_cmp_ge_u32 s3, s0
	s_cbranch_scc1 .Lcv_skip_54
	global_load_ushort v60, v4, s[98:99] offset:3072
	global_load_ushort v122, v4, s[4:5] offset:3072
.Lcv_skip_54:
	s_add_i32 s3, s2, 40
	s_cmp_ge_u32 s3, s0
	s_cbranch_scc1 .Lcv_skip_55
	global_load_ushort v61, v4, s[98:99] offset:3584
	global_load_ushort v123, v4, s[4:5] offset:3584
.Lcv_skip_55:
	s_add_u32 s98, s98, 0x1000
	s_addc_u32 s99, s99, 0
	s_add_u32 s4, s4, 0x1000
	s_addc_u32 s5, s5, 0
	s_add_i32 s3, s2, 41
	s_cmp_ge_u32 s3, s0
	s_cbranch_scc1 .Lcv_skip_56
	global_load_ushort v62, v4, s[98:99]
	global_load_ushort v124, v4, s[4:5]
.Lcv_skip_56:
	s_add_i32 s3, s2, 42
	s_cmp_ge_u32 s3, s0
	s_cbranch_scc1 .Lcv_skip_57
	global_load_ushort v63, v4, s[98:99] offset:512
	global_load_ushort v125, v4, s[4:5] offset:512
.Lcv_skip_57:
	s_add_i32 s3, s2, 43
	s_cmp_ge_u32 s3, s0
	s_cbranch_scc1 .Lcv_skip_58
	global_load_ushort v64, v4, s[98:99] offset:1024
	global_load_ushort v126, v4, s[4:5] offset:1024
.Lcv_skip_58:
	s_add_i32 s3, s2, 44
	s_cmp_ge_u32 s3, s0
	s_cbranch_scc1 .Lcv_skip_59
	global_load_ushort v65, v4, s[98:99] offset:1536
	global_load_ushort v127, v4, s[4:5] offset:1536
.Lcv_skip_59:
	s_add_i32 s3, s2, 45
	s_cmp_ge_u32 s3, s0
	s_cbranch_scc1 .Lcv_skip_60
	global_load_ushort v66, v4, s[98:99] offset:2048
	global_load_ushort v128, v4, s[4:5] offset:2048
.Lcv_skip_60:
	s_add_i32 s3, s2, 46
	s_cmp_ge_u32 s3, s0
	s_cbranch_scc1 .Lcv_skip_61
	global_load_ushort v67, v4, s[98:99] offset:2560
	global_load_ushort v129, v4, s[4:5] offset:2560
.Lcv_skip_61:
	s_waitcnt vmcnt(0)
	v_lshlrev_b32_e32 v68, 16, v68
	v_mul_f32_e32 v68, 0xbfb8aa3b, v68
	v_exp_f32_e32 v68, v68
	v_lshlrev_b32_e32 v6, 16, v6
	v_add_f32_e32 v68, 1.0, v68
	v_rcp_f32_e32 v68, v68
	s_nop 0
	v_mul_f32_e32 v6, v68, v6
	ds_write_b32 v0, v6
	v_lshlrev_b32_e32 v69, 16, v69
	v_mul_f32_e32 v69, 0xbfb8aa3b, v69
	v_exp_f32_e32 v69, v69
	v_lshlrev_b32_e32 v7, 16, v7
	v_add_f32_e32 v69, 1.0, v69
	v_rcp_f32_e32 v69, v69
	s_nop 0
	v_mul_f32_e32 v7, v69, v7
	ds_write_b32 v0, v7 offset:1024
	v_lshlrev_b32_e32 v70, 16, v70
	v_mul_f32_e32 v70, 0xbfb8aa3b, v70
	v_exp_f32_e32 v70, v70
	v_lshlrev_b32_e32 v8, 16, v8
	v_add_f32_e32 v70, 1.0, v70
	v_rcp_f32_e32 v70, v70
	s_nop 0
	v_mul_f32_e32 v8, v70, v8
	ds_write_b32 v0, v8 offset:2048
	v_lshlrev_b32_e32 v71, 16, v71
	v_mul_f32_e32 v71, 0xbfb8aa3b, v71
	v_exp_f32_e32 v71, v71
	v_lshlrev_b32_e32 v9, 16, v9
	v_add_f32_e32 v71, 1.0, v71
	v_rcp_f32_e32 v71, v71
	s_nop 0
	v_mul_f32_e32 v9, v71, v9
	ds_write_b32 v0, v9 offset:3072
	v_lshlrev_b32_e32 v72, 16, v72
	v_mul_f32_e32 v72, 0xbfb8aa3b, v72
	v_exp_f32_e32 v72, v72
	v_lshlrev_b32_e32 v10, 16, v10
	v_add_f32_e32 v72, 1.0, v72
	v_rcp_f32_e32 v72, v72
	s_nop 0
	v_mul_f32_e32 v10, v72, v10
	ds_write_b32 v0, v10 offset:4096
	v_lshlrev_b32_e32 v73, 16, v73
	v_mul_f32_e32 v73, 0xbfb8aa3b, v73
	v_exp_f32_e32 v73, v73
	v_lshlrev_b32_e32 v11, 16, v11
	v_add_f32_e32 v73, 1.0, v73
	v_rcp_f32_e32 v73, v73
	s_nop 0
	v_mul_f32_e32 v11, v73, v11
	ds_write_b32 v0, v11 offset:5120
	v_lshlrev_b32_e32 v74, 16, v74
	v_mul_f32_e32 v74, 0xbfb8aa3b, v74
	v_exp_f32_e32 v74, v74
	v_lshlrev_b32_e32 v12, 16, v12
	v_add_f32_e32 v74, 1.0, v74
	v_rcp_f32_e32 v74, v74
	s_nop 0
	v_mul_f32_e32 v12, v74, v12
	ds_write_b32 v0, v12 offset:6144
	v_lshlrev_b32_e32 v75, 16, v75
	v_mul_f32_e32 v75, 0xbfb8aa3b, v75
	v_exp_f32_e32 v75, v75
	v_lshlrev_b32_e32 v13, 16, v13
	v_add_f32_e32 v75, 1.0, v75
	v_rcp_f32_e32 v75, v75
	s_nop 0
	v_mul_f32_e32 v13, v75, v13
	ds_write_b32 v0, v13 offset:7168
	v_lshlrev_b32_e32 v76, 16, v76
	v_mul_f32_e32 v76, 0xbfb8aa3b, v76
	v_exp_f32_e32 v76, v76
	v_lshlrev_b32_e32 v14, 16, v14
	v_add_f32_e32 v76, 1.0, v76
	v_rcp_f32_e32 v76, v76
	s_nop 0
	v_mul_f32_e32 v14, v76, v14
	ds_write_b32 v0, v14 offset:8192
	v_lshlrev_b32_e32 v77, 16, v77
	v_mul_f32_e32 v77, 0xbfb8aa3b, v77
	v_exp_f32_e32 v77, v77
	v_lshlrev_b32_e32 v15, 16, v15
	v_add_f32_e32 v77, 1.0, v77
	v_rcp_f32_e32 v77, v77
	s_nop 0
	v_mul_f32_e32 v15, v77, v15
	ds_write_b32 v0, v15 offset:9216
	v_lshlrev_b32_e32 v78, 16, v78
	v_mul_f32_e32 v78, 0xbfb8aa3b, v78
	v_exp_f32_e32 v78, v78
	v_lshlrev_b32_e32 v16, 16, v16
	v_add_f32_e32 v78, 1.0, v78
	v_rcp_f32_e32 v78, v78
	s_nop 0
	v_mul_f32_e32 v16, v78, v16
	ds_write_b32 v0, v16 offset:10240
	v_lshlrev_b32_e32 v79, 16, v79
	v_mul_f32_e32 v79, 0xbfb8aa3b, v79
	v_exp_f32_e32 v79, v79
	v_lshlrev_b32_e32 v17, 16, v17
	v_add_f32_e32 v79, 1.0, v79
	v_rcp_f32_e32 v79, v79
	s_nop 0
	v_mul_f32_e32 v17, v79, v17
	ds_write_b32 v0, v17 offset:11264
	v_lshlrev_b32_e32 v80, 16, v80
	v_mul_f32_e32 v80, 0xbfb8aa3b, v80
	v_exp_f32_e32 v80, v80
	v_lshlrev_b32_e32 v18, 16, v18
	v_add_f32_e32 v80, 1.0, v80
	v_rcp_f32_e32 v80, v80
	s_nop 0
	v_mul_f32_e32 v18, v80, v18
	ds_write_b32 v0, v18 offset:12288
	v_lshlrev_b32_e32 v81, 16, v81
	v_mul_f32_e32 v81, 0xbfb8aa3b, v81
	v_exp_f32_e32 v81, v81
	v_lshlrev_b32_e32 v19, 16, v19
	v_add_f32_e32 v81, 1.0, v81
	v_rcp_f32_e32 v81, v81
	s_nop 0
	v_mul_f32_e32 v19, v81, v19
	ds_write_b32 v0, v19 offset:13312
	v_lshlrev_b32_e32 v82, 16, v82
	v_mul_f32_e32 v82, 0xbfb8aa3b, v82
	v_exp_f32_e32 v82, v82
	v_lshlrev_b32_e32 v20, 16, v20
	v_add_f32_e32 v82, 1.0, v82
	v_rcp_f32_e32 v82, v82
	s_nop 0
	v_mul_f32_e32 v20, v82, v20
	ds_write_b32 v0, v20 offset:14336
	v_lshlrev_b32_e32 v83, 16, v83
	v_mul_f32_e32 v83, 0xbfb8aa3b, v83
	v_exp_f32_e32 v83, v83
	v_lshlrev_b32_e32 v21, 16, v21
	v_add_f32_e32 v83, 1.0, v83
	v_rcp_f32_e32 v83, v83
	s_nop 0
	v_mul_f32_e32 v21, v83, v21
	ds_write_b32 v0, v21 offset:15360
	v_lshlrev_b32_e32 v84, 16, v84
	v_mul_f32_e32 v84, 0xbfb8aa3b, v84
	v_exp_f32_e32 v84, v84
	v_lshlrev_b32_e32 v22, 16, v22
	v_add_f32_e32 v84, 1.0, v84
	v_rcp_f32_e32 v84, v84
	s_nop 0
	v_mul_f32_e32 v22, v84, v22
	ds_write_b32 v0, v22 offset:16384
	v_lshlrev_b32_e32 v85, 16, v85
	v_mul_f32_e32 v85, 0xbfb8aa3b, v85
	v_exp_f32_e32 v85, v85
	v_lshlrev_b32_e32 v23, 16, v23
	v_add_f32_e32 v85, 1.0, v85
	v_rcp_f32_e32 v85, v85
	s_nop 0
	v_mul_f32_e32 v23, v85, v23
	ds_write_b32 v0, v23 offset:17408
	v_lshlrev_b32_e32 v86, 16, v86
	v_mul_f32_e32 v86, 0xbfb8aa3b, v86
	v_exp_f32_e32 v86, v86
	v_lshlrev_b32_e32 v24, 16, v24
	v_add_f32_e32 v86, 1.0, v86
	v_rcp_f32_e32 v86, v86
	s_nop 0
	v_mul_f32_e32 v24, v86, v24
	ds_write_b32 v0, v24 offset:18432
	v_lshlrev_b32_e32 v87, 16, v87
	v_mul_f32_e32 v87, 0xbfb8aa3b, v87
	v_exp_f32_e32 v87, v87
	v_lshlrev_b32_e32 v25, 16, v25
	v_add_f32_e32 v87, 1.0, v87
	v_rcp_f32_e32 v87, v87
	s_nop 0
	v_mul_f32_e32 v25, v87, v25
	ds_write_b32 v0, v25 offset:19456
	v_lshlrev_b32_e32 v88, 16, v88
	v_mul_f32_e32 v88, 0xbfb8aa3b, v88
	v_exp_f32_e32 v88, v88
	v_lshlrev_b32_e32 v26, 16, v26
	v_add_f32_e32 v88, 1.0, v88
	v_rcp_f32_e32 v88, v88
	s_nop 0
	v_mul_f32_e32 v26, v88, v26
	ds_write_b32 v0, v26 offset:20480
	v_lshlrev_b32_e32 v89, 16, v89
	v_mul_f32_e32 v89, 0xbfb8aa3b, v89
	v_exp_f32_e32 v89, v89
	v_lshlrev_b32_e32 v27, 16, v27
	v_add_f32_e32 v89, 1.0, v89
	v_rcp_f32_e32 v89, v89
	s_nop 0
	v_mul_f32_e32 v27, v89, v27
	ds_write_b32 v0, v27 offset:21504
	v_lshlrev_b32_e32 v90, 16, v90
	v_mul_f32_e32 v90, 0xbfb8aa3b, v90
	v_exp_f32_e32 v90, v90
	v_lshlrev_b32_e32 v28, 16, v28
	v_add_f32_e32 v90, 1.0, v90
	v_rcp_f32_e32 v90, v90
	s_nop 0
	v_mul_f32_e32 v28, v90, v28
	ds_write_b32 v0, v28 offset:22528
	v_lshlrev_b32_e32 v91, 16, v91
	v_mul_f32_e32 v91, 0xbfb8aa3b, v91
	v_exp_f32_e32 v91, v91
	v_lshlrev_b32_e32 v29, 16, v29
	v_add_f32_e32 v91, 1.0, v91
	v_rcp_f32_e32 v91, v91
	s_nop 0
	v_mul_f32_e32 v29, v91, v29
	ds_write_b32 v0, v29 offset:23552
	v_lshlrev_b32_e32 v92, 16, v92
	v_mul_f32_e32 v92, 0xbfb8aa3b, v92
	v_exp_f32_e32 v92, v92
	v_lshlrev_b32_e32 v30, 16, v30
	v_add_f32_e32 v92, 1.0, v92
	v_rcp_f32_e32 v92, v92
	s_nop 0
	v_mul_f32_e32 v30, v92, v30
	ds_write_b32 v0, v30 offset:24576
	v_lshlrev_b32_e32 v93, 16, v93
	v_mul_f32_e32 v93, 0xbfb8aa3b, v93
	v_exp_f32_e32 v93, v93
	v_lshlrev_b32_e32 v31, 16, v31
	v_add_f32_e32 v93, 1.0, v93
	v_rcp_f32_e32 v93, v93
	s_nop 0
	v_mul_f32_e32 v31, v93, v31
	ds_write_b32 v0, v31 offset:25600
	v_lshlrev_b32_e32 v94, 16, v94
	v_mul_f32_e32 v94, 0xbfb8aa3b, v94
	v_exp_f32_e32 v94, v94
	v_lshlrev_b32_e32 v32, 16, v32
	v_add_f32_e32 v94, 1.0, v94
	v_rcp_f32_e32 v94, v94
	s_nop 0
	v_mul_f32_e32 v32, v94, v32
	ds_write_b32 v0, v32 offset:26624
	v_lshlrev_b32_e32 v95, 16, v95
	v_mul_f32_e32 v95, 0xbfb8aa3b, v95
	v_exp_f32_e32 v95, v95
	v_lshlrev_b32_e32 v33, 16, v33
	v_add_f32_e32 v95, 1.0, v95
	v_rcp_f32_e32 v95, v95
	s_nop 0
	v_mul_f32_e32 v33, v95, v33
	ds_write_b32 v0, v33 offset:27648
	v_lshlrev_b32_e32 v96, 16, v96
	v_mul_f32_e32 v96, 0xbfb8aa3b, v96
	v_exp_f32_e32 v96, v96
	v_lshlrev_b32_e32 v34, 16, v34
	v_add_f32_e32 v96, 1.0, v96
	v_rcp_f32_e32 v96, v96
	s_nop 0
	v_mul_f32_e32 v34, v96, v34
	ds_write_b32 v0, v34 offset:28672
	v_lshlrev_b32_e32 v97, 16, v97
	v_mul_f32_e32 v97, 0xbfb8aa3b, v97
	v_exp_f32_e32 v97, v97
	v_lshlrev_b32_e32 v35, 16, v35
	v_add_f32_e32 v97, 1.0, v97
	v_rcp_f32_e32 v97, v97
	s_nop 0
	v_mul_f32_e32 v35, v97, v35
	ds_write_b32 v0, v35 offset:29696
	v_lshlrev_b32_e32 v98, 16, v98
	v_mul_f32_e32 v98, 0xbfb8aa3b, v98
	v_exp_f32_e32 v98, v98
	v_lshlrev_b32_e32 v36, 16, v36
	v_add_f32_e32 v98, 1.0, v98
	v_rcp_f32_e32 v98, v98
	s_nop 0
	v_mul_f32_e32 v36, v98, v36
	ds_write_b32 v0, v36 offset:30720
	v_lshlrev_b32_e32 v99, 16, v99
	v_mul_f32_e32 v99, 0xbfb8aa3b, v99
	v_exp_f32_e32 v99, v99
	v_lshlrev_b32_e32 v37, 16, v37
	v_add_f32_e32 v99, 1.0, v99
	v_rcp_f32_e32 v99, v99
	s_nop 0
	v_mul_f32_e32 v37, v99, v37
	ds_write_b32 v0, v37 offset:31744
	v_lshlrev_b32_e32 v100, 16, v100
	v_mul_f32_e32 v100, 0xbfb8aa3b, v100
	v_exp_f32_e32 v100, v100
	v_lshlrev_b32_e32 v38, 16, v38
	v_add_f32_e32 v100, 1.0, v100
	v_rcp_f32_e32 v100, v100
	s_nop 0
	v_mul_f32_e32 v38, v100, v38
	ds_write_b32 v0, v38 offset:32768
	v_lshlrev_b32_e32 v101, 16, v101
	v_mul_f32_e32 v101, 0xbfb8aa3b, v101
	v_exp_f32_e32 v101, v101
	v_lshlrev_b32_e32 v39, 16, v39
	v_add_f32_e32 v101, 1.0, v101
	v_rcp_f32_e32 v101, v101
	s_nop 0
	v_mul_f32_e32 v39, v101, v39
	ds_write_b32 v0, v39 offset:33792
	v_lshlrev_b32_e32 v102, 16, v102
	v_mul_f32_e32 v102, 0xbfb8aa3b, v102
	v_exp_f32_e32 v102, v102
	v_lshlrev_b32_e32 v40, 16, v40
	v_add_f32_e32 v102, 1.0, v102
	v_rcp_f32_e32 v102, v102
	s_nop 0
	v_mul_f32_e32 v40, v102, v40
	ds_write_b32 v0, v40 offset:34816
	v_lshlrev_b32_e32 v103, 16, v103
	v_mul_f32_e32 v103, 0xbfb8aa3b, v103
	v_exp_f32_e32 v103, v103
	v_lshlrev_b32_e32 v41, 16, v41
	v_add_f32_e32 v103, 1.0, v103
	v_rcp_f32_e32 v103, v103
	s_nop 0
	v_mul_f32_e32 v41, v103, v41
	ds_write_b32 v0, v41 offset:35840
	v_lshlrev_b32_e32 v104, 16, v104
	v_mul_f32_e32 v104, 0xbfb8aa3b, v104
	v_exp_f32_e32 v104, v104
	v_lshlrev_b32_e32 v42, 16, v42
	v_add_f32_e32 v104, 1.0, v104
	v_rcp_f32_e32 v104, v104
	s_nop 0
	v_mul_f32_e32 v42, v104, v42
	ds_write_b32 v0, v42 offset:36864
	v_lshlrev_b32_e32 v105, 16, v105
	v_mul_f32_e32 v105, 0xbfb8aa3b, v105
	v_exp_f32_e32 v105, v105
	v_lshlrev_b32_e32 v43, 16, v43
	v_add_f32_e32 v105, 1.0, v105
	v_rcp_f32_e32 v105, v105
	s_nop 0
	v_mul_f32_e32 v43, v105, v43
	ds_write_b32 v0, v43 offset:37888
	v_lshlrev_b32_e32 v106, 16, v106
	v_mul_f32_e32 v106, 0xbfb8aa3b, v106
	v_exp_f32_e32 v106, v106
	v_lshlrev_b32_e32 v44, 16, v44
	v_add_f32_e32 v106, 1.0, v106
	v_rcp_f32_e32 v106, v106
	s_nop 0
	v_mul_f32_e32 v44, v106, v44
	ds_write_b32 v0, v44 offset:38912
	v_lshlrev_b32_e32 v107, 16, v107
	v_mul_f32_e32 v107, 0xbfb8aa3b, v107
	v_exp_f32_e32 v107, v107
	v_lshlrev_b32_e32 v45, 16, v45
	v_add_f32_e32 v107, 1.0, v107
	v_rcp_f32_e32 v107, v107
	s_nop 0
	v_mul_f32_e32 v45, v107, v45
	ds_write_b32 v0, v45 offset:39936
	v_lshlrev_b32_e32 v108, 16, v108
	v_mul_f32_e32 v108, 0xbfb8aa3b, v108
	v_exp_f32_e32 v108, v108
	v_lshlrev_b32_e32 v46, 16, v46
	v_add_f32_e32 v108, 1.0, v108
	v_rcp_f32_e32 v108, v108
	s_nop 0
	v_mul_f32_e32 v46, v108, v46
	ds_write_b32 v0, v46 offset:40960
	v_lshlrev_b32_e32 v109, 16, v109
	v_mul_f32_e32 v109, 0xbfb8aa3b, v109
	v_exp_f32_e32 v109, v109
	v_lshlrev_b32_e32 v47, 16, v47
	v_add_f32_e32 v109, 1.0, v109
	v_rcp_f32_e32 v109, v109
	s_nop 0
	v_mul_f32_e32 v47, v109, v47
	ds_write_b32 v0, v47 offset:41984
	v_lshlrev_b32_e32 v110, 16, v110
	v_mul_f32_e32 v110, 0xbfb8aa3b, v110
	v_exp_f32_e32 v110, v110
	v_lshlrev_b32_e32 v48, 16, v48
	v_add_f32_e32 v110, 1.0, v110
	v_rcp_f32_e32 v110, v110
	s_nop 0
	v_mul_f32_e32 v48, v110, v48
	ds_write_b32 v0, v48 offset:43008
	v_lshlrev_b32_e32 v111, 16, v111
	v_mul_f32_e32 v111, 0xbfb8aa3b, v111
	v_exp_f32_e32 v111, v111
	v_lshlrev_b32_e32 v49, 16, v49
	v_add_f32_e32 v111, 1.0, v111
	v_rcp_f32_e32 v111, v111
	s_nop 0
	v_mul_f32_e32 v49, v111, v49
	ds_write_b32 v0, v49 offset:44032
	v_lshlrev_b32_e32 v112, 16, v112
	v_mul_f32_e32 v112, 0xbfb8aa3b, v112
	v_exp_f32_e32 v112, v112
	v_lshlrev_b32_e32 v50, 16, v50
	v_add_f32_e32 v112, 1.0, v112
	v_rcp_f32_e32 v112, v112
	s_nop 0
	v_mul_f32_e32 v50, v112, v50
	ds_write_b32 v0, v50 offset:45056
	v_lshlrev_b32_e32 v113, 16, v113
	v_mul_f32_e32 v113, 0xbfb8aa3b, v113
	v_exp_f32_e32 v113, v113
	v_lshlrev_b32_e32 v51, 16, v51
	v_add_f32_e32 v113, 1.0, v113
	v_rcp_f32_e32 v113, v113
	s_nop 0
	v_mul_f32_e32 v51, v113, v51
	ds_write_b32 v0, v51 offset:46080
	v_lshlrev_b32_e32 v114, 16, v114
	v_mul_f32_e32 v114, 0xbfb8aa3b, v114
	v_exp_f32_e32 v114, v114
	v_lshlrev_b32_e32 v52, 16, v52
	v_add_f32_e32 v114, 1.0, v114
	v_rcp_f32_e32 v114, v114
	s_nop 0
	v_mul_f32_e32 v52, v114, v52
	ds_write_b32 v0, v52 offset:47104
	v_lshlrev_b32_e32 v115, 16, v115
	v_mul_f32_e32 v115, 0xbfb8aa3b, v115
	v_exp_f32_e32 v115, v115
	v_lshlrev_b32_e32 v53, 16, v53
	v_add_f32_e32 v115, 1.0, v115
	v_rcp_f32_e32 v115, v115
	s_nop 0
	v_mul_f32_e32 v53, v115, v53
	ds_write_b32 v0, v53 offset:48128
	v_lshlrev_b32_e32 v116, 16, v116
	v_mul_f32_e32 v116, 0xbfb8aa3b, v116
	v_exp_f32_e32 v116, v116
	v_lshlrev_b32_e32 v54, 16, v54
	v_add_f32_e32 v116, 1.0, v116
	v_rcp_f32_e32 v116, v116
	s_nop 0
	v_mul_f32_e32 v54, v116, v54
	ds_write_b32 v0, v54 offset:49152
	v_lshlrev_b32_e32 v117, 16, v117
	v_mul_f32_e32 v117, 0xbfb8aa3b, v117
	v_exp_f32_e32 v117, v117
	v_lshlrev_b32_e32 v55, 16, v55
	v_add_f32_e32 v117, 1.0, v117
	v_rcp_f32_e32 v117, v117
	s_nop 0
	v_mul_f32_e32 v55, v117, v55
	ds_write_b32 v0, v55 offset:50176
	v_lshlrev_b32_e32 v118, 16, v118
	v_mul_f32_e32 v118, 0xbfb8aa3b, v118
	v_exp_f32_e32 v118, v118
	v_lshlrev_b32_e32 v56, 16, v56
	v_add_f32_e32 v118, 1.0, v118
	v_rcp_f32_e32 v118, v118
	s_nop 0
	v_mul_f32_e32 v56, v118, v56
	ds_write_b32 v0, v56 offset:51200
	v_lshlrev_b32_e32 v119, 16, v119
	v_mul_f32_e32 v119, 0xbfb8aa3b, v119
	v_exp_f32_e32 v119, v119
	v_lshlrev_b32_e32 v57, 16, v57
	v_add_f32_e32 v119, 1.0, v119
	v_rcp_f32_e32 v119, v119
	s_nop 0
	v_mul_f32_e32 v57, v119, v57
	ds_write_b32 v0, v57 offset:52224
	v_lshlrev_b32_e32 v120, 16, v120
	v_mul_f32_e32 v120, 0xbfb8aa3b, v120
	v_exp_f32_e32 v120, v120
	v_lshlrev_b32_e32 v58, 16, v58
	v_add_f32_e32 v120, 1.0, v120
	v_rcp_f32_e32 v120, v120
	s_nop 0
	v_mul_f32_e32 v58, v120, v58
	ds_write_b32 v0, v58 offset:53248
	v_lshlrev_b32_e32 v121, 16, v121
	v_mul_f32_e32 v121, 0xbfb8aa3b, v121
	v_exp_f32_e32 v121, v121
	v_lshlrev_b32_e32 v59, 16, v59
	v_add_f32_e32 v121, 1.0, v121
	v_rcp_f32_e32 v121, v121
	s_nop 0
	v_mul_f32_e32 v59, v121, v59
	ds_write_b32 v0, v59 offset:54272
	v_lshlrev_b32_e32 v122, 16, v122
	v_mul_f32_e32 v122, 0xbfb8aa3b, v122
	v_exp_f32_e32 v122, v122
	v_lshlrev_b32_e32 v60, 16, v60
	v_add_f32_e32 v122, 1.0, v122
	v_rcp_f32_e32 v122, v122
	s_nop 0
	v_mul_f32_e32 v60, v122, v60
	ds_write_b32 v0, v60 offset:55296
	v_lshlrev_b32_e32 v123, 16, v123
	v_mul_f32_e32 v123, 0xbfb8aa3b, v123
	v_exp_f32_e32 v123, v123
	v_lshlrev_b32_e32 v61, 16, v61
	v_add_f32_e32 v123, 1.0, v123
	v_rcp_f32_e32 v123, v123
	s_nop 0
	v_mul_f32_e32 v61, v123, v61
	ds_write_b32 v0, v61 offset:56320
	v_lshlrev_b32_e32 v124, 16, v124
	v_mul_f32_e32 v124, 0xbfb8aa3b, v124
	v_exp_f32_e32 v124, v124
	v_lshlrev_b32_e32 v62, 16, v62
	v_add_f32_e32 v124, 1.0, v124
	v_rcp_f32_e32 v124, v124
	s_nop 0
	v_mul_f32_e32 v62, v124, v62
	ds_write_b32 v0, v62 offset:57344
	v_lshlrev_b32_e32 v125, 16, v125
	v_mul_f32_e32 v125, 0xbfb8aa3b, v125
	v_exp_f32_e32 v125, v125
	v_lshlrev_b32_e32 v63, 16, v63
	v_add_f32_e32 v125, 1.0, v125
	v_rcp_f32_e32 v125, v125
	s_nop 0
	v_mul_f32_e32 v63, v125, v63
	ds_write_b32 v0, v63 offset:58368
	v_lshlrev_b32_e32 v126, 16, v126
	v_mul_f32_e32 v126, 0xbfb8aa3b, v126
	v_exp_f32_e32 v126, v126
	v_lshlrev_b32_e32 v64, 16, v64
	v_add_f32_e32 v126, 1.0, v126
	v_rcp_f32_e32 v126, v126
	s_nop 0
	v_mul_f32_e32 v64, v126, v64
	ds_write_b32 v0, v64 offset:59392
	v_lshlrev_b32_e32 v127, 16, v127
	v_mul_f32_e32 v127, 0xbfb8aa3b, v127
	v_exp_f32_e32 v127, v127
	v_lshlrev_b32_e32 v65, 16, v65
	v_add_f32_e32 v127, 1.0, v127
	v_rcp_f32_e32 v127, v127
	s_nop 0
	v_mul_f32_e32 v65, v127, v65
	ds_write_b32 v0, v65 offset:60416
	v_lshlrev_b32_e32 v128, 16, v128
	v_mul_f32_e32 v128, 0xbfb8aa3b, v128
	v_exp_f32_e32 v128, v128
	v_lshlrev_b32_e32 v66, 16, v66
	v_add_f32_e32 v128, 1.0, v128
	v_rcp_f32_e32 v128, v128
	s_nop 0
	v_mul_f32_e32 v66, v128, v66
	ds_write_b32 v0, v66 offset:61440
	v_lshlrev_b32_e32 v129, 16, v129
	v_mul_f32_e32 v129, 0xbfb8aa3b, v129
	v_exp_f32_e32 v129, v129
	v_lshlrev_b32_e32 v67, 16, v67
	v_add_f32_e32 v129, 1.0, v129
	v_rcp_f32_e32 v129, v129
	s_nop 0
	v_mul_f32_e32 v67, v129, v67
	ds_write_b32 v0, v67 offset:62464

.LBB0_303:
	s_lshl_b32 s0, s40, 5
	v_mov_b32_e32 v12, v218
	s_and_b32 s4, s0, 0x3f80
	s_movk_i32 s0, 0x80
	s_nop 0
	v_cmp_gt_i32_e32 vcc, s0, v12
	s_and_saveexec_b64 s[0:1], vcc
	s_cbranch_execz .LBB0_309
	v_add_u32_e32 v2, s4, v12
	v_ashrrev_i32_e32 v3, 31, v2
	v_lshlrev_b64 v[2:3], 9, v[2:3]
	v_lshl_add_u64 v[2:3], s[94:95], 0, v[2:3]
	v_mov_b32_e32 v0, 0
	s_mov_b64 s[2:3], 0
	s_mov_b64 s[6:7], 0x10085100
	v_lshl_add_u64 v[14:15], v[2:3], 0, s[6:7]
	global_load_dwordx4 v[16:19], v[14:15], off
	global_load_dwordx4 v[20:23], v[14:15], off offset:16
	global_load_dwordx4 v[24:27], v[14:15], off offset:32
	global_load_dwordx4 v[28:31], v[14:15], off offset:48
	global_load_dwordx4 v[32:35], v[14:15], off offset:64
	global_load_dwordx4 v[36:39], v[14:15], off offset:80
	global_load_dwordx4 v[40:43], v[14:15], off offset:96
	global_load_dwordx4 v[44:47], v[14:15], off offset:112
	global_load_dwordx4 v[48:51], v[14:15], off offset:128
	global_load_dwordx4 v[52:55], v[14:15], off offset:144
	global_load_dwordx4 v[56:59], v[14:15], off offset:160
	global_load_dwordx4 v[60:63], v[14:15], off offset:176
	global_load_dwordx4 v[64:67], v[14:15], off offset:192
	global_load_dwordx4 v[68:71], v[14:15], off offset:208
	global_load_dwordx4 v[72:75], v[14:15], off offset:224
	global_load_dwordx4 v[76:79], v[14:15], off offset:240
	global_load_dwordx4 v[80:83], v[14:15], off offset:256
	global_load_dwordx4 v[84:87], v[14:15], off offset:272
	global_load_dwordx4 v[88:91], v[14:15], off offset:288
	global_load_dwordx4 v[92:95], v[14:15], off offset:304
	global_load_dwordx4 v[96:99], v[14:15], off offset:320
	global_load_dwordx4 v[100:103], v[14:15], off offset:336
	global_load_dwordx4 v[104:107], v[14:15], off offset:352
	global_load_dwordx4 v[108:111], v[14:15], off offset:368
	global_load_dwordx4 v[112:115], v[14:15], off offset:384
	global_load_dwordx4 v[116:119], v[14:15], off offset:400
	global_load_dwordx4 v[120:123], v[14:15], off offset:416
	global_load_dwordx4 v[124:127], v[14:15], off offset:432
	global_load_dwordx4 v[128:131], v[14:15], off offset:448
	global_load_dwordx4 v[132:135], v[14:15], off offset:464
	global_load_dwordx4 v[136:139], v[14:15], off offset:480
	global_load_dwordx4 v[140:143], v[14:15], off offset:496
	v_mov_b32_e32 v144, 0
	v_mov_b32_e32 v145, 0
	v_mov_b32_e32 v146, 0
	v_mov_b32_e32 v147, 0
	v_mov_b32_e32 v148, 0
	v_mov_b32_e32 v149, 0
	v_mov_b32_e32 v150, 0
	v_mov_b32_e32 v151, 0
	s_waitcnt vmcnt(28)
	v_lshlrev_b32_e32 v152, 16, v16
	v_and_b32_e32 v153, 0xffff0000, v16
	v_add_f32_e32 v144, v144, v152
	v_add_f32_e32 v148, v148, v153
	v_lshlrev_b32_e32 v152, 16, v17
	v_and_b32_e32 v153, 0xffff0000, v17
	v_add_f32_e32 v145, v145, v152
	v_add_f32_e32 v149, v149, v153
	v_lshlrev_b32_e32 v152, 16, v18
	v_and_b32_e32 v153, 0xffff0000, v18
	v_add_f32_e32 v146, v146, v152
	v_add_f32_e32 v150, v150, v153
	v_lshlrev_b32_e32 v152, 16, v19
	v_and_b32_e32 v153, 0xffff0000, v19
	v_add_f32_e32 v147, v147, v152
	v_add_f32_e32 v151, v151, v153
	v_lshlrev_b32_e32 v152, 16, v20
	v_and_b32_e32 v153, 0xffff0000, v20
	v_add_f32_e32 v144, v144, v152
	v_add_f32_e32 v148, v148, v153
	v_lshlrev_b32_e32 v152, 16, v21
	v_and_b32_e32 v153, 0xffff0000, v21
	v_add_f32_e32 v145, v145, v152
	v_add_f32_e32 v149, v149, v153
	v_lshlrev_b32_e32 v152, 16, v22
	v_and_b32_e32 v153, 0xffff0000, v22
	v_add_f32_e32 v146, v146, v152
	v_add_f32_e32 v150, v150, v153
	v_lshlrev_b32_e32 v152, 16, v23
	v_and_b32_e32 v153, 0xffff0000, v23
	v_add_f32_e32 v147, v147, v152
	v_add_f32_e32 v151, v151, v153
	v_lshlrev_b32_e32 v152, 16, v24
	v_and_b32_e32 v153, 0xffff0000, v24
	v_add_f32_e32 v144, v144, v152
	v_add_f32_e32 v148, v148, v153
	v_lshlrev_b32_e32 v152, 16, v25
	v_and_b32_e32 v153, 0xffff0000, v25
	v_add_f32_e32 v145, v145, v152
	v_add_f32_e32 v149, v149, v153
	v_lshlrev_b32_e32 v152, 16, v26
	v_and_b32_e32 v153, 0xffff0000, v26
	v_add_f32_e32 v146, v146, v152
	v_add_f32_e32 v150, v150, v153
	v_lshlrev_b32_e32 v152, 16, v27
	v_and_b32_e32 v153, 0xffff0000, v27
	v_add_f32_e32 v147, v147, v152
	v_add_f32_e32 v151, v151, v153
	v_lshlrev_b32_e32 v152, 16, v28
	v_and_b32_e32 v153, 0xffff0000, v28
	v_add_f32_e32 v144, v144, v152
	v_add_f32_e32 v148, v148, v153
	v_lshlrev_b32_e32 v152, 16, v29
	v_and_b32_e32 v153, 0xffff0000, v29
	v_add_f32_e32 v145, v145, v152
	v_add_f32_e32 v149, v149, v153
	v_lshlrev_b32_e32 v152, 16, v30
	v_and_b32_e32 v153, 0xffff0000, v30
	v_add_f32_e32 v146, v146, v152
	v_add_f32_e32 v150, v150, v153
	v_lshlrev_b32_e32 v152, 16, v31
	v_and_b32_e32 v153, 0xffff0000, v31
	v_add_f32_e32 v147, v147, v152
	v_add_f32_e32 v151, v151, v153
	s_waitcnt vmcnt(24)
	v_lshlrev_b32_e32 v152, 16, v32
	v_and_b32_e32 v153, 0xffff0000, v32
	v_add_f32_e32 v144, v144, v152
	v_add_f32_e32 v148, v148, v153
	v_lshlrev_b32_e32 v152, 16, v33
	v_and_b32_e32 v153, 0xffff0000, v33
	v_add_f32_e32 v145, v145, v152
	v_add_f32_e32 v149, v149, v153
	v_lshlrev_b32_e32 v152, 16, v34
	v_and_b32_e32 v153, 0xffff0000, v34
	v_add_f32_e32 v146, v146, v152
	v_add_f32_e32 v150, v150, v153
	v_lshlrev_b32_e32 v152, 16, v35
	v_and_b32_e32 v153, 0xffff0000, v35
	v_add_f32_e32 v147, v147, v152
	v_add_f32_e32 v151, v151, v153
	v_lshlrev_b32_e32 v152, 16, v36
	v_and_b32_e32 v153, 0xffff0000, v36
	v_add_f32_e32 v144, v144, v152
	v_add_f32_e32 v148, v148, v153
	v_lshlrev_b32_e32 v152, 16, v37
	v_and_b32_e32 v153, 0xffff0000, v37
	v_add_f32_e32 v145, v145, v152
	v_add_f32_e32 v149, v149, v153
	v_lshlrev_b32_e32 v152, 16, v38
	v_and_b32_e32 v153, 0xffff0000, v38
	v_add_f32_e32 v146, v146, v152
	v_add_f32_e32 v150, v150, v153
	v_lshlrev_b32_e32 v152, 16, v39
	v_and_b32_e32 v153, 0xffff0000, v39
	v_add_f32_e32 v147, v147, v152
	v_add_f32_e32 v151, v151, v153
	v_lshlrev_b32_e32 v152, 16, v40
	v_and_b32_e32 v153, 0xffff0000, v40
	v_add_f32_e32 v144, v144, v152
	v_add_f32_e32 v148, v148, v153
	v_lshlrev_b32_e32 v152, 16, v41
	v_and_b32_e32 v153, 0xffff0000, v41
	v_add_f32_e32 v145, v145, v152
	v_add_f32_e32 v149, v149, v153
	v_lshlrev_b32_e32 v152, 16, v42
	v_and_b32_e32 v153, 0xffff0000, v42
	v_add_f32_e32 v146, v146, v152
	v_add_f32_e32 v150, v150, v153
	v_lshlrev_b32_e32 v152, 16, v43
	v_and_b32_e32 v153, 0xffff0000, v43
	v_add_f32_e32 v147, v147, v152
	v_add_f32_e32 v151, v151, v153
	v_lshlrev_b32_e32 v152, 16, v44
	v_and_b32_e32 v153, 0xffff0000, v44
	v_add_f32_e32 v144, v144, v152
	v_add_f32_e32 v148, v148, v153
	v_lshlrev_b32_e32 v152, 16, v45
	v_and_b32_e32 v153, 0xffff0000, v45
	v_add_f32_e32 v145, v145, v152
	v_add_f32_e32 v149, v149, v153
	v_lshlrev_b32_e32 v152, 16, v46
	v_and_b32_e32 v153, 0xffff0000, v46
	v_add_f32_e32 v146, v146, v152
	v_add_f32_e32 v150, v150, v153
	v_lshlrev_b32_e32 v152, 16, v47
	v_and_b32_e32 v153, 0xffff0000, v47
	v_add_f32_e32 v147, v147, v152
	v_add_f32_e32 v151, v151, v153
	s_waitcnt vmcnt(20)
	v_lshlrev_b32_e32 v152, 16, v48
	v_and_b32_e32 v153, 0xffff0000, v48
	v_add_f32_e32 v144, v144, v152
	v_add_f32_e32 v148, v148, v153
	v_lshlrev_b32_e32 v152, 16, v49
	v_and_b32_e32 v153, 0xffff0000, v49
	v_add_f32_e32 v145, v145, v152
	v_add_f32_e32 v149, v149, v153
	v_lshlrev_b32_e32 v152, 16, v50
	v_and_b32_e32 v153, 0xffff0000, v50
	v_add_f32_e32 v146, v146, v152
	v_add_f32_e32 v150, v150, v153
	v_lshlrev_b32_e32 v152, 16, v51
	v_and_b32_e32 v153, 0xffff0000, v51
	v_add_f32_e32 v147, v147, v152
	v_add_f32_e32 v151, v151, v153
	v_lshlrev_b32_e32 v152, 16, v52
	v_and_b32_e32 v153, 0xffff0000, v52
	v_add_f32_e32 v144, v144, v152
	v_add_f32_e32 v148, v148, v153
	v_lshlrev_b32_e32 v152, 16, v53
	v_and_b32_e32 v153, 0xffff0000, v53
	v_add_f32_e32 v145, v145, v152
	v_add_f32_e32 v149, v149, v153
	v_lshlrev_b32_e32 v152, 16, v54
	v_and_b32_e32 v153, 0xffff0000, v54
	v_add_f32_e32 v146, v146, v152
	v_add_f32_e32 v150, v150, v153
	v_lshlrev_b32_e32 v152, 16, v55
	v_and_b32_e32 v153, 0xffff0000, v55
	v_add_f32_e32 v147, v147, v152
	v_add_f32_e32 v151, v151, v153
	v_lshlrev_b32_e32 v152, 16, v56
	v_and_b32_e32 v153, 0xffff0000, v56
	v_add_f32_e32 v144, v144, v152
	v_add_f32_e32 v148, v148, v153
	v_lshlrev_b32_e32 v152, 16, v57
	v_and_b32_e32 v153, 0xffff0000, v57
	v_add_f32_e32 v145, v145, v152
	v_add_f32_e32 v149, v149, v153
	v_lshlrev_b32_e32 v152, 16, v58
	v_and_b32_e32 v153, 0xffff0000, v58
	v_add_f32_e32 v146, v146, v152
	v_add_f32_e32 v150, v150, v153
	v_lshlrev_b32_e32 v152, 16, v59
	v_and_b32_e32 v153, 0xffff0000, v59
	v_add_f32_e32 v147, v147, v152
	v_add_f32_e32 v151, v151, v153
	v_lshlrev_b32_e32 v152, 16, v60
	v_and_b32_e32 v153, 0xffff0000, v60
	v_add_f32_e32 v144, v144, v152
	v_add_f32_e32 v148, v148, v153
	v_lshlrev_b32_e32 v152, 16, v61
	v_and_b32_e32 v153, 0xffff0000, v61
	v_add_f32_e32 v145, v145, v152
	v_add_f32_e32 v149, v149, v153
	v_lshlrev_b32_e32 v152, 16, v62
	v_and_b32_e32 v153, 0xffff0000, v62
	v_add_f32_e32 v146, v146, v152
	v_add_f32_e32 v150, v150, v153
	v_lshlrev_b32_e32 v152, 16, v63
	v_and_b32_e32 v153, 0xffff0000, v63
	v_add_f32_e32 v147, v147, v152
	v_add_f32_e32 v151, v151, v153
	s_waitcnt vmcnt(16)
	v_lshlrev_b32_e32 v152, 16, v64
	v_and_b32_e32 v153, 0xffff0000, v64
	v_add_f32_e32 v144, v144, v152
	v_add_f32_e32 v148, v148, v153
	v_lshlrev_b32_e32 v152, 16, v65
	v_and_b32_e32 v153, 0xffff0000, v65
	v_add_f32_e32 v145, v145, v152
	v_add_f32_e32 v149, v149, v153
	v_lshlrev_b32_e32 v152, 16, v66
	v_and_b32_e32 v153, 0xffff0000, v66
	v_add_f32_e32 v146, v146, v152
	v_add_f32_e32 v150, v150, v153
	v_lshlrev_b32_e32 v152, 16, v67
	v_and_b32_e32 v153, 0xffff0000, v67
	v_add_f32_e32 v147, v147, v152
	v_add_f32_e32 v151, v151, v153
	v_lshlrev_b32_e32 v152, 16, v68
	v_and_b32_e32 v153, 0xffff0000, v68
	v_add_f32_e32 v144, v144, v152
	v_add_f32_e32 v148, v148, v153
	v_lshlrev_b32_e32 v152, 16, v69
	v_and_b32_e32 v153, 0xffff0000, v69
	v_add_f32_e32 v145, v145, v152
	v_add_f32_e32 v149, v149, v153
	v_lshlrev_b32_e32 v152, 16, v70
	v_and_b32_e32 v153, 0xffff0000, v70
	v_add_f32_e32 v146, v146, v152
	v_add_f32_e32 v150, v150, v153
	v_lshlrev_b32_e32 v152, 16, v71
	v_and_b32_e32 v153, 0xffff0000, v71
	v_add_f32_e32 v147, v147, v152
	v_add_f32_e32 v151, v151, v153
	v_lshlrev_b32_e32 v152, 16, v72
	v_and_b32_e32 v153, 0xffff0000, v72
	v_add_f32_e32 v144, v144, v152
	v_add_f32_e32 v148, v148, v153
	v_lshlrev_b32_e32 v152, 16, v73
	v_and_b32_e32 v153, 0xffff0000, v73
	v_add_f32_e32 v145, v145, v152
	v_add_f32_e32 v149, v149, v153
	v_lshlrev_b32_e32 v152, 16, v74
	v_and_b32_e32 v153, 0xffff0000, v74
	v_add_f32_e32 v146, v146, v152
	v_add_f32_e32 v150, v150, v153
	v_lshlrev_b32_e32 v152, 16, v75
	v_and_b32_e32 v153, 0xffff0000, v75
	v_add_f32_e32 v147, v147, v152
	v_add_f32_e32 v151, v151, v153
	v_lshlrev_b32_e32 v152, 16, v76
	v_and_b32_e32 v153, 0xffff0000, v76
	v_add_f32_e32 v144, v144, v152
	v_add_f32_e32 v148, v148, v153
	v_lshlrev_b32_e32 v152, 16, v77
	v_and_b32_e32 v153, 0xffff0000, v77
	v_add_f32_e32 v145, v145, v152
	v_add_f32_e32 v149, v149, v153
	v_lshlrev_b32_e32 v152, 16, v78
	v_and_b32_e32 v153, 0xffff0000, v78
	v_add_f32_e32 v146, v146, v152
	v_add_f32_e32 v150, v150, v153
	v_lshlrev_b32_e32 v152, 16, v79
	v_and_b32_e32 v153, 0xffff0000, v79
	v_add_f32_e32 v147, v147, v152
	v_add_f32_e32 v151, v151, v153
	s_waitcnt vmcnt(12)
	v_lshlrev_b32_e32 v152, 16, v80
	v_and_b32_e32 v153, 0xffff0000, v80
	v_add_f32_e32 v144, v144, v152
	v_add_f32_e32 v148, v148, v153
	v_lshlrev_b32_e32 v152, 16, v81
	v_and_b32_e32 v153, 0xffff0000, v81
	v_add_f32_e32 v145, v145, v152
	v_add_f32_e32 v149, v149, v153
	v_lshlrev_b32_e32 v152, 16, v82
	v_and_b32_e32 v153, 0xffff0000, v82
	v_add_f32_e32 v146, v146, v152
	v_add_f32_e32 v150, v150, v153
	v_lshlrev_b32_e32 v152, 16, v83
	v_and_b32_e32 v153, 0xffff0000, v83
	v_add_f32_e32 v147, v147, v152
	v_add_f32_e32 v151, v151, v153
	v_lshlrev_b32_e32 v152, 16, v84
	v_and_b32_e32 v153, 0xffff0000, v84
	v_add_f32_e32 v144, v144, v152
	v_add_f32_e32 v148, v148, v153
	v_lshlrev_b32_e32 v152, 16, v85
	v_and_b32_e32 v153, 0xffff0000, v85
	v_add_f32_e32 v145, v145, v152
	v_add_f32_e32 v149, v149, v153
	v_lshlrev_b32_e32 v152, 16, v86
	v_and_b32_e32 v153, 0xffff0000, v86
	v_add_f32_e32 v146, v146, v152
	v_add_f32_e32 v150, v150, v153
	v_lshlrev_b32_e32 v152, 16, v87
	v_and_b32_e32 v153, 0xffff0000, v87
	v_add_f32_e32 v147, v147, v152
	v_add_f32_e32 v151, v151, v153
	v_lshlrev_b32_e32 v152, 16, v88
	v_and_b32_e32 v153, 0xffff0000, v88
	v_add_f32_e32 v144, v144, v152
	v_add_f32_e32 v148, v148, v153
	v_lshlrev_b32_e32 v152, 16, v89
	v_and_b32_e32 v153, 0xffff0000, v89
	v_add_f32_e32 v145, v145, v152
	v_add_f32_e32 v149, v149, v153
	v_lshlrev_b32_e32 v152, 16, v90
	v_and_b32_e32 v153, 0xffff0000, v90
	v_add_f32_e32 v146, v146, v152
	v_add_f32_e32 v150, v150, v153
	v_lshlrev_b32_e32 v152, 16, v91
	v_and_b32_e32 v153, 0xffff0000, v91
	v_add_f32_e32 v147, v147, v152
	v_add_f32_e32 v151, v151, v153
	v_lshlrev_b32_e32 v152, 16, v92
	v_and_b32_e32 v153, 0xffff0000, v92
	v_add_f32_e32 v144, v144, v152
	v_add_f32_e32 v148, v148, v153
	v_lshlrev_b32_e32 v152, 16, v93
	v_and_b32_e32 v153, 0xffff0000, v93
	v_add_f32_e32 v145, v145, v152
	v_add_f32_e32 v149, v149, v153
	v_lshlrev_b32_e32 v152, 16, v94
	v_and_b32_e32 v153, 0xffff0000, v94
	v_add_f32_e32 v146, v146, v152
	v_add_f32_e32 v150, v150, v153
	v_lshlrev_b32_e32 v152, 16, v95
	v_and_b32_e32 v153, 0xffff0000, v95
	v_add_f32_e32 v147, v147, v152
	v_add_f32_e32 v151, v151, v153
	s_waitcnt vmcnt(8)
	v_lshlrev_b32_e32 v152, 16, v96
	v_and_b32_e32 v153, 0xffff0000, v96
	v_add_f32_e32 v144, v144, v152
	v_add_f32_e32 v148, v148, v153
	v_lshlrev_b32_e32 v152, 16, v97
	v_and_b32_e32 v153, 0xffff0000, v97
	v_add_f32_e32 v145, v145, v152
	v_add_f32_e32 v149, v149, v153
	v_lshlrev_b32_e32 v152, 16, v98
	v_and_b32_e32 v153, 0xffff0000, v98
	v_add_f32_e32 v146, v146, v152
	v_add_f32_e32 v150, v150, v153
	v_lshlrev_b32_e32 v152, 16, v99
	v_and_b32_e32 v153, 0xffff0000, v99
	v_add_f32_e32 v147, v147, v152
	v_add_f32_e32 v151, v151, v153
	v_lshlrev_b32_e32 v152, 16, v100
	v_and_b32_e32 v153, 0xffff0000, v100
	v_add_f32_e32 v144, v144, v152
	v_add_f32_e32 v148, v148, v153
	v_lshlrev_b32_e32 v152, 16, v101
	v_and_b32_e32 v153, 0xffff0000, v101
	v_add_f32_e32 v145, v145, v152
	v_add_f32_e32 v149, v149, v153
	v_lshlrev_b32_e32 v152, 16, v102
	v_and_b32_e32 v153, 0xffff0000, v102
	v_add_f32_e32 v146, v146, v152
	v_add_f32_e32 v150, v150, v153
	v_lshlrev_b32_e32 v152, 16, v103
	v_and_b32_e32 v153, 0xffff0000, v103
	v_add_f32_e32 v147, v147, v152
	v_add_f32_e32 v151, v151, v153
	v_lshlrev_b32_e32 v152, 16, v104
	v_and_b32_e32 v153, 0xffff0000, v104
	v_add_f32_e32 v144, v144, v152
	v_add_f32_e32 v148, v148, v153
	v_lshlrev_b32_e32 v152, 16, v105
	v_and_b32_e32 v153, 0xffff0000, v105
	v_add_f32_e32 v145, v145, v152
	v_add_f32_e32 v149, v149, v153
	v_lshlrev_b32_e32 v152, 16, v106
	v_and_b32_e32 v153, 0xffff0000, v106
	v_add_f32_e32 v146, v146, v152
	v_add_f32_e32 v150, v150, v153
	v_lshlrev_b32_e32 v152, 16, v107
	v_and_b32_e32 v153, 0xffff0000, v107
	v_add_f32_e32 v147, v147, v152
	v_add_f32_e32 v151, v151, v153
	v_lshlrev_b32_e32 v152, 16, v108
	v_and_b32_e32 v153, 0xffff0000, v108
	v_add_f32_e32 v144, v144, v152
	v_add_f32_e32 v148, v148, v153
	v_lshlrev_b32_e32 v152, 16, v109
	v_and_b32_e32 v153, 0xffff0000, v109
	v_add_f32_e32 v145, v145, v152
	v_add_f32_e32 v149, v149, v153
	v_lshlrev_b32_e32 v152, 16, v110
	v_and_b32_e32 v153, 0xffff0000, v110
	v_add_f32_e32 v146, v146, v152
	v_add_f32_e32 v150, v150, v153
	v_lshlrev_b32_e32 v152, 16, v111
	v_and_b32_e32 v153, 0xffff0000, v111
	v_add_f32_e32 v147, v147, v152
	v_add_f32_e32 v151, v151, v153
	s_waitcnt vmcnt(4)
	v_lshlrev_b32_e32 v152, 16, v112
	v_and_b32_e32 v153, 0xffff0000, v112
	v_add_f32_e32 v144, v144, v152
	v_add_f32_e32 v148, v148, v153
	v_lshlrev_b32_e32 v152, 16, v113
	v_and_b32_e32 v153, 0xffff0000, v113
	v_add_f32_e32 v145, v145, v152
	v_add_f32_e32 v149, v149, v153
	v_lshlrev_b32_e32 v152, 16, v114
	v_and_b32_e32 v153, 0xffff0000, v114
	v_add_f32_e32 v146, v146, v152
	v_add_f32_e32 v150, v150, v153
	v_lshlrev_b32_e32 v152, 16, v115
	v_and_b32_e32 v153, 0xffff0000, v115
	v_add_f32_e32 v147, v147, v152
	v_add_f32_e32 v151, v151, v153
	v_lshlrev_b32_e32 v152, 16, v116
	v_and_b32_e32 v153, 0xffff0000, v116
	v_add_f32_e32 v144, v144, v152
	v_add_f32_e32 v148, v148, v153
	v_lshlrev_b32_e32 v152, 16, v117
	v_and_b32_e32 v153, 0xffff0000, v117
	v_add_f32_e32 v145, v145, v152
	v_add_f32_e32 v149, v149, v153
	v_lshlrev_b32_e32 v152, 16, v118
	v_and_b32_e32 v153, 0xffff0000, v118
	v_add_f32_e32 v146, v146, v152
	v_add_f32_e32 v150, v150, v153
	v_lshlrev_b32_e32 v152, 16, v119
	v_and_b32_e32 v153, 0xffff0000, v119
	v_add_f32_e32 v147, v147, v152
	v_add_f32_e32 v151, v151, v153
	v_lshlrev_b32_e32 v152, 16, v120
	v_and_b32_e32 v153, 0xffff0000, v120
	v_add_f32_e32 v144, v144, v152
	v_add_f32_e32 v148, v148, v153
	v_lshlrev_b32_e32 v152, 16, v121
	v_and_b32_e32 v153, 0xffff0000, v121
	v_add_f32_e32 v145, v145, v152
	v_add_f32_e32 v149, v149, v153
	v_lshlrev_b32_e32 v152, 16, v122
	v_and_b32_e32 v153, 0xffff0000, v122
	v_add_f32_e32 v146, v146, v152
	v_add_f32_e32 v150, v150, v153
	v_lshlrev_b32_e32 v152, 16, v123
	v_and_b32_e32 v153, 0xffff0000, v123
	v_add_f32_e32 v147, v147, v152
	v_add_f32_e32 v151, v151, v153
	v_lshlrev_b32_e32 v152, 16, v124
	v_and_b32_e32 v153, 0xffff0000, v124
	v_add_f32_e32 v144, v144, v152
	v_add_f32_e32 v148, v148, v153
	v_lshlrev_b32_e32 v152, 16, v125
	v_and_b32_e32 v153, 0xffff0000, v125
	v_add_f32_e32 v145, v145, v152
	v_add_f32_e32 v149, v149, v153
	v_lshlrev_b32_e32 v152, 16, v126
	v_and_b32_e32 v153, 0xffff0000, v126
	v_add_f32_e32 v146, v146, v152
	v_add_f32_e32 v150, v150, v153
	v_lshlrev_b32_e32 v152, 16, v127
	v_and_b32_e32 v153, 0xffff0000, v127
	v_add_f32_e32 v147, v147, v152
	v_add_f32_e32 v151, v151, v153
	s_waitcnt vmcnt(0)
	v_lshlrev_b32_e32 v152, 16, v128
	v_and_b32_e32 v153, 0xffff0000, v128
	v_add_f32_e32 v144, v144, v152
	v_add_f32_e32 v148, v148, v153
	v_lshlrev_b32_e32 v152, 16, v129
	v_and_b32_e32 v153, 0xffff0000, v129
	v_add_f32_e32 v145, v145, v152
	v_add_f32_e32 v149, v149, v153
	v_lshlrev_b32_e32 v152, 16, v130
	v_and_b32_e32 v153, 0xffff0000, v130
	v_add_f32_e32 v146, v146, v152
	v_add_f32_e32 v150, v150, v153
	v_lshlrev_b32_e32 v152, 16, v131
	v_and_b32_e32 v153, 0xffff0000, v131
	v_add_f32_e32 v147, v147, v152
	v_add_f32_e32 v151, v151, v153
	v_lshlrev_b32_e32 v152, 16, v132
	v_and_b32_e32 v153, 0xffff0000, v132
	v_add_f32_e32 v144, v144, v152
	v_add_f32_e32 v148, v148, v153
	v_lshlrev_b32_e32 v152, 16, v133
	v_and_b32_e32 v153, 0xffff0000, v133
	v_add_f32_e32 v145, v145, v152
	v_add_f32_e32 v149, v149, v153
	v_lshlrev_b32_e32 v152, 16, v134
	v_and_b32_e32 v153, 0xffff0000, v134
	v_add_f32_e32 v146, v146, v152
	v_add_f32_e32 v150, v150, v153
	v_lshlrev_b32_e32 v152, 16, v135
	v_and_b32_e32 v153, 0xffff0000, v135
	v_add_f32_e32 v147, v147, v152
	v_add_f32_e32 v151, v151, v153
	v_lshlrev_b32_e32 v152, 16, v136
	v_and_b32_e32 v153, 0xffff0000, v136
	v_add_f32_e32 v144, v144, v152
	v_add_f32_e32 v148, v148, v153
	v_lshlrev_b32_e32 v152, 16, v137
	v_and_b32_e32 v153, 0xffff0000, v137
	v_add_f32_e32 v145, v145, v152
	v_add_f32_e32 v149, v149, v153
	v_lshlrev_b32_e32 v152, 16, v138
	v_and_b32_e32 v153, 0xffff0000, v138
	v_add_f32_e32 v146, v146, v152
	v_add_f32_e32 v150, v150, v153
	v_lshlrev_b32_e32 v152, 16, v139
	v_and_b32_e32 v153, 0xffff0000, v139
	v_add_f32_e32 v147, v147, v152
	v_add_f32_e32 v151, v151, v153
	v_lshlrev_b32_e32 v152, 16, v140
	v_and_b32_e32 v153, 0xffff0000, v140
	v_add_f32_e32 v144, v144, v152
	v_add_f32_e32 v148, v148, v153
	v_lshlrev_b32_e32 v152, 16, v141
	v_and_b32_e32 v153, 0xffff0000, v141
	v_add_f32_e32 v145, v145, v152
	v_add_f32_e32 v149, v149, v153
	v_lshlrev_b32_e32 v152, 16, v142
	v_and_b32_e32 v153, 0xffff0000, v142
	v_add_f32_e32 v146, v146, v152
	v_add_f32_e32 v150, v150, v153
	v_lshlrev_b32_e32 v152, 16, v143
	v_and_b32_e32 v153, 0xffff0000, v143
	v_add_f32_e32 v147, v147, v152
	v_add_f32_e32 v151, v151, v153
	v_add_f32_e32 v144, v144, v145
	v_add_f32_e32 v146, v146, v147
	v_add_f32_e32 v148, v148, v149
	v_add_f32_e32 v150, v150, v151
	v_add_f32_e32 v144, v144, v146
	v_add_f32_e32 v148, v148, v150
	v_add_f32_e32 v0, v144, v148
	v_mul_f32_e32 v4, 0x3b800000, v0
	v_mov_b32_e32 v5, v4
	v_mov_b32_e32 v144, 0
	v_mov_b32_e32 v145, 0
	v_mov_b32_e32 v146, 0
	v_mov_b32_e32 v147, 0
	v_mov_b32_e32 v148, 0
	v_mov_b32_e32 v149, 0
	v_mov_b32_e32 v150, 0
	v_mov_b32_e32 v151, 0
	v_lshlrev_b32_e32 v152, 16, v16
	v_and_b32_e32 v153, 0xffff0000, v16
	v_sub_f32_e32 v152, v152, v4
	v_sub_f32_e32 v153, v153, v4
	v_fmac_f32_e32 v144, v152, v152
	v_fmac_f32_e32 v148, v153, v153
	v_lshlrev_b32_e32 v152, 16, v17
	v_and_b32_e32 v153, 0xffff0000, v17
	v_sub_f32_e32 v152, v152, v4
	v_sub_f32_e32 v153, v153, v4
	v_fmac_f32_e32 v145, v152, v152
	v_fmac_f32_e32 v149, v153, v153
	v_lshlrev_b32_e32 v152, 16, v18
	v_and_b32_e32 v153, 0xffff0000, v18
	v_sub_f32_e32 v152, v152, v4
	v_sub_f32_e32 v153, v153, v4
	v_fmac_f32_e32 v146, v152, v152
	v_fmac_f32_e32 v150, v153, v153
	v_lshlrev_b32_e32 v152, 16, v19
	v_and_b32_e32 v153, 0xffff0000, v19
	v_sub_f32_e32 v152, v152, v4
	v_sub_f32_e32 v153, v153, v4
	v_fmac_f32_e32 v147, v152, v152
	v_fmac_f32_e32 v151, v153, v153
	v_lshlrev_b32_e32 v152, 16, v20
	v_and_b32_e32 v153, 0xffff0000, v20
	v_sub_f32_e32 v152, v152, v4
	v_sub_f32_e32 v153, v153, v4
	v_fmac_f32_e32 v144, v152, v152
	v_fmac_f32_e32 v148, v153, v153
	v_lshlrev_b32_e32 v152, 16, v21
	v_and_b32_e32 v153, 0xffff0000, v21
	v_sub_f32_e32 v152, v152, v4
	v_sub_f32_e32 v153, v153, v4
	v_fmac_f32_e32 v145, v152, v152
	v_fmac_f32_e32 v149, v153, v153
	v_lshlrev_b32_e32 v152, 16, v22
	v_and_b32_e32 v153, 0xffff0000, v22
	v_sub_f32_e32 v152, v152, v4
	v_sub_f32_e32 v153, v153, v4
	v_fmac_f32_e32 v146, v152, v152
	v_fmac_f32_e32 v150, v153, v153
	v_lshlrev_b32_e32 v152, 16, v23
	v_and_b32_e32 v153, 0xffff0000, v23
	v_sub_f32_e32 v152, v152, v4
	v_sub_f32_e32 v153, v153, v4
	v_fmac_f32_e32 v147, v152, v152
	v_fmac_f32_e32 v151, v153, v153
	v_lshlrev_b32_e32 v152, 16, v24
	v_and_b32_e32 v153, 0xffff0000, v24
	v_sub_f32_e32 v152, v152, v4
	v_sub_f32_e32 v153, v153, v4
	v_fmac_f32_e32 v144, v152, v152
	v_fmac_f32_e32 v148, v153, v153
	v_lshlrev_b32_e32 v152, 16, v25
	v_and_b32_e32 v153, 0xffff0000, v25
	v_sub_f32_e32 v152, v152, v4
	v_sub_f32_e32 v153, v153, v4
	v_fmac_f32_e32 v145, v152, v152
	v_fmac_f32_e32 v149, v153, v153
	v_lshlrev_b32_e32 v152, 16, v26
	v_and_b32_e32 v153, 0xffff0000, v26
	v_sub_f32_e32 v152, v152, v4
	v_sub_f32_e32 v153, v153, v4
	v_fmac_f32_e32 v146, v152, v152
	v_fmac_f32_e32 v150, v153, v153
	v_lshlrev_b32_e32 v152, 16, v27
	v_and_b32_e32 v153, 0xffff0000, v27
	v_sub_f32_e32 v152, v152, v4
	v_sub_f32_e32 v153, v153, v4
	v_fmac_f32_e32 v147, v152, v152
	v_fmac_f32_e32 v151, v153, v153
	v_lshlrev_b32_e32 v152, 16, v28
	v_and_b32_e32 v153, 0xffff0000, v28
	v_sub_f32_e32 v152, v152, v4
	v_sub_f32_e32 v153, v153, v4
	v_fmac_f32_e32 v144, v152, v152
	v_fmac_f32_e32 v148, v153, v153
	v_lshlrev_b32_e32 v152, 16, v29
	v_and_b32_e32 v153, 0xffff0000, v29
	v_sub_f32_e32 v152, v152, v4
	v_sub_f32_e32 v153, v153, v4
	v_fmac_f32_e32 v145, v152, v152
	v_fmac_f32_e32 v149, v153, v153
	v_lshlrev_b32_e32 v152, 16, v30
	v_and_b32_e32 v153, 0xffff0000, v30
	v_sub_f32_e32 v152, v152, v4
	v_sub_f32_e32 v153, v153, v4
	v_fmac_f32_e32 v146, v152, v152
	v_fmac_f32_e32 v150, v153, v153
	v_lshlrev_b32_e32 v152, 16, v31
	v_and_b32_e32 v153, 0xffff0000, v31
	v_sub_f32_e32 v152, v152, v4
	v_sub_f32_e32 v153, v153, v4
	v_fmac_f32_e32 v147, v152, v152
	v_fmac_f32_e32 v151, v153, v153
	v_lshlrev_b32_e32 v152, 16, v32
	v_and_b32_e32 v153, 0xffff0000, v32
	v_sub_f32_e32 v152, v152, v4
	v_sub_f32_e32 v153, v153, v4
	v_fmac_f32_e32 v144, v152, v152
	v_fmac_f32_e32 v148, v153, v153
	v_lshlrev_b32_e32 v152, 16, v33
	v_and_b32_e32 v153, 0xffff0000, v33
	v_sub_f32_e32 v152, v152, v4
	v_sub_f32_e32 v153, v153, v4
	v_fmac_f32_e32 v145, v152, v152
	v_fmac_f32_e32 v149, v153, v153
	v_lshlrev_b32_e32 v152, 16, v34
	v_and_b32_e32 v153, 0xffff0000, v34
	v_sub_f32_e32 v152, v152, v4
	v_sub_f32_e32 v153, v153, v4
	v_fmac_f32_e32 v146, v152, v152
	v_fmac_f32_e32 v150, v153, v153
	v_lshlrev_b32_e32 v152, 16, v35
	v_and_b32_e32 v153, 0xffff0000, v35
	v_sub_f32_e32 v152, v152, v4
	v_sub_f32_e32 v153, v153, v4
	v_fmac_f32_e32 v147, v152, v152
	v_fmac_f32_e32 v151, v153, v153
	v_lshlrev_b32_e32 v152, 16, v36
	v_and_b32_e32 v153, 0xffff0000, v36
	v_sub_f32_e32 v152, v152, v4
	v_sub_f32_e32 v153, v153, v4
	v_fmac_f32_e32 v144, v152, v152
	v_fmac_f32_e32 v148, v153, v153
	v_lshlrev_b32_e32 v152, 16, v37
	v_and_b32_e32 v153, 0xffff0000, v37
	v_sub_f32_e32 v152, v152, v4
	v_sub_f32_e32 v153, v153, v4
	v_fmac_f32_e32 v145, v152, v152
	v_fmac_f32_e32 v149, v153, v153
	v_lshlrev_b32_e32 v152, 16, v38
	v_and_b32_e32 v153, 0xffff0000, v38
	v_sub_f32_e32 v152, v152, v4
	v_sub_f32_e32 v153, v153, v4
	v_fmac_f32_e32 v146, v152, v152
	v_fmac_f32_e32 v150, v153, v153
	v_lshlrev_b32_e32 v152, 16, v39
	v_and_b32_e32 v153, 0xffff0000, v39
	v_sub_f32_e32 v152, v152, v4
	v_sub_f32_e32 v153, v153, v4
	v_fmac_f32_e32 v147, v152, v152
	v_fmac_f32_e32 v151, v153, v153
	v_lshlrev_b32_e32 v152, 16, v40
	v_and_b32_e32 v153, 0xffff0000, v40
	v_sub_f32_e32 v152, v152, v4
	v_sub_f32_e32 v153, v153, v4
	v_fmac_f32_e32 v144, v152, v152
	v_fmac_f32_e32 v148, v153, v153
	v_lshlrev_b32_e32 v152, 16, v41
	v_and_b32_e32 v153, 0xffff0000, v41
	v_sub_f32_e32 v152, v152, v4
	v_sub_f32_e32 v153, v153, v4
	v_fmac_f32_e32 v145, v152, v152
	v_fmac_f32_e32 v149, v153, v153
	v_lshlrev_b32_e32 v152, 16, v42
	v_and_b32_e32 v153, 0xffff0000, v42
	v_sub_f32_e32 v152, v152, v4
	v_sub_f32_e32 v153, v153, v4
	v_fmac_f32_e32 v146, v152, v152
	v_fmac_f32_e32 v150, v153, v153
	v_lshlrev_b32_e32 v152, 16, v43
	v_and_b32_e32 v153, 0xffff0000, v43
	v_sub_f32_e32 v152, v152, v4
	v_sub_f32_e32 v153, v153, v4
	v_fmac_f32_e32 v147, v152, v152
	v_fmac_f32_e32 v151, v153, v153
	v_lshlrev_b32_e32 v152, 16, v44
	v_and_b32_e32 v153, 0xffff0000, v44
	v_sub_f32_e32 v152, v152, v4
	v_sub_f32_e32 v153, v153, v4
	v_fmac_f32_e32 v144, v152, v152
	v_fmac_f32_e32 v148, v153, v153
	v_lshlrev_b32_e32 v152, 16, v45
	v_and_b32_e32 v153, 0xffff0000, v45
	v_sub_f32_e32 v152, v152, v4
	v_sub_f32_e32 v153, v153, v4
	v_fmac_f32_e32 v145, v152, v152
	v_fmac_f32_e32 v149, v153, v153
	v_lshlrev_b32_e32 v152, 16, v46
	v_and_b32_e32 v153, 0xffff0000, v46
	v_sub_f32_e32 v152, v152, v4
	v_sub_f32_e32 v153, v153, v4
	v_fmac_f32_e32 v146, v152, v152
	v_fmac_f32_e32 v150, v153, v153
	v_lshlrev_b32_e32 v152, 16, v47
	v_and_b32_e32 v153, 0xffff0000, v47
	v_sub_f32_e32 v152, v152, v4
	v_sub_f32_e32 v153, v153, v4
	v_fmac_f32_e32 v147, v152, v152
	v_fmac_f32_e32 v151, v153, v153
	v_lshlrev_b32_e32 v152, 16, v48
	v_and_b32_e32 v153, 0xffff0000, v48
	v_sub_f32_e32 v152, v152, v4
	v_sub_f32_e32 v153, v153, v4
	v_fmac_f32_e32 v144, v152, v152
	v_fmac_f32_e32 v148, v153, v153
	v_lshlrev_b32_e32 v152, 16, v49
	v_and_b32_e32 v153, 0xffff0000, v49
	v_sub_f32_e32 v152, v152, v4
	v_sub_f32_e32 v153, v153, v4
	v_fmac_f32_e32 v145, v152, v152
	v_fmac_f32_e32 v149, v153, v153
	v_lshlrev_b32_e32 v152, 16, v50
	v_and_b32_e32 v153, 0xffff0000, v50
	v_sub_f32_e32 v152, v152, v4
	v_sub_f32_e32 v153, v153, v4
	v_fmac_f32_e32 v146, v152, v152
	v_fmac_f32_e32 v150, v153, v153
	v_lshlrev_b32_e32 v152, 16, v51
	v_and_b32_e32 v153, 0xffff0000, v51
	v_sub_f32_e32 v152, v152, v4
	v_sub_f32_e32 v153, v153, v4
	v_fmac_f32_e32 v147, v152, v152
	v_fmac_f32_e32 v151, v153, v153
	v_lshlrev_b32_e32 v152, 16, v52
	v_and_b32_e32 v153, 0xffff0000, v52
	v_sub_f32_e32 v152, v152, v4
	v_sub_f32_e32 v153, v153, v4
	v_fmac_f32_e32 v144, v152, v152
	v_fmac_f32_e32 v148, v153, v153
	v_lshlrev_b32_e32 v152, 16, v53
	v_and_b32_e32 v153, 0xffff0000, v53
	v_sub_f32_e32 v152, v152, v4
	v_sub_f32_e32 v153, v153, v4
	v_fmac_f32_e32 v145, v152, v152
	v_fmac_f32_e32 v149, v153, v153
	v_lshlrev_b32_e32 v152, 16, v54
	v_and_b32_e32 v153, 0xffff0000, v54
	v_sub_f32_e32 v152, v152, v4
	v_sub_f32_e32 v153, v153, v4
	v_fmac_f32_e32 v146, v152, v152
	v_fmac_f32_e32 v150, v153, v153
	v_lshlrev_b32_e32 v152, 16, v55
	v_and_b32_e32 v153, 0xffff0000, v55
	v_sub_f32_e32 v152, v152, v4
	v_sub_f32_e32 v153, v153, v4
	v_fmac_f32_e32 v147, v152, v152
	v_fmac_f32_e32 v151, v153, v153
	v_lshlrev_b32_e32 v152, 16, v56
	v_and_b32_e32 v153, 0xffff0000, v56
	v_sub_f32_e32 v152, v152, v4
	v_sub_f32_e32 v153, v153, v4
	v_fmac_f32_e32 v144, v152, v152
	v_fmac_f32_e32 v148, v153, v153
	v_lshlrev_b32_e32 v152, 16, v57
	v_and_b32_e32 v153, 0xffff0000, v57
	v_sub_f32_e32 v152, v152, v4
	v_sub_f32_e32 v153, v153, v4
	v_fmac_f32_e32 v145, v152, v152
	v_fmac_f32_e32 v149, v153, v153
	v_lshlrev_b32_e32 v152, 16, v58
	v_and_b32_e32 v153, 0xffff0000, v58
	v_sub_f32_e32 v152, v152, v4
	v_sub_f32_e32 v153, v153, v4
	v_fmac_f32_e32 v146, v152, v152
	v_fmac_f32_e32 v150, v153, v153
	v_lshlrev_b32_e32 v152, 16, v59
	v_and_b32_e32 v153, 0xffff0000, v59
	v_sub_f32_e32 v152, v152, v4
	v_sub_f32_e32 v153, v153, v4
	v_fmac_f32_e32 v147, v152, v152
	v_fmac_f32_e32 v151, v153, v153
	v_lshlrev_b32_e32 v152, 16, v60
	v_and_b32_e32 v153, 0xffff0000, v60
	v_sub_f32_e32 v152, v152, v4
	v_sub_f32_e32 v153, v153, v4
	v_fmac_f32_e32 v144, v152, v152
	v_fmac_f32_e32 v148, v153, v153
	v_lshlrev_b32_e32 v152, 16, v61
	v_and_b32_e32 v153, 0xffff0000, v61
	v_sub_f32_e32 v152, v152, v4
	v_sub_f32_e32 v153, v153, v4
	v_fmac_f32_e32 v145, v152, v152
	v_fmac_f32_e32 v149, v153, v153
	v_lshlrev_b32_e32 v152, 16, v62
	v_and_b32_e32 v153, 0xffff0000, v62
	v_sub_f32_e32 v152, v152, v4
	v_sub_f32_e32 v153, v153, v4
	v_fmac_f32_e32 v146, v152, v152
	v_fmac_f32_e32 v150, v153, v153
	v_lshlrev_b32_e32 v152, 16, v63
	v_and_b32_e32 v153, 0xffff0000, v63
	v_sub_f32_e32 v152, v152, v4
	v_sub_f32_e32 v153, v153, v4
	v_fmac_f32_e32 v147, v152, v152
	v_fmac_f32_e32 v151, v153, v153
	v_lshlrev_b32_e32 v152, 16, v64
	v_and_b32_e32 v153, 0xffff0000, v64
	v_sub_f32_e32 v152, v152, v4
	v_sub_f32_e32 v153, v153, v4
	v_fmac_f32_e32 v144, v152, v152
	v_fmac_f32_e32 v148, v153, v153
	v_lshlrev_b32_e32 v152, 16, v65
	v_and_b32_e32 v153, 0xffff0000, v65
	v_sub_f32_e32 v152, v152, v4
	v_sub_f32_e32 v153, v153, v4
	v_fmac_f32_e32 v145, v152, v152
	v_fmac_f32_e32 v149, v153, v153
	v_lshlrev_b32_e32 v152, 16, v66
	v_and_b32_e32 v153, 0xffff0000, v66
	v_sub_f32_e32 v152, v152, v4
	v_sub_f32_e32 v153, v153, v4
	v_fmac_f32_e32 v146, v152, v152
	v_fmac_f32_e32 v150, v153, v153
	v_lshlrev_b32_e32 v152, 16, v67
	v_and_b32_e32 v153, 0xffff0000, v67
	v_sub_f32_e32 v152, v152, v4
	v_sub_f32_e32 v153, v153, v4
	v_fmac_f32_e32 v147, v152, v152
	v_fmac_f32_e32 v151, v153, v153
	v_lshlrev_b32_e32 v152, 16, v68
	v_and_b32_e32 v153, 0xffff0000, v68
	v_sub_f32_e32 v152, v152, v4
	v_sub_f32_e32 v153, v153, v4
	v_fmac_f32_e32 v144, v152, v152
	v_fmac_f32_e32 v148, v153, v153
	v_lshlrev_b32_e32 v152, 16, v69
	v_and_b32_e32 v153, 0xffff0000, v69
	v_sub_f32_e32 v152, v152, v4
	v_sub_f32_e32 v153, v153, v4
	v_fmac_f32_e32 v145, v152, v152
	v_fmac_f32_e32 v149, v153, v153
	v_lshlrev_b32_e32 v152, 16, v70
	v_and_b32_e32 v153, 0xffff0000, v70
	v_sub_f32_e32 v152, v152, v4
	v_sub_f32_e32 v153, v153, v4
	v_fmac_f32_e32 v146, v152, v152
	v_fmac_f32_e32 v150, v153, v153
	v_lshlrev_b32_e32 v152, 16, v71
	v_and_b32_e32 v153, 0xffff0000, v71
	v_sub_f32_e32 v152, v152, v4
	v_sub_f32_e32 v153, v153, v4
	v_fmac_f32_e32 v147, v152, v152
	v_fmac_f32_e32 v151, v153, v153
	v_lshlrev_b32_e32 v152, 16, v72
	v_and_b32_e32 v153, 0xffff0000, v72
	v_sub_f32_e32 v152, v152, v4
	v_sub_f32_e32 v153, v153, v4
	v_fmac_f32_e32 v144, v152, v152
	v_fmac_f32_e32 v148, v153, v153
	v_lshlrev_b32_e32 v152, 16, v73
	v_and_b32_e32 v153, 0xffff0000, v73
	v_sub_f32_e32 v152, v152, v4
	v_sub_f32_e32 v153, v153, v4
	v_fmac_f32_e32 v145, v152, v152
	v_fmac_f32_e32 v149, v153, v153
	v_lshlrev_b32_e32 v152, 16, v74
	v_and_b32_e32 v153, 0xffff0000, v74
	v_sub_f32_e32 v152, v152, v4
	v_sub_f32_e32 v153, v153, v4
	v_fmac_f32_e32 v146, v152, v152
	v_fmac_f32_e32 v150, v153, v153
	v_lshlrev_b32_e32 v152, 16, v75
	v_and_b32_e32 v153, 0xffff0000, v75
	v_sub_f32_e32 v152, v152, v4
	v_sub_f32_e32 v153, v153, v4
	v_fmac_f32_e32 v147, v152, v152
	v_fmac_f32_e32 v151, v153, v153
	v_lshlrev_b32_e32 v152, 16, v76
	v_and_b32_e32 v153, 0xffff0000, v76
	v_sub_f32_e32 v152, v152, v4
	v_sub_f32_e32 v153, v153, v4
	v_fmac_f32_e32 v144, v152, v152
	v_fmac_f32_e32 v148, v153, v153
	v_lshlrev_b32_e32 v152, 16, v77
	v_and_b32_e32 v153, 0xffff0000, v77
	v_sub_f32_e32 v152, v152, v4
	v_sub_f32_e32 v153, v153, v4
	v_fmac_f32_e32 v145, v152, v152
	v_fmac_f32_e32 v149, v153, v153
	v_lshlrev_b32_e32 v152, 16, v78
	v_and_b32_e32 v153, 0xffff0000, v78
	v_sub_f32_e32 v152, v152, v4
	v_sub_f32_e32 v153, v153, v4
	v_fmac_f32_e32 v146, v152, v152
	v_fmac_f32_e32 v150, v153, v153
	v_lshlrev_b32_e32 v152, 16, v79
	v_and_b32_e32 v153, 0xffff0000, v79
	v_sub_f32_e32 v152, v152, v4
	v_sub_f32_e32 v153, v153, v4
	v_fmac_f32_e32 v147, v152, v152
	v_fmac_f32_e32 v151, v153, v153
	v_lshlrev_b32_e32 v152, 16, v80
	v_and_b32_e32 v153, 0xffff0000, v80
	v_sub_f32_e32 v152, v152, v4
	v_sub_f32_e32 v153, v153, v4
	v_fmac_f32_e32 v144, v152, v152
	v_fmac_f32_e32 v148, v153, v153
	v_lshlrev_b32_e32 v152, 16, v81
	v_and_b32_e32 v153, 0xffff0000, v81
	v_sub_f32_e32 v152, v152, v4
	v_sub_f32_e32 v153, v153, v4
	v_fmac_f32_e32 v145, v152, v152
	v_fmac_f32_e32 v149, v153, v153
	v_lshlrev_b32_e32 v152, 16, v82
	v_and_b32_e32 v153, 0xffff0000, v82
	v_sub_f32_e32 v152, v152, v4
	v_sub_f32_e32 v153, v153, v4
	v_fmac_f32_e32 v146, v152, v152
	v_fmac_f32_e32 v150, v153, v153
	v_lshlrev_b32_e32 v152, 16, v83
	v_and_b32_e32 v153, 0xffff0000, v83
	v_sub_f32_e32 v152, v152, v4
	v_sub_f32_e32 v153, v153, v4
	v_fmac_f32_e32 v147, v152, v152
	v_fmac_f32_e32 v151, v153, v153
	v_lshlrev_b32_e32 v152, 16, v84
	v_and_b32_e32 v153, 0xffff0000, v84
	v_sub_f32_e32 v152, v152, v4
	v_sub_f32_e32 v153, v153, v4
	v_fmac_f32_e32 v144, v152, v152
	v_fmac_f32_e32 v148, v153, v153
	v_lshlrev_b32_e32 v152, 16, v85
	v_and_b32_e32 v153, 0xffff0000, v85
	v_sub_f32_e32 v152, v152, v4
	v_sub_f32_e32 v153, v153, v4
	v_fmac_f32_e32 v145, v152, v152
	v_fmac_f32_e32 v149, v153, v153
	v_lshlrev_b32_e32 v152, 16, v86
	v_and_b32_e32 v153, 0xffff0000, v86
	v_sub_f32_e32 v152, v152, v4
	v_sub_f32_e32 v153, v153, v4
	v_fmac_f32_e32 v146, v152, v152
	v_fmac_f32_e32 v150, v153, v153
	v_lshlrev_b32_e32 v152, 16, v87
	v_and_b32_e32 v153, 0xffff0000, v87
	v_sub_f32_e32 v152, v152, v4
	v_sub_f32_e32 v153, v153, v4
	v_fmac_f32_e32 v147, v152, v152
	v_fmac_f32_e32 v151, v153, v153
	v_lshlrev_b32_e32 v152, 16, v88
	v_and_b32_e32 v153, 0xffff0000, v88
	v_sub_f32_e32 v152, v152, v4
	v_sub_f32_e32 v153, v153, v4
	v_fmac_f32_e32 v144, v152, v152
	v_fmac_f32_e32 v148, v153, v153
	v_lshlrev_b32_e32 v152, 16, v89
	v_and_b32_e32 v153, 0xffff0000, v89
	v_sub_f32_e32 v152, v152, v4
	v_sub_f32_e32 v153, v153, v4
	v_fmac_f32_e32 v145, v152, v152
	v_fmac_f32_e32 v149, v153, v153
	v_lshlrev_b32_e32 v152, 16, v90
	v_and_b32_e32 v153, 0xffff0000, v90
	v_sub_f32_e32 v152, v152, v4
	v_sub_f32_e32 v153, v153, v4
	v_fmac_f32_e32 v146, v152, v152
	v_fmac_f32_e32 v150, v153, v153
	v_lshlrev_b32_e32 v152, 16, v91
	v_and_b32_e32 v153, 0xffff0000, v91
	v_sub_f32_e32 v152, v152, v4
	v_sub_f32_e32 v153, v153, v4
	v_fmac_f32_e32 v147, v152, v152
	v_fmac_f32_e32 v151, v153, v153
	v_lshlrev_b32_e32 v152, 16, v92
	v_and_b32_e32 v153, 0xffff0000, v92
	v_sub_f32_e32 v152, v152, v4
	v_sub_f32_e32 v153, v153, v4
	v_fmac_f32_e32 v144, v152, v152
	v_fmac_f32_e32 v148, v153, v153
	v_lshlrev_b32_e32 v152, 16, v93
	v_and_b32_e32 v153, 0xffff0000, v93
	v_sub_f32_e32 v152, v152, v4
	v_sub_f32_e32 v153, v153, v4
	v_fmac_f32_e32 v145, v152, v152
	v_fmac_f32_e32 v149, v153, v153
	v_lshlrev_b32_e32 v152, 16, v94
	v_and_b32_e32 v153, 0xffff0000, v94
	v_sub_f32_e32 v152, v152, v4
	v_sub_f32_e32 v153, v153, v4
	v_fmac_f32_e32 v146, v152, v152
	v_fmac_f32_e32 v150, v153, v153
	v_lshlrev_b32_e32 v152, 16, v95
	v_and_b32_e32 v153, 0xffff0000, v95
	v_sub_f32_e32 v152, v152, v4
	v_sub_f32_e32 v153, v153, v4
	v_fmac_f32_e32 v147, v152, v152
	v_fmac_f32_e32 v151, v153, v153
	v_lshlrev_b32_e32 v152, 16, v96
	v_and_b32_e32 v153, 0xffff0000, v96
	v_sub_f32_e32 v152, v152, v4
	v_sub_f32_e32 v153, v153, v4
	v_fmac_f32_e32 v144, v152, v152
	v_fmac_f32_e32 v148, v153, v153
	v_lshlrev_b32_e32 v152, 16, v97
	v_and_b32_e32 v153, 0xffff0000, v97
	v_sub_f32_e32 v152, v152, v4
	v_sub_f32_e32 v153, v153, v4
	v_fmac_f32_e32 v145, v152, v152
	v_fmac_f32_e32 v149, v153, v153
	v_lshlrev_b32_e32 v152, 16, v98
	v_and_b32_e32 v153, 0xffff0000, v98
	v_sub_f32_e32 v152, v152, v4
	v_sub_f32_e32 v153, v153, v4
	v_fmac_f32_e32 v146, v152, v152
	v_fmac_f32_e32 v150, v153, v153
	v_lshlrev_b32_e32 v152, 16, v99
	v_and_b32_e32 v153, 0xffff0000, v99
	v_sub_f32_e32 v152, v152, v4
	v_sub_f32_e32 v153, v153, v4
	v_fmac_f32_e32 v147, v152, v152
	v_fmac_f32_e32 v151, v153, v153
	v_lshlrev_b32_e32 v152, 16, v100
	v_and_b32_e32 v153, 0xffff0000, v100
	v_sub_f32_e32 v152, v152, v4
	v_sub_f32_e32 v153, v153, v4
	v_fmac_f32_e32 v144, v152, v152
	v_fmac_f32_e32 v148, v153, v153
	v_lshlrev_b32_e32 v152, 16, v101
	v_and_b32_e32 v153, 0xffff0000, v101
	v_sub_f32_e32 v152, v152, v4
	v_sub_f32_e32 v153, v153, v4
	v_fmac_f32_e32 v145, v152, v152
	v_fmac_f32_e32 v149, v153, v153
	v_lshlrev_b32_e32 v152, 16, v102
	v_and_b32_e32 v153, 0xffff0000, v102
	v_sub_f32_e32 v152, v152, v4
	v_sub_f32_e32 v153, v153, v4
	v_fmac_f32_e32 v146, v152, v152
	v_fmac_f32_e32 v150, v153, v153
	v_lshlrev_b32_e32 v152, 16, v103
	v_and_b32_e32 v153, 0xffff0000, v103
	v_sub_f32_e32 v152, v152, v4
	v_sub_f32_e32 v153, v153, v4
	v_fmac_f32_e32 v147, v152, v152
	v_fmac_f32_e32 v151, v153, v153
	v_lshlrev_b32_e32 v152, 16, v104
	v_and_b32_e32 v153, 0xffff0000, v104
	v_sub_f32_e32 v152, v152, v4
	v_sub_f32_e32 v153, v153, v4
	v_fmac_f32_e32 v144, v152, v152
	v_fmac_f32_e32 v148, v153, v153
	v_lshlrev_b32_e32 v152, 16, v105
	v_and_b32_e32 v153, 0xffff0000, v105
	v_sub_f32_e32 v152, v152, v4
	v_sub_f32_e32 v153, v153, v4
	v_fmac_f32_e32 v145, v152, v152
	v_fmac_f32_e32 v149, v153, v153
	v_lshlrev_b32_e32 v152, 16, v106
	v_and_b32_e32 v153, 0xffff0000, v106
	v_sub_f32_e32 v152, v152, v4
	v_sub_f32_e32 v153, v153, v4
	v_fmac_f32_e32 v146, v152, v152
	v_fmac_f32_e32 v150, v153, v153
	v_lshlrev_b32_e32 v152, 16, v107
	v_and_b32_e32 v153, 0xffff0000, v107
	v_sub_f32_e32 v152, v152, v4
	v_sub_f32_e32 v153, v153, v4
	v_fmac_f32_e32 v147, v152, v152
	v_fmac_f32_e32 v151, v153, v153
	v_lshlrev_b32_e32 v152, 16, v108
	v_and_b32_e32 v153, 0xffff0000, v108
	v_sub_f32_e32 v152, v152, v4
	v_sub_f32_e32 v153, v153, v4
	v_fmac_f32_e32 v144, v152, v152
	v_fmac_f32_e32 v148, v153, v153
	v_lshlrev_b32_e32 v152, 16, v109
	v_and_b32_e32 v153, 0xffff0000, v109
	v_sub_f32_e32 v152, v152, v4
	v_sub_f32_e32 v153, v153, v4
	v_fmac_f32_e32 v145, v152, v152
	v_fmac_f32_e32 v149, v153, v153
	v_lshlrev_b32_e32 v152, 16, v110
	v_and_b32_e32 v153, 0xffff0000, v110
	v_sub_f32_e32 v152, v152, v4
	v_sub_f32_e32 v153, v153, v4
	v_fmac_f32_e32 v146, v152, v152
	v_fmac_f32_e32 v150, v153, v153
	v_lshlrev_b32_e32 v152, 16, v111
	v_and_b32_e32 v153, 0xffff0000, v111
	v_sub_f32_e32 v152, v152, v4
	v_sub_f32_e32 v153, v153, v4
	v_fmac_f32_e32 v147, v152, v152
	v_fmac_f32_e32 v151, v153, v153
	v_lshlrev_b32_e32 v152, 16, v112
	v_and_b32_e32 v153, 0xffff0000, v112
	v_sub_f32_e32 v152, v152, v4
	v_sub_f32_e32 v153, v153, v4
	v_fmac_f32_e32 v144, v152, v152
	v_fmac_f32_e32 v148, v153, v153
	v_lshlrev_b32_e32 v152, 16, v113
	v_and_b32_e32 v153, 0xffff0000, v113
	v_sub_f32_e32 v152, v152, v4
	v_sub_f32_e32 v153, v153, v4
	v_fmac_f32_e32 v145, v152, v152
	v_fmac_f32_e32 v149, v153, v153
	v_lshlrev_b32_e32 v152, 16, v114
	v_and_b32_e32 v153, 0xffff0000, v114
	v_sub_f32_e32 v152, v152, v4
	v_sub_f32_e32 v153, v153, v4
	v_fmac_f32_e32 v146, v152, v152
	v_fmac_f32_e32 v150, v153, v153
	v_lshlrev_b32_e32 v152, 16, v115
	v_and_b32_e32 v153, 0xffff0000, v115
	v_sub_f32_e32 v152, v152, v4
	v_sub_f32_e32 v153, v153, v4
	v_fmac_f32_e32 v147, v152, v152
	v_fmac_f32_e32 v151, v153, v153
	v_lshlrev_b32_e32 v152, 16, v116
	v_and_b32_e32 v153, 0xffff0000, v116
	v_sub_f32_e32 v152, v152, v4
	v_sub_f32_e32 v153, v153, v4
	v_fmac_f32_e32 v144, v152, v152
	v_fmac_f32_e32 v148, v153, v153
	v_lshlrev_b32_e32 v152, 16, v117
	v_and_b32_e32 v153, 0xffff0000, v117
	v_sub_f32_e32 v152, v152, v4
	v_sub_f32_e32 v153, v153, v4
	v_fmac_f32_e32 v145, v152, v152
	v_fmac_f32_e32 v149, v153, v153
	v_lshlrev_b32_e32 v152, 16, v118
	v_and_b32_e32 v153, 0xffff0000, v118
	v_sub_f32_e32 v152, v152, v4
	v_sub_f32_e32 v153, v153, v4
	v_fmac_f32_e32 v146, v152, v152
	v_fmac_f32_e32 v150, v153, v153
	v_lshlrev_b32_e32 v152, 16, v119
	v_and_b32_e32 v153, 0xffff0000, v119
	v_sub_f32_e32 v152, v152, v4
	v_sub_f32_e32 v153, v153, v4
	v_fmac_f32_e32 v147, v152, v152
	v_fmac_f32_e32 v151, v153, v153
	v_lshlrev_b32_e32 v152, 16, v120
	v_and_b32_e32 v153, 0xffff0000, v120
	v_sub_f32_e32 v152, v152, v4
	v_sub_f32_e32 v153, v153, v4
	v_fmac_f32_e32 v144, v152, v152
	v_fmac_f32_e32 v148, v153, v153
	v_lshlrev_b32_e32 v152, 16, v121
	v_and_b32_e32 v153, 0xffff0000, v121
	v_sub_f32_e32 v152, v152, v4
	v_sub_f32_e32 v153, v153, v4
	v_fmac_f32_e32 v145, v152, v152
	v_fmac_f32_e32 v149, v153, v153
	v_lshlrev_b32_e32 v152, 16, v122
	v_and_b32_e32 v153, 0xffff0000, v122
	v_sub_f32_e32 v152, v152, v4
	v_sub_f32_e32 v153, v153, v4
	v_fmac_f32_e32 v146, v152, v152
	v_fmac_f32_e32 v150, v153, v153
	v_lshlrev_b32_e32 v152, 16, v123
	v_and_b32_e32 v153, 0xffff0000, v123
	v_sub_f32_e32 v152, v152, v4
	v_sub_f32_e32 v153, v153, v4
	v_fmac_f32_e32 v147, v152, v152
	v_fmac_f32_e32 v151, v153, v153
	v_lshlrev_b32_e32 v152, 16, v124
	v_and_b32_e32 v153, 0xffff0000, v124
	v_sub_f32_e32 v152, v152, v4
	v_sub_f32_e32 v153, v153, v4
	v_fmac_f32_e32 v144, v152, v152
	v_fmac_f32_e32 v148, v153, v153
	v_lshlrev_b32_e32 v152, 16, v125
	v_and_b32_e32 v153, 0xffff0000, v125
	v_sub_f32_e32 v152, v152, v4
	v_sub_f32_e32 v153, v153, v4
	v_fmac_f32_e32 v145, v152, v152
	v_fmac_f32_e32 v149, v153, v153
	v_lshlrev_b32_e32 v152, 16, v126
	v_and_b32_e32 v153, 0xffff0000, v126
	v_sub_f32_e32 v152, v152, v4
	v_sub_f32_e32 v153, v153, v4
	v_fmac_f32_e32 v146, v152, v152
	v_fmac_f32_e32 v150, v153, v153
	v_lshlrev_b32_e32 v152, 16, v127
	v_and_b32_e32 v153, 0xffff0000, v127
	v_sub_f32_e32 v152, v152, v4
	v_sub_f32_e32 v153, v153, v4
	v_fmac_f32_e32 v147, v152, v152
	v_fmac_f32_e32 v151, v153, v153
	v_lshlrev_b32_e32 v152, 16, v128
	v_and_b32_e32 v153, 0xffff0000, v128
	v_sub_f32_e32 v152, v152, v4
	v_sub_f32_e32 v153, v153, v4
	v_fmac_f32_e32 v144, v152, v152
	v_fmac_f32_e32 v148, v153, v153
	v_lshlrev_b32_e32 v152, 16, v129
	v_and_b32_e32 v153, 0xffff0000, v129
	v_sub_f32_e32 v152, v152, v4
	v_sub_f32_e32 v153, v153, v4
	v_fmac_f32_e32 v145, v152, v152
	v_fmac_f32_e32 v149, v153, v153
	v_lshlrev_b32_e32 v152, 16, v130
	v_and_b32_e32 v153, 0xffff0000, v130
	v_sub_f32_e32 v152, v152, v4
	v_sub_f32_e32 v153, v153, v4
	v_fmac_f32_e32 v146, v152, v152
	v_fmac_f32_e32 v150, v153, v153
	v_lshlrev_b32_e32 v152, 16, v131
	v_and_b32_e32 v153, 0xffff0000, v131
	v_sub_f32_e32 v152, v152, v4
	v_sub_f32_e32 v153, v153, v4
	v_fmac_f32_e32 v147, v152, v152
	v_fmac_f32_e32 v151, v153, v153
	v_lshlrev_b32_e32 v152, 16, v132
	v_and_b32_e32 v153, 0xffff0000, v132
	v_sub_f32_e32 v152, v152, v4
	v_sub_f32_e32 v153, v153, v4
	v_fmac_f32_e32 v144, v152, v152
	v_fmac_f32_e32 v148, v153, v153
	v_lshlrev_b32_e32 v152, 16, v133
	v_and_b32_e32 v153, 0xffff0000, v133
	v_sub_f32_e32 v152, v152, v4
	v_sub_f32_e32 v153, v153, v4
	v_fmac_f32_e32 v145, v152, v152
	v_fmac_f32_e32 v149, v153, v153
	v_lshlrev_b32_e32 v152, 16, v134
	v_and_b32_e32 v153, 0xffff0000, v134
	v_sub_f32_e32 v152, v152, v4
	v_sub_f32_e32 v153, v153, v4
	v_fmac_f32_e32 v146, v152, v152
	v_fmac_f32_e32 v150, v153, v153
	v_lshlrev_b32_e32 v152, 16, v135
	v_and_b32_e32 v153, 0xffff0000, v135
	v_sub_f32_e32 v152, v152, v4
	v_sub_f32_e32 v153, v153, v4
	v_fmac_f32_e32 v147, v152, v152
	v_fmac_f32_e32 v151, v153, v153
	v_lshlrev_b32_e32 v152, 16, v136
	v_and_b32_e32 v153, 0xffff0000, v136
	v_sub_f32_e32 v152, v152, v4
	v_sub_f32_e32 v153, v153, v4
	v_fmac_f32_e32 v144, v152, v152
	v_fmac_f32_e32 v148, v153, v153
	v_lshlrev_b32_e32 v152, 16, v137
	v_and_b32_e32 v153, 0xffff0000, v137
	v_sub_f32_e32 v152, v152, v4
	v_sub_f32_e32 v153, v153, v4
	v_fmac_f32_e32 v145, v152, v152
	v_fmac_f32_e32 v149, v153, v153
	v_lshlrev_b32_e32 v152, 16, v138
	v_and_b32_e32 v153, 0xffff0000, v138
	v_sub_f32_e32 v152, v152, v4
	v_sub_f32_e32 v153, v153, v4
	v_fmac_f32_e32 v146, v152, v152
	v_fmac_f32_e32 v150, v153, v153
	v_lshlrev_b32_e32 v152, 16, v139
	v_and_b32_e32 v153, 0xffff0000, v139
	v_sub_f32_e32 v152, v152, v4
	v_sub_f32_e32 v153, v153, v4
	v_fmac_f32_e32 v147, v152, v152
	v_fmac_f32_e32 v151, v153, v153
	v_lshlrev_b32_e32 v152, 16, v140
	v_and_b32_e32 v153, 0xffff0000, v140
	v_sub_f32_e32 v152, v152, v4
	v_sub_f32_e32 v153, v153, v4
	v_fmac_f32_e32 v144, v152, v152
	v_fmac_f32_e32 v148, v153, v153
	v_lshlrev_b32_e32 v152, 16, v141
	v_and_b32_e32 v153, 0xffff0000, v141
	v_sub_f32_e32 v152, v152, v4
	v_sub_f32_e32 v153, v153, v4
	v_fmac_f32_e32 v145, v152, v152
	v_fmac_f32_e32 v149, v153, v153
	v_lshlrev_b32_e32 v152, 16, v142
	v_and_b32_e32 v153, 0xffff0000, v142
	v_sub_f32_e32 v152, v152, v4
	v_sub_f32_e32 v153, v153, v4
	v_fmac_f32_e32 v146, v152, v152
	v_fmac_f32_e32 v150, v153, v153
	v_lshlrev_b32_e32 v152, 16, v143
	v_and_b32_e32 v153, 0xffff0000, v143
	v_sub_f32_e32 v152, v152, v4
	v_sub_f32_e32 v153, v153, v4
	v_fmac_f32_e32 v147, v152, v152
	v_fmac_f32_e32 v151, v153, v153
	v_add_f32_e32 v144, v144, v145
	v_add_f32_e32 v146, v146, v147
	v_add_f32_e32 v148, v148, v149
	v_add_f32_e32 v150, v150, v151
	v_add_f32_e32 v144, v144, v146
	v_add_f32_e32 v148, v148, v150
	v_add_f32_e32 v0, v144, v148
	v_fmamk_f32 v0, v0, 0x3b800000, v213
	v_mul_f32_e32 v2, 0x4b800000, v0
	v_cmp_gt_f32_e32 vcc, s54, v0
	s_nop 1
	v_cndmask_b32_e32 v0, v0, v2, vcc
	v_rsq_f32_e32 v0, v0
	v_lshlrev_b32_e32 v2, 2, v12
	v_mul_f32_e32 v3, 0x45800000, v0
	v_cndmask_b32_e32 v0, v0, v3, vcc
	ds_write2st64_b32 v2, v4, v0 offset0:68 offset1:70

.LBB0_333:
	v_mov_b32_e32 v133, 0xff800000
	v_mov_b32_e32 v134, 0x97d0
	ds_write_b32 v134, v133
	v_mov_b32_e32 v166, 0x1f4
	s_add_i32 s8, s40, 0xffffff00
	s_waitcnt vmcnt(7)
	v_mov_b32_e32 v98, v218
	s_lshl_b32 s0, s8, 7
	v_ashrrev_i32_e32 v0, 1, v98
	s_waitcnt vmcnt(3)
	v_and_b32_e32 v110, 0xffffffe0, v0
	s_and_b32 s11, s0, 0xf80
	v_and_b32_e32 v6, 31, v98
	s_lshr_b32 s10, s8, 5
	v_add_u32_e32 v38, s11, v110
	s_bfe_u32 s9, s8, 0x20005
	s_lshl_b32 s28, s10, 19
	v_readlane_b32 s0, v251, 41
	v_or_b32_e32 v34, v38, v6
	s_add_u32 s0, s0, s28
	v_readlane_b32 s1, v251, 42
	v_ashrrev_i32_e32 v35, 31, v34
	v_bfe_u32 v37, v98, 5, 1
	s_addc_u32 s1, s1, 0
	v_lshlrev_b64 v[2:3], 7, v[34:35]
	v_lshl_add_u64 v[2:3], s[0:1], 0, v[2:3]
	v_lshlrev_b32_e32 v100, 4, v37
	v_mov_b32_e32 v101, v1
	v_lshl_add_u64 v[2:3], v[2:3], 0, v[100:101]
	global_load_dwordx4 v[66:69], v[2:3], off
	global_load_dwordx4 v[70:73], v[2:3], off offset:32
	global_load_dwordx4 v[74:77], v[2:3], off offset:64
	global_load_dwordx4 v[78:81], v[2:3], off offset:96
	s_movk_i32 s0, 0x1d1
	v_cmp_gt_i32_e32 vcc, s0, v98
	s_and_saveexec_b64 s[0:1], vcc
	s_cbranch_execz .LBB0_341
	v_max_i32_e32 v0, 0xd1, v98
	v_sub_u32_e32 v0, v0, v98
	v_add_u32_e32 v0, 0xff, v0
	v_cmp_lt_u32_e32 vcc, s36, v0
	s_mov_b64 s[4:5], -1
	v_mov_b32_e32 v2, v98
	s_and_saveexec_b64 s[2:3], vcc
	s_cbranch_execz .LBB0_338
	s_or_b32 s4, s9, s39
	v_readlane_b32 s12, v250, 18
	v_lshrrev_b32_e32 v0, 8, v0
	s_mul_hi_i32 s5, s4, 0x744
	s_mulk_i32 s4, 0x744
	v_readlane_b32 s14, v250, 20
	v_add_u32_e32 v0, 1, v0
	v_readlane_b32 s15, v250, 21
	s_add_u32 s4, s14, s4
	v_and_b32_e32 v4, 0x1fffffe, v0
	v_add_u32_e32 v99, 0x100, v98
	v_mov_b32_e32 v2, 0x9000
	s_addc_u32 s5, s15, s5
	v_lshl_add_u32 v5, v98, 2, v2
	s_mov_b64 s[6:7], 0
	v_mov_b32_e32 v7, v4
	v_mov_b64_e32 v[2:3], v[98:99]
	v_readlane_b32 s13, v250, 19
	v_readlane_b32 s16, v250, 22
	v_readlane_b32 s17, v250, 23
	v_readlane_b32 s18, v250, 24
	v_readlane_b32 s19, v250, 25
	v_readlane_b32 s20, v250, 26
	v_readlane_b32 s21, v250, 27
	v_readlane_b32 s22, v250, 28
	v_readlane_b32 s23, v250, 29
	v_readlane_b32 s24, v250, 30
	v_readlane_b32 s25, v250, 31
	v_readlane_b32 s26, v250, 32
	v_readlane_b32 s27, v250, 33

.LBB0_353:
	s_bitcmp1_b32 s66, 0
	s_cselect_b32 s68, 0x4800, 0
	v_or_b32_e32 v34, s68, v100
	v_add_u32_e32 v119, v34, v112
	ds_read_b128 v[34:37], v119
	ds_read_b128 v[38:41], v119 offset:32
	s_add_i32 s40, s61, s66
	v_cmp_lt_i32_e32 vcc, s40, v114
	s_cmp_gt_u32 s66, 3
	s_waitcnt lgkmcnt(1)
	v_mfma_f32_32x32x16_bf16 v[50:65], v[34:37], v[66:69], 0
	ds_read_b128 v[34:37], v119 offset:64
	ds_read_b128 v[120:123], v119 offset:4640
	v_cmp_ge_i32_e64 s[40:41], s40, v113
	s_cselect_b64 s[64:65], -1, 0
	s_and_b64 s[62:63], s[40:41], vcc
	s_cmp_lt_u32 s66, 4
	s_waitcnt lgkmcnt(2)
	v_mfma_f32_32x32x16_bf16 v[50:65], v[38:41], v[70:73], v[50:65]
	s_waitcnt lgkmcnt(1)
	v_mfma_f32_32x32x16_bf16 v[50:65], v[34:37], v[74:77], v[50:65]
	ds_read_b128 v[34:37], v119 offset:96
	s_waitcnt lgkmcnt(0)
	v_mfma_f32_32x32x16_bf16 v[50:65], v[34:37], v[78:81], v[50:65]
	ds_read_b128 v[34:37], v119 offset:4608
	s_waitcnt lgkmcnt(0)
	v_mfma_f32_32x32x16_bf16 v[34:49], v[34:37], v[66:69], 0
	s_nop 8
	v_mul_f32_e32 v50, 0x3e38aa3b, v50
	v_mfma_f32_32x32x16_bf16 v[34:49], v[120:123], v[70:73], v[34:49]
	ds_read_b128 v[120:123], v119 offset:4672
	s_waitcnt lgkmcnt(0)
	v_mfma_f32_32x32x16_bf16 v[34:49], v[120:123], v[74:77], v[34:49]
	ds_read_b128 v[120:123], v119 offset:4704
	s_waitcnt lgkmcnt(0)
	v_mfma_f32_32x32x16_bf16 v[34:49], v[120:123], v[78:81], v[34:49]
	s_cbranch_scc1 .LBB0_355
	v_readlane_b32 s40, v255, 19
	v_readlane_b32 s41, v255, 20
	s_and_b64 vcc, s[62:63], s[40:41]
	v_cndmask_b32_e32 v133, v166, v116, vcc
	v_lshlrev_b32_e32 v133, 2, v133
	ds_read_b32 v133, v133 offset:36864
.LBB0_355:
	v_cndmask_b32_e64 v119, 0, 1, s[64:65]
	v_cmp_ne_u32_e64 s[40:41], 1, v119
	s_andn2_b64 vcc, exec, s[64:65]
	v_mul_f32_e32 v51, 0x3e38aa3b, v51
	s_cbranch_vccnz .LBB0_391
	v_readlane_b32 s64, v255, 21
	v_readlane_b32 s65, v255, 22
	v_add_u32_e32 v119, 1, v116
	s_and_b64 vcc, s[62:63], s[64:65]
	v_cndmask_b32_e32 v134, v166, v119, vcc
	v_lshlrev_b32_e32 v134, 2, v134
	ds_read_b32 v134, v134 offset:36864
	s_and_b64 vcc, exec, s[40:41]
	v_mul_f32_e32 v52, 0x3e38aa3b, v52
	s_cbranch_vccz .LBB0_392

.LBB0_358:
	v_readlane_b32 s64, v255, 25
	v_readlane_b32 s65, v255, 26
	v_add_u32_e32 v119, 3, v116
	s_and_b64 vcc, s[62:63], s[64:65]
	v_cndmask_b32_e32 v135, v166, v119, vcc
	v_lshlrev_b32_e32 v135, 2, v135
	ds_read_b32 v135, v135 offset:36864
	s_and_b64 vcc, exec, s[40:41]
	v_mul_f32_e32 v54, 0x3e38aa3b, v54
	s_cbranch_vccz .LBB0_394

.LBB0_360:
	v_readlane_b32 s64, v255, 29
	v_readlane_b32 s65, v255, 30
	v_add_u32_e32 v119, 9, v116
	s_and_b64 vcc, s[62:63], s[64:65]
	v_cndmask_b32_e32 v136, v166, v119, vcc
	v_lshlrev_b32_e32 v136, 2, v136
	ds_read_b32 v136, v136 offset:36864
	s_and_b64 vcc, exec, s[40:41]
	v_mul_f32_e32 v56, 0x3e38aa3b, v56
	s_cbranch_vccz .LBB0_396

.LBB0_362:
	v_readlane_b32 s64, v255, 33
	v_readlane_b32 s65, v255, 34
	v_add_u32_e32 v119, 11, v116
	s_and_b64 vcc, s[62:63], s[64:65]
	v_cndmask_b32_e32 v137, v166, v119, vcc
	v_lshlrev_b32_e32 v137, 2, v137
	ds_read_b32 v137, v137 offset:36864
	s_and_b64 vcc, exec, s[40:41]
	v_mul_f32_e32 v58, 0x3e38aa3b, v58
	s_cbranch_vccz .LBB0_398

.LBB0_364:
	v_readlane_b32 s64, v255, 39
	v_readlane_b32 s65, v255, 40
	v_readlane_b32 vcc_lo, v255, 41
	s_and_b64 s[64:65], s[62:63], s[64:65]
	v_readlane_b32 vcc_hi, v255, 42
	v_add_u32_e32 v119, 17, v116
	s_and_b64 vcc, s[64:65], vcc
	v_cndmask_b32_e32 v138, v166, v119, vcc
	v_lshlrev_b32_e32 v138, 2, v138
	ds_read_b32 v138, v138 offset:36864
	s_and_b64 vcc, exec, s[40:41]
	v_mul_f32_e32 v60, 0x3e38aa3b, v60
	s_cbranch_vccz .LBB0_400

.LBB0_366:
	v_readlane_b32 s64, v255, 47
	v_readlane_b32 s65, v255, 48
	v_readlane_b32 vcc_lo, v255, 49
	s_and_b64 s[64:65], s[62:63], s[64:65]
	v_readlane_b32 vcc_hi, v255, 50
	v_add_u32_e32 v119, 19, v116
	s_and_b64 vcc, s[64:65], vcc
	v_cndmask_b32_e32 v139, v166, v119, vcc
	v_lshlrev_b32_e32 v139, 2, v139
	ds_read_b32 v139, v139 offset:36864
	s_and_b64 vcc, exec, s[40:41]
	v_mul_f32_e32 v62, 0x3e38aa3b, v62
	s_cbranch_vccz .LBB0_402

.LBB0_368:
	s_and_b64 s[64:65], s[62:63], s[76:77]
	v_add_u32_e32 v119, 25, v116
	s_and_b64 vcc, s[64:65], s[78:79]
	v_cndmask_b32_e32 v140, v166, v119, vcc
	v_lshlrev_b32_e32 v140, 2, v140
	ds_read_b32 v140, v140 offset:36864
	s_and_b64 vcc, exec, s[40:41]
	v_mul_f32_e32 v64, 0x3e38aa3b, v64
	s_cbranch_vccz .LBB0_404

.LBB0_370:
	s_and_b64 s[64:65], s[62:63], s[84:85]
	v_add_u32_e32 v119, 27, v116
	s_and_b64 vcc, s[64:65], s[86:87]
	v_cndmask_b32_e32 v141, v166, v119, vcc
	v_lshlrev_b32_e32 v141, 2, v141
	ds_read_b32 v141, v141 offset:36864
	s_and_b64 vcc, exec, s[40:41]
	v_mul_f32_e32 v119, 0x3e38aa3b, v34
	s_cbranch_vccz .LBB0_406

.LBB0_372:
	s_and_b64 s[64:65], s[62:63], s[92:93]
	v_add_u32_e32 v34, 33, v116
	s_and_b64 vcc, s[64:65], s[50:51]
	v_cndmask_b32_e32 v142, v166, v34, vcc
	v_lshlrev_b32_e32 v142, 2, v142
	ds_read_b32 v142, v142 offset:36864
	s_and_b64 vcc, exec, s[40:41]
	v_mul_f32_e32 v36, 0x3e38aa3b, v36
	s_cbranch_vccz .LBB0_408

.LBB0_374:
	s_and_b64 s[64:65], s[62:63], s[6:7]
	v_add_u32_e32 v34, 35, v116
	s_and_b64 vcc, s[64:65], s[8:9]
	v_cndmask_b32_e32 v143, v166, v34, vcc
	v_lshlrev_b32_e32 v143, 2, v143
	ds_read_b32 v143, v143 offset:36864
	s_and_b64 vcc, exec, s[40:41]
	v_mul_f32_e32 v38, 0x3e38aa3b, v38
	s_cbranch_vccz .LBB0_410

.LBB0_376:
	s_and_b64 s[64:65], s[62:63], s[14:15]
	v_add_u32_e32 v34, 41, v116
	s_and_b64 vcc, s[64:65], s[16:17]
	v_cndmask_b32_e32 v144, v166, v34, vcc
	v_lshlrev_b32_e32 v144, 2, v144
	ds_read_b32 v144, v144 offset:36864
	s_and_b64 vcc, exec, s[40:41]
	v_mul_f32_e32 v40, 0x3e38aa3b, v40
	s_cbranch_vccz .LBB0_412

.LBB0_378:
	s_and_b64 s[64:65], s[62:63], s[22:23]
	v_add_u32_e32 v34, 43, v116
	s_and_b64 vcc, s[64:65], s[24:25]
	v_cndmask_b32_e32 v145, v166, v34, vcc
	v_lshlrev_b32_e32 v145, 2, v145
	ds_read_b32 v145, v145 offset:36864
	s_mov_b64 s[64:65], s[96:97]
	s_and_b64 vcc, exec, s[40:41]
	v_mul_f32_e32 v42, 0x3e38aa3b, v42
	s_cbranch_vccz .LBB0_414

.LBB0_380:
	v_add_u32_e32 v34, 49, v116
	s_and_b64 vcc, s[62:63], s[28:29]
	v_cndmask_b32_e32 v146, v166, v34, vcc
	v_lshlrev_b32_e32 v146, 2, v146
	ds_read_b32 v146, v146 offset:36864
	s_and_b64 vcc, exec, s[40:41]
	v_mul_f32_e32 v44, 0x3e38aa3b, v44
	s_cbranch_vccz .LBB0_416

.LBB0_382:
	v_add_u32_e32 v34, 51, v116
	s_and_b64 vcc, s[62:63], s[34:35]
	v_cndmask_b32_e32 v147, v166, v34, vcc
	v_lshlrev_b32_e32 v147, 2, v147
	ds_read_b32 v147, v147 offset:36864
	s_and_b64 vcc, exec, s[40:41]
	v_mul_f32_e32 v46, 0x3e38aa3b, v46
	s_cbranch_vccz .LBB0_418

.LBB0_384:
	v_add_u32_e32 v34, 57, v116
	s_and_b64 vcc, s[62:63], s[38:39]
	v_cndmask_b32_e32 v148, v166, v34, vcc
	v_lshlrev_b32_e32 v148, 2, v148
	ds_read_b32 v148, v148 offset:36864
	s_and_b64 vcc, exec, s[40:41]
	v_mul_f32_e32 v48, 0x3e38aa3b, v48
	s_cbranch_vccz .LBB0_420

.LBB0_386:
	v_add_u32_e32 v34, 59, v116
	s_and_b64 vcc, s[62:63], s[2:3]
	v_cndmask_b32_e32 v149, v166, v34, vcc
	v_lshlrev_b32_e32 v149, 2, v149
	ds_read_b32 v149, v149 offset:36864
.LBB0_387:
	s_cmp_lt_u32 s66, 4
	s_cbranch_scc1 .Lna_nobias
	s_waitcnt lgkmcnt(0)
	v_fmac_f32_e32 v50, 0x3fb8aa3b, v133
	v_fmac_f32_e32 v51, 0x3fb8aa3b, v134
	v_fmac_f32_e32 v53, 0x3fb8aa3b, v135
	v_fmac_f32_e32 v55, 0x3fb8aa3b, v136
	v_fmac_f32_e32 v57, 0x3fb8aa3b, v137
	v_fmac_f32_e32 v59, 0x3fb8aa3b, v138
	v_fmac_f32_e32 v61, 0x3fb8aa3b, v139
	v_fmac_f32_e32 v63, 0x3fb8aa3b, v140
	v_fmac_f32_e32 v65, 0x3fb8aa3b, v141
	v_fmac_f32_e32 v120, 0x3fb8aa3b, v142
	v_fmac_f32_e32 v37, 0x3fb8aa3b, v143
	v_fmac_f32_e32 v39, 0x3fb8aa3b, v144
	v_fmac_f32_e32 v41, 0x3fb8aa3b, v145
	v_fmac_f32_e32 v43, 0x3fb8aa3b, v146
	v_fmac_f32_e32 v45, 0x3fb8aa3b, v147
	v_fmac_f32_e32 v47, 0x3fb8aa3b, v148
	v_fmac_f32_e32 v49, 0x3fb8aa3b, v149
	v_fmac_f32_e32 v52, 0x3fb8aa3b, v150
	v_fmac_f32_e32 v54, 0x3fb8aa3b, v151
	v_fmac_f32_e32 v56, 0x3fb8aa3b, v152
	v_fmac_f32_e32 v58, 0x3fb8aa3b, v153
	v_fmac_f32_e32 v60, 0x3fb8aa3b, v154
	v_fmac_f32_e32 v62, 0x3fb8aa3b, v155
	v_fmac_f32_e32 v64, 0x3fb8aa3b, v156
	v_fmac_f32_e32 v119, 0x3fb8aa3b, v157
	v_fmac_f32_e32 v36, 0x3fb8aa3b, v158
	v_fmac_f32_e32 v38, 0x3fb8aa3b, v159
	v_fmac_f32_e32 v40, 0x3fb8aa3b, v160
	v_fmac_f32_e32 v42, 0x3fb8aa3b, v161
	v_fmac_f32_e32 v44, 0x3fb8aa3b, v162
	v_fmac_f32_e32 v46, 0x3fb8aa3b, v163
	v_fmac_f32_e32 v48, 0x3fb8aa3b, v164

.LBB0_392:
	v_readlane_b32 s64, v255, 23
	v_readlane_b32 s65, v255, 24
	v_add_u32_e32 v119, 2, v116
	s_and_b64 vcc, s[62:63], s[64:65]
	v_cndmask_b32_e32 v150, v166, v119, vcc
	v_lshlrev_b32_e32 v150, 2, v150
	ds_read_b32 v150, v150 offset:36864
	s_and_b64 vcc, exec, s[40:41]
	v_mul_f32_e32 v53, 0x3e38aa3b, v53
	s_cbranch_vccz .LBB0_358

.LBB0_394:
	v_readlane_b32 s64, v255, 27
	v_readlane_b32 s65, v255, 28
	v_add_u32_e32 v119, 8, v116
	s_and_b64 vcc, s[62:63], s[64:65]
	v_cndmask_b32_e32 v151, v166, v119, vcc
	v_lshlrev_b32_e32 v151, 2, v151
	ds_read_b32 v151, v151 offset:36864
	s_and_b64 vcc, exec, s[40:41]
	v_mul_f32_e32 v55, 0x3e38aa3b, v55
	s_cbranch_vccz .LBB0_360

.LBB0_396:
	v_readlane_b32 s64, v255, 31
	v_readlane_b32 s65, v255, 32
	v_add_u32_e32 v119, 10, v116
	s_and_b64 vcc, s[62:63], s[64:65]
	v_cndmask_b32_e32 v152, v166, v119, vcc
	v_lshlrev_b32_e32 v152, 2, v152
	ds_read_b32 v152, v152 offset:36864
	s_and_b64 vcc, exec, s[40:41]
	v_mul_f32_e32 v57, 0x3e38aa3b, v57
	s_cbranch_vccz .LBB0_362

.LBB0_398:
	v_readlane_b32 s64, v255, 35
	v_readlane_b32 s65, v255, 36
	v_readlane_b32 vcc_lo, v255, 37
	s_and_b64 s[64:65], s[62:63], s[64:65]
	v_readlane_b32 vcc_hi, v255, 38
	v_add_u32_e32 v119, 16, v116
	s_and_b64 vcc, s[64:65], vcc
	v_cndmask_b32_e32 v153, v166, v119, vcc
	v_lshlrev_b32_e32 v153, 2, v153
	ds_read_b32 v153, v153 offset:36864
	s_and_b64 vcc, exec, s[40:41]
	v_mul_f32_e32 v59, 0x3e38aa3b, v59
	s_cbranch_vccz .LBB0_364

.LBB0_400:
	v_readlane_b32 s64, v255, 43
	v_readlane_b32 s65, v255, 44
	v_readlane_b32 vcc_lo, v255, 45
	s_and_b64 s[64:65], s[62:63], s[64:65]
	v_readlane_b32 vcc_hi, v255, 46
	v_add_u32_e32 v119, 18, v116
	s_and_b64 vcc, s[64:65], vcc
	v_cndmask_b32_e32 v154, v166, v119, vcc
	v_lshlrev_b32_e32 v154, 2, v154
	ds_read_b32 v154, v154 offset:36864
	s_and_b64 vcc, exec, s[40:41]
	v_mul_f32_e32 v61, 0x3e38aa3b, v61
	s_cbranch_vccz .LBB0_366

.LBB0_402:
	v_readlane_b32 s64, v255, 51
	v_readlane_b32 s65, v255, 52
	s_and_b64 s[64:65], s[62:63], s[64:65]
	v_add_u32_e32 v119, 24, v116
	s_and_b64 vcc, s[64:65], s[74:75]
	v_cndmask_b32_e32 v155, v166, v119, vcc
	v_lshlrev_b32_e32 v155, 2, v155
	ds_read_b32 v155, v155 offset:36864
	s_and_b64 vcc, exec, s[40:41]
	v_mul_f32_e32 v63, 0x3e38aa3b, v63
	s_cbranch_vccz .LBB0_368

.LBB0_404:
	s_and_b64 s[64:65], s[62:63], s[80:81]
	v_add_u32_e32 v119, 26, v116
	s_and_b64 vcc, s[64:65], s[82:83]
	v_cndmask_b32_e32 v156, v166, v119, vcc
	v_lshlrev_b32_e32 v156, 2, v156
	ds_read_b32 v156, v156 offset:36864
	s_and_b64 vcc, exec, s[40:41]
	v_mul_f32_e32 v65, 0x3e38aa3b, v65
	s_cbranch_vccz .LBB0_370

.LBB0_406:
	s_and_b64 s[64:65], s[62:63], s[88:89]
	v_add_u32_e32 v34, 32, v116
	s_and_b64 vcc, s[64:65], s[90:91]
	v_cndmask_b32_e32 v157, v166, v34, vcc
	v_lshlrev_b32_e32 v157, 2, v157
	ds_read_b32 v157, v157 offset:36864
	s_and_b64 vcc, exec, s[40:41]
	v_mul_f32_e32 v120, 0x3e38aa3b, v35
	s_cbranch_vccz .LBB0_372

.LBB0_408:
	s_and_b64 s[64:65], s[62:63], s[72:73]
	v_add_u32_e32 v34, 34, v116
	s_and_b64 vcc, s[64:65], s[4:5]
	v_cndmask_b32_e32 v158, v166, v34, vcc
	v_lshlrev_b32_e32 v158, 2, v158
	ds_read_b32 v158, v158 offset:36864
	s_and_b64 vcc, exec, s[40:41]
	v_mul_f32_e32 v37, 0x3e38aa3b, v37
	s_cbranch_vccz .LBB0_374

.LBB0_410:
	s_and_b64 s[64:65], s[62:63], s[10:11]
	v_add_u32_e32 v34, 40, v116
	s_and_b64 vcc, s[64:65], s[12:13]
	v_cndmask_b32_e32 v159, v166, v34, vcc
	v_lshlrev_b32_e32 v159, 2, v159
	ds_read_b32 v159, v159 offset:36864
	s_and_b64 vcc, exec, s[40:41]
	v_mul_f32_e32 v39, 0x3e38aa3b, v39
	s_cbranch_vccz .LBB0_376

.LBB0_412:
	s_and_b64 s[64:65], s[62:63], s[18:19]
	v_add_u32_e32 v34, 42, v116
	s_and_b64 vcc, s[64:65], s[20:21]
	v_cndmask_b32_e32 v160, v166, v34, vcc
	v_lshlrev_b32_e32 v160, 2, v160
	ds_read_b32 v160, v160 offset:36864
	s_and_b64 vcc, exec, s[40:41]
	v_mul_f32_e32 v41, 0x3e38aa3b, v41
	s_cbranch_vccz .LBB0_378

.LBB0_414:
	v_add_u32_e32 v34, 48, v116
	s_and_b64 vcc, s[62:63], s[26:27]
	v_cndmask_b32_e32 v161, v166, v34, vcc
	v_lshlrev_b32_e32 v161, 2, v161
	ds_read_b32 v161, v161 offset:36864
	s_and_b64 vcc, exec, s[40:41]
	v_mul_f32_e32 v43, 0x3e38aa3b, v43
	s_cbranch_vccz .LBB0_380

.LBB0_416:
	v_add_u32_e32 v34, 50, v116
	s_and_b64 vcc, s[62:63], s[30:31]
	v_cndmask_b32_e32 v162, v166, v34, vcc
	v_lshlrev_b32_e32 v162, 2, v162
	ds_read_b32 v162, v162 offset:36864
	s_and_b64 vcc, exec, s[40:41]
	v_mul_f32_e32 v45, 0x3e38aa3b, v45
	s_cbranch_vccz .LBB0_382

.LBB0_418:
	v_add_u32_e32 v34, 56, v116
	s_and_b64 vcc, s[62:63], s[36:37]
	v_cndmask_b32_e32 v163, v166, v34, vcc
	v_lshlrev_b32_e32 v163, 2, v163
	ds_read_b32 v163, v163 offset:36864
	s_and_b64 vcc, exec, s[40:41]
	v_mul_f32_e32 v47, 0x3e38aa3b, v47
	s_cbranch_vccz .LBB0_384

.LBB0_420:
	v_add_u32_e32 v34, 58, v116
	s_and_b64 vcc, s[62:63], s[0:1]
	v_cndmask_b32_e32 v164, v166, v34, vcc
	v_lshlrev_b32_e32 v164, 2, v164
	ds_read_b32 v164, v164 offset:36864
	s_and_b64 vcc, exec, s[40:41]
	v_mul_f32_e32 v49, 0x3e38aa3b, v49
	s_cbranch_vccz .LBB0_386
	s_branch .LBB0_387

.LBB0_538:
	v_cmp_gt_i32_e32 vcc, s33, v2
	s_or_b64 s[16:17], s[16:17], exec
	s_and_saveexec_b64 s[18:19], vcc
	s_cbranch_execz .LBB0_537
	v_ashrrev_i32_e32 v3, 31, v2
	v_lshlrev_b64 v[4:5], 11, v[2:3]
	v_lshl_add_u64 v[8:9], v[60:61], 0, v[4:5]
	global_load_dwordx4 v[4:7], v[8:9], off offset:16
	s_nop 0
	global_load_dwordx4 v[8:11], v[8:9], off
	s_waitcnt lgkmcnt(0)
	v_add_u32_e32 v109, s20, v193
	s_waitcnt vmcnt(1)
	v_lshlrev_b32_e32 v13, 16, v4
	s_waitcnt vmcnt(0)
	v_lshlrev_b32_e32 v12, 16, v8
	v_and_b32_e32 v8, 0xffff0000, v8
	v_lshlrev_b32_e32 v14, 16, v9
	v_and_b32_e32 v15, 0xffff0000, v9
	v_max3_f32 v0, |v12|, 0, |v8|
	v_lshlrev_b32_e32 v17, 16, v10
	v_and_b32_e32 v10, 0xffff0000, v10
	v_max3_f32 v0, v0, |v14|, |v15|
	v_lshlrev_b32_e32 v19, 16, v11
	v_and_b32_e32 v11, 0xffff0000, v11
	v_max3_f32 v0, v0, |v17|, |v10|
	v_and_b32_e32 v4, 0xffff0000, v4
	v_max3_f32 v0, v0, |v19|, |v11|
	v_lshlrev_b32_e32 v16, 16, v5
	v_and_b32_e32 v5, 0xffff0000, v5
	v_max3_f32 v0, v0, |v13|, |v4|
	v_lshlrev_b32_e32 v18, 16, v6
	v_and_b32_e32 v6, 0xffff0000, v6
	v_max3_f32 v0, v0, |v16|, |v5|
	v_lshlrev_b32_e32 v20, 16, v7
	v_and_b32_e32 v7, 0xffff0000, v7
	v_max3_f32 v0, v0, |v18|, |v6|
	v_max3_f32 v9, v0, |v20|, |v7|
	v_and_b32_e32 v0, 64, v219
	v_add_u32_e32 v21, 64, v0
	v_xor_b32_e32 v0, 32, v219
	v_cmp_lt_i32_e32 vcc, v0, v21
	s_nop 1
	v_cndmask_b32_e32 v0, v219, v0, vcc
	v_lshlrev_b32_e32 v0, 2, v0
	ds_bpermute_b32 v22, v0, v9
	s_waitcnt lgkmcnt(0)
	v_max_f32_e32 v22, v22, v22
	v_max_f32_e32 v9, v9, v22
	v_xor_b32_e32 v22, 16, v219
	v_cmp_lt_i32_e32 vcc, v22, v21
	s_nop 1
	v_cndmask_b32_e32 v22, v219, v22, vcc
	v_lshlrev_b32_e32 v22, 2, v22
	ds_bpermute_b32 v22, v22, v9
	s_waitcnt lgkmcnt(0)
	v_max_f32_e32 v22, v22, v22
	v_max_f32_e32 v9, v9, v22
	v_xor_b32_e32 v22, 8, v219
	v_cmp_lt_i32_e32 vcc, v22, v21
	s_nop 1
	v_cndmask_b32_e32 v22, v219, v22, vcc
	v_lshlrev_b32_e32 v22, 2, v22
	ds_bpermute_b32 v22, v22, v9
	s_waitcnt lgkmcnt(0)
	v_max_f32_e32 v22, v22, v22
	v_max_f32_e32 v9, v9, v22
	v_xor_b32_e32 v22, 4, v219
	v_cmp_lt_i32_e32 vcc, v22, v21
	s_nop 1
	v_cndmask_b32_e32 v22, v219, v22, vcc
	v_lshlrev_b32_e32 v22, 2, v22
	ds_bpermute_b32 v22, v22, v9
	s_waitcnt lgkmcnt(0)
	v_max_f32_e32 v22, v22, v22
	v_max_f32_e32 v9, v9, v22
	v_xor_b32_e32 v22, 2, v219
	v_cmp_lt_i32_e32 vcc, v22, v21
	s_nop 1
	v_cndmask_b32_e32 v22, v219, v22, vcc
	v_lshlrev_b32_e32 v22, 2, v22
	ds_bpermute_b32 v22, v22, v9
	s_waitcnt lgkmcnt(0)
	v_max_f32_e32 v22, v22, v22
	v_max_f32_e32 v9, v9, v22
	v_xor_b32_e32 v22, 1, v219
	v_cmp_lt_i32_e32 vcc, v22, v21
	s_nop 1
	v_cndmask_b32_e32 v21, v219, v22, vcc
	v_lshlrev_b32_e32 v21, 2, v21
	ds_bpermute_b32 v21, v21, v9
	s_waitcnt lgkmcnt(0)
	v_max_f32_e32 v21, v21, v21
	v_max_f32_e32 v9, v9, v21
	v_div_scale_f32 v21, s[22:23], v9, v9, s69
	v_rcp_f32_e32 v22, v21
	v_cmp_lt_f32_e64 s[0:1], 0, v9
	v_fma_f32 v23, -v21, v22, 1.0
	v_fmac_f32_e32 v22, v23, v22
	v_div_scale_f32 v23, vcc, s69, v9, s69
	v_mul_f32_e32 v24, v23, v22
	v_fma_f32 v25, -v21, v24, v23
	v_fmac_f32_e32 v24, v25, v22
	v_fma_f32 v21, -v21, v24, v23
	v_div_fmas_f32 v21, v21, v22, v24
	v_div_fixup_f32 v21, v21, v9, s69
	v_cndmask_b32_e64 v21, 0, v21, s[0:1]
	v_mul_f32_e32 v12, v21, v12
	v_mul_f32_e32 v8, v21, v8
	v_rndne_f32_e32 v12, v12
	v_rndne_f32_e32 v8, v8
	v_cvt_i32_f32_e32 v12, v12
	v_cvt_i32_f32_e32 v8, v8
	v_mul_f32_e32 v14, v21, v14
	v_mul_f32_e32 v15, v21, v15
	v_rndne_f32_e32 v14, v14
	v_rndne_f32_e32 v15, v15
	v_cvt_i32_f32_e32 v14, v14
	v_cvt_i32_f32_e32 v15, v15
	v_mul_f32_e32 v17, v21, v17
	v_mul_f32_e32 v10, v21, v10
	v_rndne_f32_e32 v17, v17
	v_rndne_f32_e32 v10, v10
	v_add_u32_e32 v22, 8, v12
	v_add_u32_e32 v23, 8, v8
	v_cvt_i32_f32_e32 v17, v17
	v_cvt_i32_f32_e32 v10, v10
	v_mul_f32_e32 v11, v21, v11
	v_lshrrev_b32_e32 v22, 4, v22
	v_and_b32_e32 v23, 0xf0, v23
	v_mul_f32_e32 v19, v21, v19
	v_rndne_f32_e32 v11, v11
	v_and_or_b32 v22, v22, 15, v23
	v_lshl_add_u32 v23, v14, 4, v222
	v_lshl_add_u32 v24, v15, 8, v223
	v_rndne_f32_e32 v19, v19
	v_cvt_i32_f32_e32 v11, v11
	v_and_b32_e32 v23, 0xf00, v23
	v_and_b32_e32 v24, 0xf000, v24
	v_cvt_i32_f32_e32 v19, v19
	v_or3_b32 v22, v22, v23, v24
	v_lshl_add_u32 v23, v17, 12, v224
	v_lshl_add_u32 v24, v10, 16, v225
	v_and_b32_e32 v12, 15, v12
	v_lshlrev_b32_e32 v8, 4, v8
	v_lshlrev_b32_e32 v14, 8, v14
	v_and_b32_e32 v23, 0xf0000, v23
	v_and_b32_e32 v24, 0xf00000, v24
	v_and_b32_e32 v8, 0xf0, v8
	v_and_b32_e32 v14, 0xf00, v14
	v_lshlrev_b32_e32 v15, 12, v15
	v_lshlrev_b32_e32 v17, 16, v17
	v_or3_b32 v22, v22, v23, v24
	v_lshl_add_u32 v24, v11, 24, v227
	v_lshl_or_b32 v11, v11, 28, v12
	v_and_b32_e32 v15, 0xf000, v15
	v_and_b32_e32 v17, 0xf0000, v17
	v_lshlrev_b32_e32 v10, 20, v10
	v_lshl_add_u32 v23, v19, 20, v226
	v_lshlrev_b32_e32 v19, 24, v19
	v_or3_b32 v8, v11, v8, v14
	v_and_b32_e32 v10, 0xf00000, v10
	v_and_b32_e32 v19, 0xf000000, v19
	v_or3_b32 v8, v8, v15, v17
	v_or3_b32 v75, v8, v10, v19
	v_mul_f32_e32 v8, v21, v13
	v_mul_f32_e32 v4, v21, v4
	v_rndne_f32_e32 v8, v8
	v_rndne_f32_e32 v4, v4
	v_cvt_i32_f32_e32 v8, v8
	v_cvt_i32_f32_e32 v4, v4
	v_mul_f32_e32 v5, v21, v5
	v_rndne_f32_e32 v5, v5
	v_add_u32_e32 v10, 8, v8
	v_add_u32_e32 v11, 8, v4
	v_lshrrev_b32_e32 v10, 4, v10
	v_and_b32_e32 v11, 0xf0, v11
	v_and_or_b32 v10, v10, 15, v11
	v_mul_f32_e32 v11, v21, v16
	v_rndne_f32_e32 v11, v11
	v_cvt_i32_f32_e32 v11, v11
	v_cvt_i32_f32_e32 v5, v5
	v_mul_f32_e32 v6, v21, v6
	v_rndne_f32_e32 v6, v6
	v_lshl_add_u32 v12, v11, 4, v222
	v_lshl_add_u32 v13, v5, 8, v223
	v_and_b32_e32 v12, 0xf00, v12
	v_and_b32_e32 v13, 0xf000, v13
	v_or3_b32 v10, v10, v12, v13
	v_mul_f32_e32 v12, v21, v18
	v_rndne_f32_e32 v12, v12
	v_cvt_i32_f32_e32 v12, v12
	v_cvt_i32_f32_e32 v6, v6
	v_mul_f32_e32 v7, v21, v7
	v_rndne_f32_e32 v7, v7
	v_lshl_add_u32 v13, v12, 12, v224
	v_lshl_add_u32 v14, v6, 16, v225
	v_and_b32_e32 v13, 0xf0000, v13
	v_and_b32_e32 v14, 0xf00000, v14
	v_or3_b32 v10, v10, v13, v14
	v_mul_f32_e32 v13, v21, v20
	v_rndne_f32_e32 v13, v13
	v_cvt_i32_f32_e32 v7, v7
	v_cvt_i32_f32_e32 v13, v13
	v_and_b32_e32 v8, 15, v8
	v_lshlrev_b32_e32 v4, 4, v4
	v_lshlrev_b32_e32 v11, 8, v11
	v_and_b32_e32 v4, 0xf0, v4
	v_and_b32_e32 v11, 0xf00, v11
	v_lshlrev_b32_e32 v5, 12, v5
	v_lshlrev_b32_e32 v12, 16, v12
	v_lshl_add_u32 v15, v7, 24, v227
	v_lshl_or_b32 v7, v7, 28, v8
	v_and_b32_e32 v5, 0xf000, v5
	v_and_b32_e32 v12, 0xf0000, v12
	v_lshlrev_b32_e32 v6, 20, v6
	v_lshl_add_u32 v14, v13, 20, v226
	v_lshlrev_b32_e32 v13, 24, v13
	v_or3_b32 v4, v7, v4, v11
	v_and_b32_e32 v6, 0xf00000, v6
	v_and_b32_e32 v13, 0xf000000, v13
	v_or3_b32 v4, v4, v5, v12
	v_or3_b32 v108, v4, v6, v13
	v_lshlrev_b64 v[6:7], 9, v[2:3]
	v_and_b32_e32 v14, 0xf000000, v14
	v_and_b32_e32 v15, 0xf0000000, v15
	v_lshl_add_u64 v[4:5], v[62:63], 0, v[6:7]
	v_or3_b32 v77, v10, v14, v15
	global_load_dword v20, v[4:5], off
	global_load_dword v18, v[4:5], off offset:64
	global_load_dword v16, v[4:5], off offset:128
	global_load_dword v14, v[4:5], off offset:192
	global_load_dword v12, v[4:5], off offset:256
	global_load_dword v10, v[4:5], off offset:320
	global_load_dword v8, v[4:5], off offset:384
	s_nop 0
	global_load_dword v4, v[4:5], off offset:448
	v_and_b32_e32 v23, 0xf000000, v23
	v_and_b32_e32 v24, 0xf0000000, v24
	v_or3_b32 v73, v22, v23, v24
	v_mul_f32_e32 v3, 0x3c09ae41, v9
	v_lshl_add_u64 v[6:7], v[64:65], 0, v[6:7]
	s_waitcnt vmcnt(7)
	v_readlane_b32 s0, v20, 0
	s_lshl_b32 s0, s0, 9
	s_nop 3
	buffer_load_dwordx2 v[100:101], v192, s[52:55], s0 offen
	v_readlane_b32 s0, v20, 1
	s_lshl_b32 s0, s0, 9
	s_waitcnt vmcnt(0)
	v_dot8_i32_i4 v5, v100, v73, 0
	s_nop 1
	buffer_load_dwordx2 v[102:103], v192, s[52:55], s0 offen
	v_readlane_b32 s0, v20, 2
	s_lshl_b32 s0, s0, 9
	v_dot8_i32_i4 v9, v100, v75, 0
	v_dot8_i32_i4 v5, v101, v77, v5
	v_dot8_i32_i4 v9, v101, v108, v9
	s_waitcnt vmcnt(0)
	v_dot8_i32_i4 v11, v102, v75, 0
	buffer_load_dwordx2 v[98:99], v192, s[52:55], s0 offen
	v_readlane_b32 s0, v20, 3
	s_lshl_b32 s0, s0, 9
	v_lshl_add_u32 v5, v5, 4, v9
	v_dot8_i32_i4 v9, v102, v73, 0
	v_dot8_i32_i4 v9, v103, v77, v9
	buffer_load_dwordx2 v[104:105], v192, s[52:55], s0 offen
	v_readlane_b32 s0, v20, 4
	s_lshl_b32 s0, s0, 9
	v_dot8_i32_i4 v11, v103, v108, v11
	v_cvt_f32_i32_e32 v5, v5
	s_waitcnt vmcnt(1)
	v_dot8_i32_i4 v13, v98, v75, 0
	buffer_load_dwordx2 v[94:95], v192, s[52:55], s0 offen
	v_readlane_b32 s0, v20, 5
	s_lshl_b32 s0, s0, 9
	v_lshl_add_u32 v9, v9, 4, v11
	v_dot8_i32_i4 v11, v98, v73, 0
	v_dot8_i32_i4 v11, v99, v77, v11
	buffer_load_dwordx2 v[86:87], v192, s[52:55], s0 offen
	v_readlane_b32 s0, v20, 6
	s_lshl_b32 s0, s0, 9
	v_dot8_i32_i4 v13, v99, v108, v13
	s_waitcnt vmcnt(2)
	v_dot8_i32_i4 v15, v104, v75, 0
	v_dot8_i32_i4 v15, v105, v108, v15
	v_cvt_f32_i32_e32 v9, v9
	buffer_load_dwordx2 v[84:85], v192, s[52:55], s0 offen
	v_readlane_b32 s0, v20, 7
	s_lshl_b32 s0, s0, 9
	v_lshl_add_u32 v11, v11, 4, v13
	v_dot8_i32_i4 v13, v104, v73, 0
	v_dot8_i32_i4 v13, v105, v77, v13
	buffer_load_dwordx2 v[90:91], v192, s[52:55], s0 offen
	v_readlane_b32 s0, v20, 8
	s_lshl_b32 s0, s0, 9
	v_lshl_add_u32 v13, v13, 4, v15
	v_cvt_f32_i32_e32 v11, v11
	v_cvt_f32_i32_e32 v13, v13
	buffer_load_dwordx2 v[78:79], v192, s[52:55], s0 offen
	v_readlane_b32 s0, v20, 9
	s_lshl_b32 s0, s0, 9
	s_waitcnt vmcnt(4)
	v_dot8_i32_i4 v15, v94, v73, 0
	s_nop 1
	buffer_load_dwordx2 v[50:51], v192, s[52:55], s0 offen
	v_readlane_b32 s0, v20, 10
	s_lshl_b32 s0, s0, 9
	v_dot8_i32_i4 v17, v94, v75, 0
	v_dot8_i32_i4 v15, v95, v77, v15
	v_dot8_i32_i4 v17, v95, v108, v17
	s_waitcnt vmcnt(4)
	v_dot8_i32_i4 v19, v86, v75, 0
	buffer_load_dwordx2 v[48:49], v192, s[52:55], s0 offen
	v_readlane_b32 s0, v20, 11
	s_lshl_b32 s0, s0, 9
	v_lshl_add_u32 v15, v15, 4, v17
	v_dot8_i32_i4 v17, v86, v73, 0
	v_dot8_i32_i4 v17, v87, v77, v17
	buffer_load_dwordx2 v[54:55], v192, s[52:55], s0 offen
	v_readlane_b32 s0, v20, 12
	s_lshl_b32 s0, s0, 9
	v_dot8_i32_i4 v19, v87, v108, v19
	s_waitcnt vmcnt(5)
	v_dot8_i32_i4 v21, v84, v75, 0
	v_dot8_i32_i4 v21, v85, v108, v21
	v_cvt_f32_i32_e32 v15, v15
	buffer_load_dwordx2 v[42:43], v192, s[52:55], s0 offen
	v_readlane_b32 s0, v20, 13
	s_lshl_b32 s0, s0, 9
	v_lshl_add_u32 v17, v17, 4, v19
	v_dot8_i32_i4 v19, v84, v73, 0
	v_dot8_i32_i4 v19, v85, v77, v19
	buffer_load_dwordx2 v[34:35], v192, s[52:55], s0 offen
	v_readlane_b32 s0, v20, 14
	s_lshl_b32 s0, s0, 9
	v_lshl_add_u32 v19, v19, 4, v21
	s_waitcnt vmcnt(6)
	v_dot8_i32_i4 v21, v90, v73, 0
	buffer_load_dwordx2 v[32:33], v192, s[52:55], s0 offen
	v_readlane_b32 s0, v20, 15
	s_lshl_b32 s0, s0, 9
	v_dot8_i32_i4 v84, v90, v75, 0
	v_dot8_i32_i4 v21, v91, v77, v21
	v_dot8_i32_i4 v84, v91, v108, v84
	buffer_load_dwordx2 v[38:39], v192, s[52:55], s0 offen
	v_readlane_b32 s0, v18, 0
	s_lshl_b32 s0, s0, 9
	v_lshl_add_u32 v21, v21, 4, v84
	s_waitcnt vmcnt(7)
	v_dot8_i32_i4 v84, v78, v73, 0
	v_dot8_i32_i4 v85, v78, v75, 0
	buffer_load_dwordx2 v[96:97], v192, s[52:55], s0 offen
	v_readlane_b32 s0, v18, 1
	s_lshl_b32 s0, s0, 9
	v_dot8_i32_i4 v84, v79, v77, v84
	v_dot8_i32_i4 v85, v79, v108, v85
	v_cvt_f32_i32_e32 v17, v17
	buffer_load_dwordx2 v[88:89], v192, s[52:55], s0 offen
	v_readlane_b32 s0, v18, 2
	s_lshl_b32 s0, s0, 9
	v_lshl_add_u32 v78, v84, 4, v85
	v_cvt_f32_i32_e32 v19, v19
	v_cvt_f32_i32_e32 v21, v21
	buffer_load_dwordx2 v[82:83], v192, s[52:55], s0 offen
	v_readlane_b32 s0, v18, 3
	s_lshl_b32 s0, s0, 9
	v_cvt_f32_i32_e32 v78, v78
	s_waitcnt vmcnt(9)
	v_dot8_i32_i4 v79, v50, v73, 0
	s_nop 0
	buffer_load_dwordx2 v[92:93], v192, s[52:55], s0 offen
	v_readlane_b32 s0, v18, 4
	s_lshl_b32 s0, s0, 9
	v_dot8_i32_i4 v84, v50, v75, 0
	v_dot8_i32_i4 v79, v51, v77, v79
	v_dot8_i32_i4 v84, v51, v108, v84
	buffer_load_dwordx2 v[80:81], v192, s[52:55], s0 offen
	v_readlane_b32 s0, v18, 5
	s_lshl_b32 s0, s0, 9
	v_lshl_add_u32 v50, v79, 4, v84
	s_waitcnt vmcnt(10)
	v_dot8_i32_i4 v51, v48, v73, 0
	v_dot8_i32_i4 v79, v48, v75, 0
	buffer_load_dwordx2 v[52:53], v192, s[52:55], s0 offen
	v_readlane_b32 s0, v18, 6
	s_lshl_b32 s0, s0, 9
	v_dot8_i32_i4 v51, v49, v77, v51
	v_dot8_i32_i4 v79, v49, v108, v79
	s_waitcnt vmcnt(10)
	v_dot8_i32_i4 v49, v54, v73, 0
	buffer_load_dwordx2 v[46:47], v192, s[52:55], s0 offen
	v_readlane_b32 s0, v18, 7
	s_lshl_b32 s0, s0, 9
	v_lshl_add_u32 v48, v51, 4, v79
	v_dot8_i32_i4 v51, v54, v75, 0
	v_dot8_i32_i4 v49, v55, v77, v49
	buffer_load_dwordx2 v[56:57], v192, s[52:55], s0 offen
	v_readlane_b32 s0, v18, 8
	s_lshl_b32 s0, s0, 9
	v_dot8_i32_i4 v51, v55, v108, v51
	s_waitcnt vmcnt(11)
	v_dot8_i32_i4 v54, v42, v75, 0
	v_dot8_i32_i4 v54, v43, v108, v54
	buffer_load_dwordx2 v[44:45], v192, s[52:55], s0 offen
	v_readlane_b32 s0, v18, 9
	s_lshl_b32 s0, s0, 9
	v_lshl_add_u32 v49, v49, 4, v51
	v_dot8_i32_i4 v51, v42, v73, 0
	v_dot8_i32_i4 v51, v43, v77, v51
	buffer_load_dwordx2 v[36:37], v192, s[52:55], s0 offen
	v_readlane_b32 s0, v18, 10
	s_lshl_b32 s0, s0, 9
	v_lshl_add_u32 v42, v51, 4, v54
	s_waitcnt vmcnt(12)
	v_dot8_i32_i4 v43, v34, v73, 0
	buffer_load_dwordx2 v[30:31], v192, s[52:55], s0 offen
	v_readlane_b32 s0, v18, 11
	s_lshl_b32 s0, s0, 9
	v_dot8_i32_i4 v51, v34, v75, 0
	v_dot8_i32_i4 v43, v35, v77, v43
	v_dot8_i32_i4 v51, v35, v108, v51
	buffer_load_dwordx2 v[40:41], v192, s[52:55], s0 offen
	v_readlane_b32 s0, v18, 12
	s_lshl_b32 s0, s0, 9
	v_lshl_add_u32 v34, v43, 4, v51
	s_waitcnt vmcnt(13)
	v_dot8_i32_i4 v35, v32, v73, 0
	v_dot8_i32_i4 v43, v32, v75, 0
	buffer_load_dwordx2 v[28:29], v192, s[52:55], s0 offen
	v_readlane_b32 s0, v18, 13
	s_lshl_b32 s0, s0, 9
	v_dot8_i32_i4 v35, v33, v77, v35
	v_dot8_i32_i4 v43, v33, v108, v43
	s_waitcnt vmcnt(13)
	v_dot8_i32_i4 v33, v38, v73, 0
	buffer_load_dwordx2 v[24:25], v192, s[52:55], s0 offen
	v_readlane_b32 s0, v18, 14
	s_lshl_b32 s0, s0, 9
	v_lshl_add_u32 v32, v35, 4, v43
	v_dot8_i32_i4 v35, v38, v75, 0
	v_dot8_i32_i4 v33, v39, v77, v33
	buffer_load_dwordx2 v[22:23], v192, s[52:55], s0 offen
	v_readlane_b32 s0, v18, 15
	s_lshl_b32 s0, s0, 9
	v_dot8_i32_i4 v35, v39, v108, v35
	v_cvt_f32_i32_e32 v50, v50
	v_cvt_f32_i32_e32 v48, v48
	v_cvt_f32_i32_e32 v49, v49
	buffer_load_dwordx2 v[26:27], v192, s[52:55], s0 offen
	v_lshl_add_u32 v33, v33, 4, v35
	v_cndmask_b32_e64 v35, v9, v5, s[40:41]
	v_cndmask_b32_e64 v5, v5, v9, s[40:41]
	v_cndmask_b32_e64 v9, v13, v11, s[40:41]
	v_cndmask_b32_e64 v11, v11, v13, s[40:41]
	ds_swizzle_b32 v11, v11 offset:swizzle(SWAP,1)
	v_cndmask_b32_e64 v13, v15, v17, s[40:41]
	ds_swizzle_b32 v13, v13 offset:swizzle(SWAP,1)
	v_cvt_f32_i32_e32 v42, v42
	v_cvt_f32_i32_e32 v34, v34
	s_waitcnt lgkmcnt(1)
	v_add_f32_e32 v9, v9, v11
	v_cndmask_b32_e64 v11, v17, v15, s[40:41]
	v_cndmask_b32_e64 v15, v19, v21, s[40:41]
	ds_swizzle_b32 v15, v15 offset:swizzle(SWAP,1)
	v_cndmask_b32_e64 v17, v78, v50, s[40:41]
	s_waitcnt lgkmcnt(1)
	v_add_f32_e32 v11, v11, v13
	v_cndmask_b32_e64 v13, v21, v19, s[40:41]
	ds_swizzle_b32 v17, v17 offset:swizzle(SWAP,1)
	v_cndmask_b32_e64 v19, v48, v49, s[40:41]
	ds_swizzle_b32 v19, v19 offset:swizzle(SWAP,1)
	v_cndmask_b32_e64 v21, v42, v34, s[40:41]
	ds_swizzle_b32 v21, v21 offset:swizzle(SWAP,1)
	v_cvt_f32_i32_e32 v32, v32
	v_cvt_f32_i32_e32 v33, v33
	s_waitcnt lgkmcnt(3)
	v_add_f32_e32 v13, v13, v15
	v_cndmask_b32_e64 v15, v50, v78, s[40:41]
	s_waitcnt lgkmcnt(2)
	v_add_f32_e32 v15, v15, v17
	v_cndmask_b32_e64 v17, v49, v48, s[40:41]
	s_waitcnt lgkmcnt(1)
	v_add_f32_e32 v17, v17, v19
	v_cndmask_b32_e64 v19, v34, v42, s[40:41]
	ds_swizzle_b32 v5, v5 offset:swizzle(SWAP,1)
	s_waitcnt lgkmcnt(1)
	v_add_f32_e32 v19, v19, v21
	v_cndmask_b32_e64 v21, v33, v32, s[40:41]
	v_cndmask_b32_e64 v32, v32, v33, s[40:41]
	ds_swizzle_b32 v32, v32 offset:swizzle(SWAP,1)
	s_waitcnt lgkmcnt(1)
	v_add_f32_e32 v5, v35, v5
	s_waitcnt lgkmcnt(0)
	v_add_f32_e32 v21, v21, v32
	v_cndmask_b32_e64 v32, v9, v5, s[42:43]
	v_cndmask_b32_e64 v5, v5, v9, s[42:43]
	v_cndmask_b32_e64 v9, v13, v11, s[42:43]
	v_cndmask_b32_e64 v11, v11, v13, s[42:43]
	ds_swizzle_b32 v11, v11 offset:swizzle(SWAP,2)
	v_cndmask_b32_e64 v13, v15, v17, s[42:43]
	ds_swizzle_b32 v13, v13 offset:swizzle(SWAP,2)
	ds_swizzle_b32 v5, v5 offset:swizzle(SWAP,2)
	s_waitcnt lgkmcnt(2)
	v_add_f32_e32 v9, v9, v11
	v_cndmask_b32_e64 v11, v17, v15, s[42:43]
	v_cndmask_b32_e64 v15, v19, v21, s[42:43]
	ds_swizzle_b32 v15, v15 offset:swizzle(SWAP,2)
	s_waitcnt lgkmcnt(2)
	v_add_f32_e32 v11, v11, v13
	v_cndmask_b32_e64 v13, v21, v19, s[42:43]
	s_waitcnt lgkmcnt(1)
	v_add_f32_e32 v5, v32, v5
	s_waitcnt lgkmcnt(0)
	v_add_f32_e32 v13, v13, v15
	v_cndmask_b32_e64 v15, v9, v5, s[44:45]
	v_cndmask_b32_e64 v5, v5, v9, s[44:45]
	v_cndmask_b32_e64 v9, v13, v11, s[44:45]
	v_cndmask_b32_e64 v11, v11, v13, s[44:45]
	ds_swizzle_b32 v5, v5 offset:swizzle(SWAP,4)
	ds_swizzle_b32 v11, v11 offset:swizzle(SWAP,4)
	s_waitcnt lgkmcnt(1)
	v_add_f32_e32 v5, v15, v5
	s_waitcnt lgkmcnt(0)
	v_add_f32_e32 v9, v9, v11
	v_cndmask_b32_e64 v11, v9, v5, s[46:47]
	v_cndmask_b32_e64 v5, v5, v9, s[46:47]
	ds_swizzle_b32 v5, v5 offset:swizzle(SWAP,8)
	s_waitcnt lgkmcnt(0)
	v_add_f32_e32 v5, v11, v5
	ds_swizzle_b32 v9, v5 offset:swizzle(SWAP,16)
	s_waitcnt lgkmcnt(0)
	v_add_f32_e32 v5, v5, v9
	ds_bpermute_b32 v9, v0, v5
	s_and_saveexec_b64 s[0:1], s[48:49]
	s_cbranch_execz .LBB0_541
	v_ashrrev_i32_e32 v21, 31, v20
	v_lshlrev_b64 v[20:21], 2, v[20:21]
	v_lshl_add_u64 v[32:33], s[8:9], 0, v[20:21]
	global_load_dword v11, v[32:33], off
	v_lshl_add_u64 v[20:21], s[10:11], 0, v[20:21]
	global_load_dword v13, v[6:7], off
	global_load_dword v15, v[20:21], off
	s_waitcnt lgkmcnt(0)
	v_add_f32_e32 v5, v5, v9
	s_waitcnt vmcnt(2)
	v_mul_f32_e32 v5, v5, v11
	v_mul_f32_e32 v5, v3, v5
	v_mul_f32_e32 v11, 0x3d372713, v5
	v_mul_f32_e32 v11, v5, v11
	v_mul_f32_e32 v9, 0.5, v5
	v_fmac_f32_e32 v5, v5, v11
	v_mul_f32_e32 v5, 0x3f4c422a, v5
	v_add_f32_e32 v5, v5, v5
	v_mul_f32_e32 v5, 0x3fb8aa3b, v5
	v_exp_f32_e32 v5, v5
	s_nop 0
	v_add_f32_e32 v5, 1.0, v5
	v_rcp_f32_e32 v5, v5
	s_nop 0
	v_fma_f32 v5, v5, -2.0, 1.0
	v_add_f32_e32 v5, 1.0, v5
	v_mul_f32_e32 v5, v9, v5
	s_waitcnt vmcnt(1)
	v_mul_f32_e32 v5, v13, v5
	s_waitcnt vmcnt(0)
	v_mul_f32_e32 v5, v15, v5
	ds_write_b32 v109, v5
.LBB0_541:
	s_or_b64 exec, exec, s[0:1]
	v_readlane_b32 s0, v16, 0
	s_lshl_b32 s0, s0, 9
	s_waitcnt lgkmcnt(0)
	s_waitcnt vmcnt(15)
	v_dot8_i32_i4 v5, v96, v73, 0
	v_dot8_i32_i4 v9, v96, v75, 0
	buffer_load_dwordx2 v[102:103], v192, s[52:55], s0 offen
	v_readlane_b32 s0, v16, 1
	s_lshl_b32 s0, s0, 9
	v_dot8_i32_i4 v5, v97, v77, v5
	v_dot8_i32_i4 v9, v97, v108, v9
	s_waitcnt vmcnt(15)
	v_dot8_i32_i4 v11, v88, v75, 0
	buffer_load_dwordx2 v[98:99], v192, s[52:55], s0 offen
	v_readlane_b32 s0, v16, 2
	s_lshl_b32 s0, s0, 9
	v_lshl_add_u32 v5, v5, 4, v9
	v_dot8_i32_i4 v9, v88, v73, 0
	v_dot8_i32_i4 v9, v89, v77, v9
	buffer_load_dwordx2 v[94:95], v192, s[52:55], s0 offen
	v_readlane_b32 s0, v16, 3
	s_lshl_b32 s0, s0, 9
	v_dot8_i32_i4 v11, v89, v108, v11
	s_waitcnt vmcnt(16)
	v_dot8_i32_i4 v13, v82, v75, 0
	v_dot8_i32_i4 v13, v83, v108, v13
	buffer_load_dwordx2 v[100:101], v192, s[52:55], s0 offen
	v_readlane_b32 s0, v16, 4
	s_lshl_b32 s0, s0, 9
	v_lshl_add_u32 v9, v9, 4, v11
	v_dot8_i32_i4 v11, v82, v73, 0
	v_dot8_i32_i4 v11, v83, v77, v11
	buffer_load_dwordx2 v[90:91], v192, s[52:55], s0 offen
	v_readlane_b32 s0, v16, 5
	s_lshl_b32 s0, s0, 9
	v_lshl_add_u32 v11, v11, 4, v13
	s_waitcnt vmcnt(17)
	v_dot8_i32_i4 v13, v92, v73, 0
	buffer_load_dwordx2 v[84:85], v192, s[52:55], s0 offen
	v_readlane_b32 s0, v16, 6
	s_lshl_b32 s0, s0, 9
	v_dot8_i32_i4 v15, v92, v75, 0
	v_dot8_i32_i4 v13, v93, v77, v13
	v_dot8_i32_i4 v15, v93, v108, v15
	buffer_load_dwordx2 v[78:79], v192, s[52:55], s0 offen
	v_readlane_b32 s0, v16, 7
	s_lshl_b32 s0, s0, 9
	v_lshl_add_u32 v13, v13, 4, v15
	s_waitcnt vmcnt(18)
	v_dot8_i32_i4 v15, v80, v73, 0
	v_dot8_i32_i4 v17, v80, v75, 0
	buffer_load_dwordx2 v[86:87], v192, s[52:55], s0 offen
	v_readlane_b32 s0, v16, 8
	s_lshl_b32 s0, s0, 9
	v_dot8_i32_i4 v15, v81, v77, v15
	v_dot8_i32_i4 v17, v81, v108, v17
	s_waitcnt vmcnt(18)
	v_dot8_i32_i4 v19, v52, v75, 0
	buffer_load_dwordx2 v[54:55], v192, s[52:55], s0 offen
	v_readlane_b32 s0, v16, 9
	s_lshl_b32 s0, s0, 9
	v_lshl_add_u32 v15, v15, 4, v17
	v_dot8_i32_i4 v17, v52, v73, 0
	v_dot8_i32_i4 v17, v53, v77, v17
	buffer_load_dwordx2 v[48:49], v192, s[52:55], s0 offen
	v_readlane_b32 s0, v16, 10
	s_lshl_b32 s0, s0, 9
	v_dot8_i32_i4 v19, v53, v108, v19
	s_waitcnt vmcnt(19)
	v_dot8_i32_i4 v52, v46, v75, 0
	v_dot8_i32_i4 v52, v47, v108, v52
	buffer_load_dwordx2 v[42:43], v192, s[52:55], s0 offen
	v_readlane_b32 s0, v16, 11
	s_lshl_b32 s0, s0, 9
	v_lshl_add_u32 v17, v17, 4, v19
	v_dot8_i32_i4 v19, v46, v73, 0
	v_dot8_i32_i4 v19, v47, v77, v19
	buffer_load_dwordx2 v[50:51], v192, s[52:55], s0 offen
	v_readlane_b32 s0, v16, 12
	s_lshl_b32 s0, s0, 9
	s_waitcnt vmcnt(20)
	v_dot8_i32_i4 v46, v56, v73, 0
	v_dot8_i32_i4 v47, v56, v75, 0
	buffer_load_dwordx2 v[38:39], v192, s[52:55], s0 offen
	v_readlane_b32 s0, v16, 13
	s_lshl_b32 s0, s0, 9
	v_dot8_i32_i4 v46, v57, v77, v46
	v_dot8_i32_i4 v47, v57, v108, v47
	v_lshl_add_u32 v19, v19, 4, v52
	buffer_load_dwordx2 v[32:33], v192, s[52:55], s0 offen
	v_readlane_b32 s0, v16, 14
	s_lshl_b32 s0, s0, 9
	v_lshl_add_u32 v46, v46, 4, v47
	s_waitcnt vmcnt(21)
	v_dot8_i32_i4 v47, v44, v73, 0
	v_dot8_i32_i4 v52, v44, v75, 0
	buffer_load_dwordx2 v[20:21], v192, s[52:55], s0 offen
	v_readlane_b32 s0, v16, 15
	s_lshl_b32 s0, s0, 9
	v_dot8_i32_i4 v47, v45, v77, v47
	v_dot8_i32_i4 v52, v45, v108, v52
	s_waitcnt vmcnt(21)
	v_dot8_i32_i4 v45, v36, v73, 0
	buffer_load_dwordx2 v[34:35], v192, s[52:55], s0 offen
	v_lshl_add_u32 v44, v47, 4, v52
	v_dot8_i32_i4 v47, v36, v75, 0
	v_dot8_i32_i4 v45, v37, v77, v45
	v_dot8_i32_i4 v47, v37, v108, v47
	s_waitcnt vmcnt(21)
	v_dot8_i32_i4 v37, v30, v73, 0
	v_dot8_i32_i4 v37, v31, v77, v37
	v_lshl_add_u32 v36, v45, 4, v47
	v_dot8_i32_i4 v45, v30, v75, 0
	v_dot8_i32_i4 v45, v31, v108, v45
	s_waitcnt vmcnt(20)
	v_dot8_i32_i4 v31, v40, v73, 0
	v_dot8_i32_i4 v31, v41, v77, v31
	v_lshl_add_u32 v30, v37, 4, v45
	v_dot8_i32_i4 v37, v40, v75, 0
	v_dot8_i32_i4 v37, v41, v108, v37
	s_waitcnt vmcnt(19)
	v_dot8_i32_i4 v40, v28, v75, 0
	v_dot8_i32_i4 v40, v29, v108, v40
	v_lshl_add_u32 v31, v31, 4, v37
	v_dot8_i32_i4 v37, v28, v73, 0
	v_dot8_i32_i4 v37, v29, v77, v37
	s_waitcnt vmcnt(18)
	v_dot8_i32_i4 v29, v24, v73, 0
	v_dot8_i32_i4 v29, v25, v77, v29
	v_lshl_add_u32 v28, v37, 4, v40
	v_dot8_i32_i4 v37, v24, v75, 0
	v_dot8_i32_i4 v37, v25, v108, v37
	s_waitcnt vmcnt(17)
	v_dot8_i32_i4 v25, v22, v73, 0
	v_cvt_f32_i32_e32 v5, v5
	v_lshl_add_u32 v24, v29, 4, v37
	v_dot8_i32_i4 v29, v22, v75, 0
	v_cvt_f32_i32_e32 v9, v9
	v_cvt_f32_i32_e32 v11, v11
	v_cvt_f32_i32_e32 v13, v13
	v_dot8_i32_i4 v25, v23, v77, v25
	v_dot8_i32_i4 v29, v23, v108, v29
	v_cvt_f32_i32_e32 v15, v15
	v_cvt_f32_i32_e32 v17, v17
	s_nop 0
	v_lshl_add_u32 v22, v25, 4, v29
	s_waitcnt vmcnt(16)
	v_dot8_i32_i4 v23, v26, v73, 0
	v_dot8_i32_i4 v25, v26, v75, 0
	v_dot8_i32_i4 v23, v27, v77, v23
	v_dot8_i32_i4 v25, v27, v108, v25
	v_cvt_f32_i32_e32 v19, v19
	v_cvt_f32_i32_e32 v46, v46
	v_cvt_f32_i32_e32 v44, v44
	v_lshl_add_u32 v23, v23, 4, v25
	v_cndmask_b32_e64 v25, v9, v5, s[40:41]
	v_cndmask_b32_e64 v5, v5, v9, s[40:41]
	v_cndmask_b32_e64 v9, v13, v11, s[40:41]
	v_cndmask_b32_e64 v11, v11, v13, s[40:41]
	ds_swizzle_b32 v11, v11 offset:swizzle(SWAP,1)
	v_cndmask_b32_e64 v13, v15, v17, s[40:41]
	v_cvt_f32_i32_e32 v36, v36
	ds_swizzle_b32 v13, v13 offset:swizzle(SWAP,1)
	v_cvt_f32_i32_e32 v30, v30
	v_cvt_f32_i32_e32 v31, v31
	s_waitcnt lgkmcnt(1)
	v_add_f32_e32 v9, v9, v11
	v_cndmask_b32_e64 v11, v17, v15, s[40:41]
	v_cndmask_b32_e64 v15, v19, v46, s[40:41]
	ds_swizzle_b32 v15, v15 offset:swizzle(SWAP,1)
	v_cndmask_b32_e64 v17, v44, v36, s[40:41]
	s_waitcnt lgkmcnt(1)
	v_add_f32_e32 v11, v11, v13
	v_cndmask_b32_e64 v13, v46, v19, s[40:41]
	ds_swizzle_b32 v17, v17 offset:swizzle(SWAP,1)
	v_cndmask_b32_e64 v19, v30, v31, s[40:41]
	ds_swizzle_b32 v19, v19 offset:swizzle(SWAP,1)
	v_cvt_f32_i32_e32 v28, v28
	v_cvt_f32_i32_e32 v24, v24
	s_waitcnt lgkmcnt(2)
	v_add_f32_e32 v13, v13, v15
	v_cndmask_b32_e64 v15, v36, v44, s[40:41]
	s_waitcnt lgkmcnt(1)
	v_add_f32_e32 v15, v15, v17
	v_cndmask_b32_e64 v17, v31, v30, s[40:41]
	s_waitcnt lgkmcnt(0)
	v_add_f32_e32 v17, v17, v19
	v_cndmask_b32_e64 v19, v24, v28, s[40:41]
	v_cndmask_b32_e64 v24, v28, v24, s[40:41]
	ds_swizzle_b32 v5, v5 offset:swizzle(SWAP,1)
	ds_swizzle_b32 v24, v24 offset:swizzle(SWAP,1)
	v_cvt_f32_i32_e32 v22, v22
	v_cvt_f32_i32_e32 v23, v23
	s_waitcnt lgkmcnt(1)
	v_add_f32_e32 v5, v25, v5
	s_waitcnt lgkmcnt(0)
	v_add_f32_e32 v19, v19, v24
	v_cndmask_b32_e64 v24, v23, v22, s[40:41]
	v_cndmask_b32_e64 v22, v22, v23, s[40:41]
	ds_swizzle_b32 v22, v22 offset:swizzle(SWAP,1)
	v_cndmask_b32_e64 v23, v9, v5, s[42:43]
	v_cndmask_b32_e64 v5, v5, v9, s[42:43]
	v_cndmask_b32_e64 v9, v13, v11, s[42:43]
	v_cndmask_b32_e64 v11, v11, v13, s[42:43]
	ds_swizzle_b32 v11, v11 offset:swizzle(SWAP,2)
	s_waitcnt lgkmcnt(1)
	v_add_f32_e32 v22, v24, v22
	v_cndmask_b32_e64 v13, v15, v17, s[42:43]
	ds_swizzle_b32 v13, v13 offset:swizzle(SWAP,2)
	ds_swizzle_b32 v5, v5 offset:swizzle(SWAP,2)
	s_waitcnt lgkmcnt(2)
	v_add_f32_e32 v9, v9, v11
	v_cndmask_b32_e64 v11, v17, v15, s[42:43]
	v_cndmask_b32_e64 v15, v19, v22, s[42:43]
	ds_swizzle_b32 v15, v15 offset:swizzle(SWAP,2)
	s_waitcnt lgkmcnt(2)
	v_add_f32_e32 v11, v11, v13
	v_cndmask_b32_e64 v13, v22, v19, s[42:43]
	s_waitcnt lgkmcnt(1)
	v_add_f32_e32 v5, v23, v5
	s_waitcnt lgkmcnt(0)
	v_add_f32_e32 v13, v13, v15
	v_cndmask_b32_e64 v15, v9, v5, s[44:45]
	v_cndmask_b32_e64 v5, v5, v9, s[44:45]
	v_cndmask_b32_e64 v9, v13, v11, s[44:45]
	v_cndmask_b32_e64 v11, v11, v13, s[44:45]
	ds_swizzle_b32 v5, v5 offset:swizzle(SWAP,4)
	ds_swizzle_b32 v11, v11 offset:swizzle(SWAP,4)
	s_waitcnt lgkmcnt(1)
	v_add_f32_e32 v5, v15, v5
	s_waitcnt lgkmcnt(0)
	v_add_f32_e32 v9, v9, v11
	v_cndmask_b32_e64 v11, v9, v5, s[46:47]
	v_cndmask_b32_e64 v5, v5, v9, s[46:47]
	ds_swizzle_b32 v5, v5 offset:swizzle(SWAP,8)
	s_waitcnt lgkmcnt(0)
	v_add_f32_e32 v5, v11, v5
	ds_swizzle_b32 v9, v5 offset:swizzle(SWAP,16)
	s_waitcnt lgkmcnt(0)
	v_add_f32_e32 v5, v5, v9
	ds_bpermute_b32 v9, v0, v5
	s_and_saveexec_b64 s[0:1], s[48:49]
	s_cbranch_execz .LBB0_543
	v_ashrrev_i32_e32 v19, 31, v18
	v_lshlrev_b64 v[18:19], 2, v[18:19]
	v_lshl_add_u64 v[22:23], s[8:9], 0, v[18:19]
	global_load_dword v11, v[22:23], off
	v_lshl_add_u64 v[18:19], s[10:11], 0, v[18:19]
	global_load_dword v13, v[6:7], off offset:64
	global_load_dword v15, v[18:19], off
	s_waitcnt lgkmcnt(0)
	v_add_f32_e32 v5, v5, v9
	s_waitcnt vmcnt(2)
	v_mul_f32_e32 v5, v5, v11
	v_mul_f32_e32 v5, v3, v5
	v_mul_f32_e32 v11, 0x3d372713, v5
	v_mul_f32_e32 v11, v5, v11
	v_mul_f32_e32 v9, 0.5, v5
	v_fmac_f32_e32 v5, v5, v11
	v_mul_f32_e32 v5, 0x3f4c422a, v5
	v_add_f32_e32 v5, v5, v5
	v_mul_f32_e32 v5, 0x3fb8aa3b, v5
	v_exp_f32_e32 v5, v5
	s_nop 0
	v_add_f32_e32 v5, 1.0, v5
	v_rcp_f32_e32 v5, v5
	s_nop 0
	v_fma_f32 v5, v5, -2.0, 1.0
	v_add_f32_e32 v5, 1.0, v5
	v_mul_f32_e32 v5, v9, v5
	s_waitcnt vmcnt(1)
	v_mul_f32_e32 v5, v13, v5
	s_waitcnt vmcnt(0)
	v_mul_f32_e32 v5, v15, v5
	ds_write_b32 v109, v5 offset:64
.LBB0_543:
	s_or_b64 exec, exec, s[0:1]
	v_readlane_b32 s0, v14, 0
	s_lshl_b32 s0, s0, 9
	s_waitcnt lgkmcnt(0)
	s_waitcnt vmcnt(15)
	v_dot8_i32_i4 v5, v102, v73, 0
	v_dot8_i32_i4 v9, v102, v75, 0
	buffer_load_dwordx2 v[96:97], v192, s[52:55], s0 offen
	v_readlane_b32 s0, v14, 1
	s_lshl_b32 s0, s0, 9
	v_dot8_i32_i4 v5, v103, v77, v5
	v_dot8_i32_i4 v9, v103, v108, v9
	s_waitcnt vmcnt(15)
	v_dot8_i32_i4 v11, v98, v75, 0
	buffer_load_dwordx2 v[104:105], v192, s[52:55], s0 offen
	v_readlane_b32 s0, v14, 2
	s_lshl_b32 s0, s0, 9
	v_lshl_add_u32 v5, v5, 4, v9
	v_dot8_i32_i4 v9, v98, v73, 0
	v_dot8_i32_i4 v9, v99, v77, v9
	buffer_load_dwordx2 v[92:93], v192, s[52:55], s0 offen
	v_readlane_b32 s0, v14, 3
	s_lshl_b32 s0, s0, 9
	v_dot8_i32_i4 v11, v99, v108, v11
	s_waitcnt vmcnt(16)
	v_dot8_i32_i4 v13, v94, v75, 0
	v_dot8_i32_i4 v13, v95, v108, v13
	buffer_load_dwordx2 v[106:107], v192, s[52:55], s0 offen
	v_readlane_b32 s0, v14, 4
	s_lshl_b32 s0, s0, 9
	v_lshl_add_u32 v9, v9, 4, v11
	v_dot8_i32_i4 v11, v94, v73, 0
	v_dot8_i32_i4 v11, v95, v77, v11
	buffer_load_dwordx2 v[88:89], v192, s[52:55], s0 offen
	v_readlane_b32 s0, v14, 5
	s_lshl_b32 s0, s0, 9
	v_lshl_add_u32 v11, v11, 4, v13
	s_waitcnt vmcnt(17)
	v_dot8_i32_i4 v13, v100, v73, 0
	buffer_load_dwordx2 v[80:81], v192, s[52:55], s0 offen
	v_readlane_b32 s0, v14, 6
	s_lshl_b32 s0, s0, 9
	v_dot8_i32_i4 v15, v100, v75, 0
	v_dot8_i32_i4 v13, v101, v77, v13
	v_dot8_i32_i4 v15, v101, v108, v15
	buffer_load_dwordx2 v[56:57], v192, s[52:55], s0 offen
	v_readlane_b32 s0, v14, 7
	s_lshl_b32 s0, s0, 9
	v_lshl_add_u32 v13, v13, 4, v15
	s_waitcnt vmcnt(18)
	v_dot8_i32_i4 v15, v90, v73, 0
	v_dot8_i32_i4 v17, v90, v75, 0
	buffer_load_dwordx2 v[82:83], v192, s[52:55], s0 offen
	v_readlane_b32 s0, v14, 8
	s_lshl_b32 s0, s0, 9
	v_dot8_i32_i4 v15, v91, v77, v15
	v_dot8_i32_i4 v17, v91, v108, v17
	s_waitcnt vmcnt(18)
	v_dot8_i32_i4 v22, v84, v75, 0
	buffer_load_dwordx2 v[52:53], v192, s[52:55], s0 offen
	v_readlane_b32 s0, v14, 9
	s_lshl_b32 s0, s0, 9
	v_lshl_add_u32 v15, v15, 4, v17
	v_dot8_i32_i4 v17, v84, v73, 0
	v_dot8_i32_i4 v17, v85, v77, v17
	buffer_load_dwordx2 v[44:45], v192, s[52:55], s0 offen
	v_readlane_b32 s0, v14, 10
	s_lshl_b32 s0, s0, 9
	v_dot8_i32_i4 v22, v85, v108, v22
	s_waitcnt vmcnt(19)
	v_dot8_i32_i4 v23, v78, v75, 0
	v_dot8_i32_i4 v23, v79, v108, v23
	buffer_load_dwordx2 v[40:41], v192, s[52:55], s0 offen
	v_readlane_b32 s0, v14, 11
	s_lshl_b32 s0, s0, 9
	v_lshl_add_u32 v17, v17, 4, v22
	v_dot8_i32_i4 v22, v78, v73, 0
	v_dot8_i32_i4 v22, v79, v77, v22
	buffer_load_dwordx2 v[46:47], v192, s[52:55], s0 offen
	v_readlane_b32 s0, v14, 12
	s_lshl_b32 s0, s0, 9
	v_lshl_add_u32 v22, v22, 4, v23
	s_waitcnt vmcnt(20)
	v_dot8_i32_i4 v23, v86, v73, 0
	buffer_load_dwordx2 v[36:37], v192, s[52:55], s0 offen
	v_readlane_b32 s0, v14, 13
	s_lshl_b32 s0, s0, 9
	v_dot8_i32_i4 v26, v86, v75, 0
	v_dot8_i32_i4 v23, v87, v77, v23
	v_dot8_i32_i4 v26, v87, v108, v26
	buffer_load_dwordx2 v[24:25], v192, s[52:55], s0 offen
	v_readlane_b32 s0, v14, 14
	s_lshl_b32 s0, s0, 9
	v_lshl_add_u32 v23, v23, 4, v26
	s_waitcnt vmcnt(21)
	v_dot8_i32_i4 v26, v54, v73, 0
	v_dot8_i32_i4 v27, v54, v75, 0
	buffer_load_dwordx2 v[18:19], v192, s[52:55], s0 offen
	v_readlane_b32 s0, v14, 15
	s_lshl_b32 s0, s0, 9
	v_dot8_i32_i4 v26, v55, v77, v26
	v_dot8_i32_i4 v27, v55, v108, v27
	s_waitcnt vmcnt(21)
	v_dot8_i32_i4 v30, v48, v75, 0
	buffer_load_dwordx2 v[28:29], v192, s[52:55], s0 offen
	v_lshl_add_u32 v26, v26, 4, v27
	v_dot8_i32_i4 v27, v48, v73, 0
	v_dot8_i32_i4 v27, v49, v77, v27
	v_dot8_i32_i4 v30, v49, v108, v30
	s_waitcnt vmcnt(21)
	v_dot8_i32_i4 v31, v42, v75, 0
	v_dot8_i32_i4 v31, v43, v108, v31
	v_lshl_add_u32 v27, v27, 4, v30
	v_dot8_i32_i4 v30, v42, v73, 0
	v_dot8_i32_i4 v30, v43, v77, v30
	s_waitcnt vmcnt(20)
	v_dot8_i32_i4 v42, v50, v75, 0
	v_dot8_i32_i4 v42, v51, v108, v42
	v_lshl_add_u32 v30, v30, 4, v31
	v_dot8_i32_i4 v31, v50, v73, 0
	v_dot8_i32_i4 v31, v51, v77, v31
	s_waitcnt vmcnt(19)
	v_dot8_i32_i4 v43, v38, v75, 0
	v_dot8_i32_i4 v43, v39, v108, v43
	v_lshl_add_u32 v31, v31, 4, v42
	v_dot8_i32_i4 v42, v38, v73, 0
	v_dot8_i32_i4 v42, v39, v77, v42
	s_waitcnt vmcnt(18)
	v_dot8_i32_i4 v39, v32, v73, 0
	v_dot8_i32_i4 v39, v33, v77, v39
	v_lshl_add_u32 v38, v42, 4, v43
	v_dot8_i32_i4 v42, v32, v75, 0
	v_dot8_i32_i4 v42, v33, v108, v42
	s_waitcnt vmcnt(17)
	v_dot8_i32_i4 v33, v20, v73, 0
	v_cvt_f32_i32_e32 v5, v5
	v_lshl_add_u32 v32, v39, 4, v42
	v_dot8_i32_i4 v39, v20, v75, 0
	v_cvt_f32_i32_e32 v9, v9
	v_cvt_f32_i32_e32 v11, v11
	v_cvt_f32_i32_e32 v13, v13
	v_dot8_i32_i4 v33, v21, v77, v33
	v_dot8_i32_i4 v39, v21, v108, v39
	v_cvt_f32_i32_e32 v15, v15
	v_cvt_f32_i32_e32 v17, v17
	s_nop 0
	v_lshl_add_u32 v20, v33, 4, v39
	s_waitcnt vmcnt(16)
	v_dot8_i32_i4 v21, v34, v73, 0
	v_dot8_i32_i4 v33, v34, v75, 0
	v_dot8_i32_i4 v21, v35, v77, v21
	v_dot8_i32_i4 v33, v35, v108, v33
	v_cvt_f32_i32_e32 v22, v22
	v_cvt_f32_i32_e32 v23, v23
	v_cvt_f32_i32_e32 v26, v26
	v_lshl_add_u32 v21, v21, 4, v33
	v_cndmask_b32_e64 v33, v9, v5, s[40:41]
	v_cndmask_b32_e64 v5, v5, v9, s[40:41]
	v_cndmask_b32_e64 v9, v13, v11, s[40:41]
	v_cndmask_b32_e64 v11, v11, v13, s[40:41]
	ds_swizzle_b32 v11, v11 offset:swizzle(SWAP,1)
	v_cndmask_b32_e64 v13, v15, v17, s[40:41]
	v_cvt_f32_i32_e32 v27, v27
	ds_swizzle_b32 v13, v13 offset:swizzle(SWAP,1)
	v_cvt_f32_i32_e32 v30, v30
	v_cvt_f32_i32_e32 v31, v31
	v_cvt_f32_i32_e32 v38, v38
	v_cvt_f32_i32_e32 v32, v32
	s_waitcnt lgkmcnt(1)
	v_add_f32_e32 v9, v9, v11
	v_cndmask_b32_e64 v11, v17, v15, s[40:41]
	v_cndmask_b32_e64 v15, v22, v23, s[40:41]
	ds_swizzle_b32 v15, v15 offset:swizzle(SWAP,1)
	v_cndmask_b32_e64 v17, v26, v27, s[40:41]
	s_waitcnt lgkmcnt(1)
	v_add_f32_e32 v11, v11, v13
	v_cndmask_b32_e64 v13, v23, v22, s[40:41]
	ds_swizzle_b32 v17, v17 offset:swizzle(SWAP,1)
	v_cndmask_b32_e64 v22, v30, v31, s[40:41]
	ds_swizzle_b32 v22, v22 offset:swizzle(SWAP,1)
	v_cndmask_b32_e64 v23, v38, v32, s[40:41]
	ds_swizzle_b32 v5, v5 offset:swizzle(SWAP,1)
	ds_swizzle_b32 v23, v23 offset:swizzle(SWAP,1)
	v_cvt_f32_i32_e32 v20, v20
	v_cvt_f32_i32_e32 v21, v21
	s_waitcnt lgkmcnt(4)
	v_add_f32_e32 v13, v13, v15
	v_cndmask_b32_e64 v15, v27, v26, s[40:41]
	s_waitcnt lgkmcnt(3)
	v_add_f32_e32 v15, v15, v17
	v_cndmask_b32_e64 v17, v31, v30, s[40:41]
	s_waitcnt lgkmcnt(2)
	v_add_f32_e32 v17, v17, v22
	v_cndmask_b32_e64 v22, v32, v38, s[40:41]
	s_waitcnt lgkmcnt(1)
	v_add_f32_e32 v5, v33, v5
	s_waitcnt lgkmcnt(0)
	v_add_f32_e32 v22, v22, v23
	v_cndmask_b32_e64 v23, v21, v20, s[40:41]
	v_cndmask_b32_e64 v20, v20, v21, s[40:41]
	ds_swizzle_b32 v20, v20 offset:swizzle(SWAP,1)
	v_cndmask_b32_e64 v21, v9, v5, s[42:43]
	v_cndmask_b32_e64 v5, v5, v9, s[42:43]
	v_cndmask_b32_e64 v9, v13, v11, s[42:43]
	v_cndmask_b32_e64 v11, v11, v13, s[42:43]
	ds_swizzle_b32 v11, v11 offset:swizzle(SWAP,2)
	s_waitcnt lgkmcnt(1)
	v_add_f32_e32 v20, v23, v20
	v_cndmask_b32_e64 v13, v15, v17, s[42:43]
	ds_swizzle_b32 v13, v13 offset:swizzle(SWAP,2)
	ds_swizzle_b32 v5, v5 offset:swizzle(SWAP,2)
	s_waitcnt lgkmcnt(2)
	v_add_f32_e32 v9, v9, v11
	v_cndmask_b32_e64 v11, v17, v15, s[42:43]
	v_cndmask_b32_e64 v15, v22, v20, s[42:43]
	ds_swizzle_b32 v15, v15 offset:swizzle(SWAP,2)
	s_waitcnt lgkmcnt(2)
	v_add_f32_e32 v11, v11, v13
	v_cndmask_b32_e64 v13, v20, v22, s[42:43]
	s_waitcnt lgkmcnt(1)
	v_add_f32_e32 v5, v21, v5
	s_waitcnt lgkmcnt(0)
	v_add_f32_e32 v13, v13, v15
	v_cndmask_b32_e64 v15, v9, v5, s[44:45]
	v_cndmask_b32_e64 v5, v5, v9, s[44:45]
	v_cndmask_b32_e64 v9, v13, v11, s[44:45]
	v_cndmask_b32_e64 v11, v11, v13, s[44:45]
	ds_swizzle_b32 v5, v5 offset:swizzle(SWAP,4)
	ds_swizzle_b32 v11, v11 offset:swizzle(SWAP,4)
	s_waitcnt lgkmcnt(1)
	v_add_f32_e32 v5, v15, v5
	s_waitcnt lgkmcnt(0)
	v_add_f32_e32 v9, v9, v11
	v_cndmask_b32_e64 v11, v9, v5, s[46:47]
	v_cndmask_b32_e64 v5, v5, v9, s[46:47]
	ds_swizzle_b32 v5, v5 offset:swizzle(SWAP,8)
	s_waitcnt lgkmcnt(0)
	v_add_f32_e32 v5, v11, v5
	ds_swizzle_b32 v9, v5 offset:swizzle(SWAP,16)
	s_waitcnt lgkmcnt(0)
	v_add_f32_e32 v5, v5, v9
	ds_bpermute_b32 v9, v0, v5
	s_and_saveexec_b64 s[0:1], s[48:49]
	s_cbranch_execz .LBB0_545
	v_ashrrev_i32_e32 v17, 31, v16
	v_lshlrev_b64 v[16:17], 2, v[16:17]
	v_lshl_add_u64 v[20:21], s[8:9], 0, v[16:17]
	global_load_dword v11, v[20:21], off
	v_lshl_add_u64 v[16:17], s[10:11], 0, v[16:17]
	global_load_dword v13, v[6:7], off offset:128
	global_load_dword v15, v[16:17], off
	s_waitcnt lgkmcnt(0)
	v_add_f32_e32 v5, v5, v9
	s_waitcnt vmcnt(2)
	v_mul_f32_e32 v5, v5, v11
	v_mul_f32_e32 v5, v3, v5
	v_mul_f32_e32 v11, 0x3d372713, v5
	v_mul_f32_e32 v11, v5, v11
	v_mul_f32_e32 v9, 0.5, v5
	v_fmac_f32_e32 v5, v5, v11
	v_mul_f32_e32 v5, 0x3f4c422a, v5
	v_add_f32_e32 v5, v5, v5
	v_mul_f32_e32 v5, 0x3fb8aa3b, v5
	v_exp_f32_e32 v5, v5
	s_nop 0
	v_add_f32_e32 v5, 1.0, v5
	v_rcp_f32_e32 v5, v5
	s_nop 0
	v_fma_f32 v5, v5, -2.0, 1.0
	v_add_f32_e32 v5, 1.0, v5
	v_mul_f32_e32 v5, v9, v5
	s_waitcnt vmcnt(1)
	v_mul_f32_e32 v5, v13, v5
	s_waitcnt vmcnt(0)
	v_mul_f32_e32 v5, v15, v5
	ds_write_b32 v109, v5 offset:128
.LBB0_545:
	s_or_b64 exec, exec, s[0:1]
	v_readlane_b32 s0, v12, 0
	s_lshl_b32 s0, s0, 9
	s_waitcnt lgkmcnt(0)
	s_waitcnt vmcnt(15)
	v_dot8_i32_i4 v5, v96, v73, 0
	v_dot8_i32_i4 v9, v96, v75, 0
	buffer_load_dwordx2 v[94:95], v192, s[52:55], s0 offen
	v_readlane_b32 s0, v12, 1
	s_lshl_b32 s0, s0, 9
	v_dot8_i32_i4 v5, v97, v77, v5
	v_dot8_i32_i4 v9, v97, v108, v9
	s_waitcnt vmcnt(15)
	v_dot8_i32_i4 v11, v104, v75, 0
	buffer_load_dwordx2 v[86:87], v192, s[52:55], s0 offen
	v_readlane_b32 s0, v12, 2
	s_lshl_b32 s0, s0, 9
	v_lshl_add_u32 v5, v5, 4, v9
	v_dot8_i32_i4 v9, v104, v73, 0
	v_dot8_i32_i4 v9, v105, v77, v9
	buffer_load_dwordx2 v[84:85], v192, s[52:55], s0 offen
	v_readlane_b32 s0, v12, 3
	s_lshl_b32 s0, s0, 9
	v_dot8_i32_i4 v11, v105, v108, v11
	s_waitcnt vmcnt(16)
	v_dot8_i32_i4 v13, v92, v75, 0
	v_dot8_i32_i4 v13, v93, v108, v13
	buffer_load_dwordx2 v[90:91], v192, s[52:55], s0 offen
	v_readlane_b32 s0, v12, 4
	s_lshl_b32 s0, s0, 9
	v_lshl_add_u32 v9, v9, 4, v11
	v_dot8_i32_i4 v11, v92, v73, 0
	v_dot8_i32_i4 v11, v93, v77, v11
	buffer_load_dwordx2 v[78:79], v192, s[52:55], s0 offen
	v_readlane_b32 s0, v12, 5
	s_lshl_b32 s0, s0, 9
	v_lshl_add_u32 v11, v11, 4, v13
	s_waitcnt vmcnt(17)
	v_dot8_i32_i4 v13, v106, v73, 0
	buffer_load_dwordx2 v[50:51], v192, s[52:55], s0 offen
	v_readlane_b32 s0, v12, 6
	s_lshl_b32 s0, s0, 9
	v_dot8_i32_i4 v15, v106, v75, 0
	v_dot8_i32_i4 v13, v107, v77, v13
	v_dot8_i32_i4 v15, v107, v108, v15
	buffer_load_dwordx2 v[48:49], v192, s[52:55], s0 offen
	v_readlane_b32 s0, v12, 7
	s_lshl_b32 s0, s0, 9
	v_lshl_add_u32 v13, v13, 4, v15
	s_waitcnt vmcnt(18)
	v_dot8_i32_i4 v15, v88, v73, 0
	v_dot8_i32_i4 v32, v88, v75, 0
	buffer_load_dwordx2 v[54:55], v192, s[52:55], s0 offen
	v_readlane_b32 s0, v12, 8
	s_lshl_b32 s0, s0, 9
	v_dot8_i32_i4 v15, v89, v77, v15
	v_dot8_i32_i4 v32, v89, v108, v32
	s_waitcnt vmcnt(18)
	v_dot8_i32_i4 v33, v80, v75, 0
	buffer_load_dwordx2 v[42:43], v192, s[52:55], s0 offen
	v_readlane_b32 s0, v12, 9
	s_lshl_b32 s0, s0, 9
	v_lshl_add_u32 v15, v15, 4, v32
	v_dot8_i32_i4 v32, v80, v73, 0
	v_dot8_i32_i4 v32, v81, v77, v32
	buffer_load_dwordx2 v[34:35], v192, s[52:55], s0 offen
	v_readlane_b32 s0, v12, 10
	s_lshl_b32 s0, s0, 9
	v_dot8_i32_i4 v33, v81, v108, v33
	s_waitcnt vmcnt(19)
	v_dot8_i32_i4 v80, v56, v75, 0
	v_dot8_i32_i4 v80, v57, v108, v80
	buffer_load_dwordx2 v[30:31], v192, s[52:55], s0 offen
	v_readlane_b32 s0, v12, 11
	s_lshl_b32 s0, s0, 9
	v_lshl_add_u32 v32, v32, 4, v33
	v_dot8_i32_i4 v33, v56, v73, 0
	v_dot8_i32_i4 v33, v57, v77, v33
	buffer_load_dwordx2 v[38:39], v192, s[52:55], s0 offen
	v_readlane_b32 s0, v12, 12
	s_lshl_b32 s0, s0, 9
	s_waitcnt vmcnt(20)
	v_dot8_i32_i4 v56, v82, v73, 0
	v_dot8_i32_i4 v57, v82, v75, 0
	buffer_load_dwordx2 v[26:27], v192, s[52:55], s0 offen
	v_readlane_b32 s0, v12, 13
	s_lshl_b32 s0, s0, 9
	v_dot8_i32_i4 v56, v83, v77, v56
	v_dot8_i32_i4 v57, v83, v108, v57
	v_lshl_add_u32 v33, v33, 4, v80
	buffer_load_dwordx2 v[20:21], v192, s[52:55], s0 offen
	v_readlane_b32 s0, v12, 14
	s_lshl_b32 s0, s0, 9
	v_lshl_add_u32 v56, v56, 4, v57
	s_waitcnt vmcnt(21)
	v_dot8_i32_i4 v57, v52, v73, 0
	v_dot8_i32_i4 v80, v52, v75, 0
	buffer_load_dwordx2 v[16:17], v192, s[52:55], s0 offen
	v_readlane_b32 s0, v12, 15
	s_lshl_b32 s0, s0, 9
	v_dot8_i32_i4 v57, v53, v77, v57
	v_dot8_i32_i4 v80, v53, v108, v80
	s_waitcnt vmcnt(21)
	v_dot8_i32_i4 v53, v44, v73, 0
	buffer_load_dwordx2 v[22:23], v192, s[52:55], s0 offen
	v_lshl_add_u32 v52, v57, 4, v80
	v_dot8_i32_i4 v57, v44, v75, 0
	v_dot8_i32_i4 v53, v45, v77, v53
	v_dot8_i32_i4 v57, v45, v108, v57
	s_waitcnt vmcnt(21)
	v_dot8_i32_i4 v45, v40, v73, 0
	v_dot8_i32_i4 v45, v41, v77, v45
	v_lshl_add_u32 v44, v53, 4, v57
	v_dot8_i32_i4 v53, v40, v75, 0
	v_dot8_i32_i4 v53, v41, v108, v53
	s_waitcnt vmcnt(20)
	v_dot8_i32_i4 v41, v46, v73, 0
	v_dot8_i32_i4 v41, v47, v77, v41
	v_lshl_add_u32 v40, v45, 4, v53
	v_dot8_i32_i4 v45, v46, v75, 0
	v_dot8_i32_i4 v45, v47, v108, v45
	s_waitcnt vmcnt(19)
	v_dot8_i32_i4 v46, v36, v75, 0
	v_dot8_i32_i4 v46, v37, v108, v46
	v_lshl_add_u32 v41, v41, 4, v45
	v_dot8_i32_i4 v45, v36, v73, 0
	v_dot8_i32_i4 v45, v37, v77, v45
	s_waitcnt vmcnt(18)
	v_dot8_i32_i4 v37, v24, v73, 0
	v_dot8_i32_i4 v37, v25, v77, v37
	v_lshl_add_u32 v36, v45, 4, v46
	v_dot8_i32_i4 v45, v24, v75, 0
	v_dot8_i32_i4 v45, v25, v108, v45
	s_waitcnt vmcnt(17)
	v_dot8_i32_i4 v25, v18, v73, 0
	v_cvt_f32_i32_e32 v5, v5
	v_lshl_add_u32 v24, v37, 4, v45
	v_dot8_i32_i4 v37, v18, v75, 0
	v_cvt_f32_i32_e32 v9, v9
	v_cvt_f32_i32_e32 v11, v11
	v_cvt_f32_i32_e32 v13, v13
	v_dot8_i32_i4 v25, v19, v77, v25
	v_dot8_i32_i4 v37, v19, v108, v37
	s_waitcnt vmcnt(16)
	v_dot8_i32_i4 v19, v28, v73, 0
	v_dot8_i32_i4 v19, v29, v77, v19
	v_lshl_add_u32 v18, v25, 4, v37
	v_dot8_i32_i4 v25, v28, v75, 0
	v_dot8_i32_i4 v25, v29, v108, v25
	v_cvt_f32_i32_e32 v15, v15
	v_cvt_f32_i32_e32 v32, v32
	v_cvt_f32_i32_e32 v33, v33
	v_lshl_add_u32 v19, v19, 4, v25
	v_cndmask_b32_e64 v25, v9, v5, s[40:41]
	v_cndmask_b32_e64 v5, v5, v9, s[40:41]
	v_cndmask_b32_e64 v9, v13, v11, s[40:41]
	v_cndmask_b32_e64 v11, v11, v13, s[40:41]
	ds_swizzle_b32 v11, v11 offset:swizzle(SWAP,1)
	v_cvt_f32_i32_e32 v56, v56
	ds_swizzle_b32 v5, v5 offset:swizzle(SWAP,1)
	v_cvt_f32_i32_e32 v52, v52
	v_cvt_f32_i32_e32 v44, v44
	v_cvt_f32_i32_e32 v40, v40
	v_cvt_f32_i32_e32 v41, v41
	v_cndmask_b32_e64 v13, v15, v32, s[40:41]
	s_waitcnt lgkmcnt(1)
	v_add_f32_e32 v9, v9, v11
	v_cndmask_b32_e64 v11, v32, v15, s[40:41]
	ds_swizzle_b32 v13, v13 offset:swizzle(SWAP,1)
	v_cndmask_b32_e64 v15, v33, v56, s[40:41]
	s_waitcnt lgkmcnt(1)
	v_add_f32_e32 v5, v25, v5
	ds_swizzle_b32 v15, v15 offset:swizzle(SWAP,1)
	v_cndmask_b32_e64 v25, v52, v44, s[40:41]
	ds_swizzle_b32 v25, v25 offset:swizzle(SWAP,1)
	v_cndmask_b32_e64 v28, v40, v41, s[40:41]
	ds_swizzle_b32 v28, v28 offset:swizzle(SWAP,1)
	v_cvt_f32_i32_e32 v36, v36
	v_cvt_f32_i32_e32 v24, v24
	s_waitcnt lgkmcnt(3)
	v_add_f32_e32 v11, v11, v13
	v_cndmask_b32_e64 v13, v56, v33, s[40:41]
	s_waitcnt lgkmcnt(2)
	v_add_f32_e32 v13, v13, v15
	v_cndmask_b32_e64 v15, v44, v52, s[40:41]
	s_waitcnt lgkmcnt(1)
	v_add_f32_e32 v15, v15, v25
	v_cndmask_b32_e64 v25, v41, v40, s[40:41]
	s_waitcnt lgkmcnt(0)
	v_add_f32_e32 v25, v25, v28
	v_cndmask_b32_e64 v28, v24, v36, s[40:41]
	v_cndmask_b32_e64 v24, v36, v24, s[40:41]
	ds_swizzle_b32 v24, v24 offset:swizzle(SWAP,1)
	v_cvt_f32_i32_e32 v18, v18
	v_cvt_f32_i32_e32 v19, v19
	s_waitcnt lgkmcnt(0)
	v_add_f32_e32 v24, v28, v24
	v_cndmask_b32_e64 v28, v19, v18, s[40:41]
	v_cndmask_b32_e64 v18, v18, v19, s[40:41]
	ds_swizzle_b32 v18, v18 offset:swizzle(SWAP,1)
	v_cndmask_b32_e64 v19, v9, v5, s[42:43]
	v_cndmask_b32_e64 v5, v5, v9, s[42:43]
	v_cndmask_b32_e64 v9, v13, v11, s[42:43]
	v_cndmask_b32_e64 v11, v11, v13, s[42:43]
	ds_swizzle_b32 v11, v11 offset:swizzle(SWAP,2)
	s_waitcnt lgkmcnt(1)
	v_add_f32_e32 v18, v28, v18
	v_cndmask_b32_e64 v13, v15, v25, s[42:43]
	ds_swizzle_b32 v13, v13 offset:swizzle(SWAP,2)
	ds_swizzle_b32 v5, v5 offset:swizzle(SWAP,2)
	s_waitcnt lgkmcnt(2)
	v_add_f32_e32 v9, v9, v11
	v_cndmask_b32_e64 v11, v25, v15, s[42:43]
	v_cndmask_b32_e64 v15, v24, v18, s[42:43]
	ds_swizzle_b32 v15, v15 offset:swizzle(SWAP,2)
	s_waitcnt lgkmcnt(2)
	v_add_f32_e32 v11, v11, v13
	v_cndmask_b32_e64 v13, v18, v24, s[42:43]
	s_waitcnt lgkmcnt(1)
	v_add_f32_e32 v5, v19, v5
	s_waitcnt lgkmcnt(0)
	v_add_f32_e32 v13, v13, v15
	v_cndmask_b32_e64 v15, v9, v5, s[44:45]
	v_cndmask_b32_e64 v5, v5, v9, s[44:45]
	v_cndmask_b32_e64 v9, v13, v11, s[44:45]
	v_cndmask_b32_e64 v11, v11, v13, s[44:45]
	ds_swizzle_b32 v5, v5 offset:swizzle(SWAP,4)
	ds_swizzle_b32 v11, v11 offset:swizzle(SWAP,4)
	s_waitcnt lgkmcnt(1)
	v_add_f32_e32 v5, v15, v5
	s_waitcnt lgkmcnt(0)
	v_add_f32_e32 v9, v9, v11
	v_cndmask_b32_e64 v11, v9, v5, s[46:47]
	v_cndmask_b32_e64 v5, v5, v9, s[46:47]
	ds_swizzle_b32 v5, v5 offset:swizzle(SWAP,8)
	s_waitcnt lgkmcnt(0)
	v_add_f32_e32 v5, v11, v5
	ds_swizzle_b32 v9, v5 offset:swizzle(SWAP,16)
	s_waitcnt lgkmcnt(0)
	v_add_f32_e32 v5, v5, v9
	ds_bpermute_b32 v9, v0, v5
	s_and_saveexec_b64 s[0:1], s[48:49]
	s_cbranch_execz .LBB0_547
	v_ashrrev_i32_e32 v15, 31, v14
	v_lshlrev_b64 v[14:15], 2, v[14:15]
	v_lshl_add_u64 v[18:19], s[8:9], 0, v[14:15]
	global_load_dword v11, v[18:19], off
	v_lshl_add_u64 v[14:15], s[10:11], 0, v[14:15]
	global_load_dword v13, v[6:7], off offset:192
	s_nop 0
	global_load_dword v14, v[14:15], off
	s_waitcnt lgkmcnt(0)
	v_add_f32_e32 v5, v5, v9
	s_waitcnt vmcnt(2)
	v_mul_f32_e32 v5, v5, v11
	v_mul_f32_e32 v5, v3, v5
	v_mul_f32_e32 v11, 0x3d372713, v5
	v_mul_f32_e32 v11, v5, v11
	v_mul_f32_e32 v9, 0.5, v5
	v_fmac_f32_e32 v5, v5, v11
	v_mul_f32_e32 v5, 0x3f4c422a, v5
	v_add_f32_e32 v5, v5, v5
	v_mul_f32_e32 v5, 0x3fb8aa3b, v5
	v_exp_f32_e32 v5, v5
	s_nop 0
	v_add_f32_e32 v5, 1.0, v5
	v_rcp_f32_e32 v5, v5
	s_nop 0
	v_fma_f32 v5, v5, -2.0, 1.0
	v_add_f32_e32 v5, 1.0, v5
	v_mul_f32_e32 v5, v9, v5
	s_waitcnt vmcnt(1)
	v_mul_f32_e32 v5, v13, v5
	s_waitcnt vmcnt(0)
	v_mul_f32_e32 v5, v14, v5
	ds_write_b32 v109, v5 offset:192
.LBB0_547:
	s_or_b64 exec, exec, s[0:1]
	v_readlane_b32 s0, v10, 0
	s_lshl_b32 s0, s0, 9
	s_waitcnt lgkmcnt(0)
	s_waitcnt vmcnt(15)
	v_dot8_i32_i4 v5, v94, v73, 0
	v_dot8_i32_i4 v9, v94, v75, 0
	buffer_load_dwordx2 v[92:93], v192, s[52:55], s0 offen
	v_readlane_b32 s0, v10, 1
	s_lshl_b32 s0, s0, 9
	v_dot8_i32_i4 v5, v95, v77, v5
	v_dot8_i32_i4 v9, v95, v108, v9
	s_waitcnt vmcnt(15)
	v_dot8_i32_i4 v11, v86, v75, 0
	buffer_load_dwordx2 v[96:97], v192, s[52:55], s0 offen
	v_readlane_b32 s0, v10, 2
	s_lshl_b32 s0, s0, 9
	v_lshl_add_u32 v5, v5, 4, v9
	v_dot8_i32_i4 v9, v86, v73, 0
	v_dot8_i32_i4 v9, v87, v77, v9
	buffer_load_dwordx2 v[88:89], v192, s[52:55], s0 offen
	v_readlane_b32 s0, v10, 3
	s_lshl_b32 s0, s0, 9
	v_dot8_i32_i4 v11, v87, v108, v11
	s_waitcnt vmcnt(16)
	v_dot8_i32_i4 v13, v84, v75, 0
	v_dot8_i32_i4 v13, v85, v108, v13
	buffer_load_dwordx2 v[98:99], v192, s[52:55], s0 offen
	v_readlane_b32 s0, v10, 4
	s_lshl_b32 s0, s0, 9
	v_lshl_add_u32 v9, v9, 4, v11
	v_dot8_i32_i4 v11, v84, v73, 0
	v_dot8_i32_i4 v11, v85, v77, v11
	buffer_load_dwordx2 v[82:83], v192, s[52:55], s0 offen
	v_readlane_b32 s0, v10, 5
	s_lshl_b32 s0, s0, 9
	v_lshl_add_u32 v11, v11, 4, v13
	s_waitcnt vmcnt(17)
	v_dot8_i32_i4 v13, v90, v73, 0
	buffer_load_dwordx2 v[56:57], v192, s[52:55], s0 offen
	v_readlane_b32 s0, v10, 6
	s_lshl_b32 s0, s0, 9
	v_dot8_i32_i4 v18, v90, v75, 0
	v_dot8_i32_i4 v13, v91, v77, v13
	v_dot8_i32_i4 v18, v91, v108, v18
	buffer_load_dwordx2 v[52:53], v192, s[52:55], s0 offen
	v_readlane_b32 s0, v10, 7
	s_lshl_b32 s0, s0, 9
	v_lshl_add_u32 v13, v13, 4, v18
	s_waitcnt vmcnt(18)
	v_dot8_i32_i4 v18, v78, v73, 0
	v_dot8_i32_i4 v19, v78, v75, 0
	buffer_load_dwordx2 v[80:81], v192, s[52:55], s0 offen
	v_readlane_b32 s0, v10, 8
	s_lshl_b32 s0, s0, 9
	v_dot8_i32_i4 v18, v79, v77, v18
	v_dot8_i32_i4 v19, v79, v108, v19
	s_waitcnt vmcnt(18)
	v_dot8_i32_i4 v78, v50, v75, 0
	buffer_load_dwordx2 v[46:47], v192, s[52:55], s0 offen
	v_readlane_b32 s0, v10, 9
	s_lshl_b32 s0, s0, 9
	v_lshl_add_u32 v18, v18, 4, v19
	v_dot8_i32_i4 v19, v50, v73, 0
	v_dot8_i32_i4 v19, v51, v77, v19
	buffer_load_dwordx2 v[40:41], v192, s[52:55], s0 offen
	v_readlane_b32 s0, v10, 10
	s_lshl_b32 s0, s0, 9
	v_dot8_i32_i4 v78, v51, v108, v78
	s_waitcnt vmcnt(19)
	v_dot8_i32_i4 v50, v48, v73, 0
	buffer_load_dwordx2 v[36:37], v192, s[52:55], s0 offen
	v_readlane_b32 s0, v10, 11
	s_lshl_b32 s0, s0, 9
	v_dot8_i32_i4 v51, v48, v75, 0
	v_dot8_i32_i4 v50, v49, v77, v50
	v_dot8_i32_i4 v51, v49, v108, v51
	buffer_load_dwordx2 v[44:45], v192, s[52:55], s0 offen
	v_readlane_b32 s0, v10, 12
	s_lshl_b32 s0, s0, 9
	v_lshl_add_u32 v48, v50, 4, v51
	s_waitcnt vmcnt(20)
	v_dot8_i32_i4 v49, v54, v73, 0
	v_dot8_i32_i4 v50, v54, v75, 0
	buffer_load_dwordx2 v[32:33], v192, s[52:55], s0 offen
	v_readlane_b32 s0, v10, 13
	s_lshl_b32 s0, s0, 9
	v_dot8_i32_i4 v49, v55, v77, v49
	v_dot8_i32_i4 v50, v55, v108, v50
	s_waitcnt vmcnt(20)
	v_dot8_i32_i4 v51, v42, v75, 0
	buffer_load_dwordx2 v[24:25], v192, s[52:55], s0 offen
	v_readlane_b32 s0, v10, 14
	s_lshl_b32 s0, s0, 9
	v_lshl_add_u32 v49, v49, 4, v50
	v_dot8_i32_i4 v50, v42, v73, 0
	v_dot8_i32_i4 v50, v43, v77, v50
	buffer_load_dwordx2 v[14:15], v192, s[52:55], s0 offen
	v_readlane_b32 s0, v10, 15
	s_lshl_b32 s0, s0, 9
	v_dot8_i32_i4 v51, v43, v108, v51
	s_waitcnt vmcnt(21)
	v_dot8_i32_i4 v43, v34, v73, 0
	v_dot8_i32_i4 v43, v35, v77, v43
	buffer_load_dwordx2 v[28:29], v192, s[52:55], s0 offen
	v_lshl_add_u32 v42, v50, 4, v51
	v_dot8_i32_i4 v50, v34, v75, 0
	v_dot8_i32_i4 v50, v35, v108, v50
	s_waitcnt vmcnt(21)
	v_dot8_i32_i4 v35, v30, v73, 0
	v_dot8_i32_i4 v35, v31, v77, v35
	v_lshl_add_u32 v34, v43, 4, v50
	v_dot8_i32_i4 v43, v30, v75, 0
	v_dot8_i32_i4 v43, v31, v108, v43
	s_waitcnt vmcnt(20)
	v_dot8_i32_i4 v31, v38, v73, 0
	v_dot8_i32_i4 v31, v39, v77, v31
	v_lshl_add_u32 v30, v35, 4, v43
	v_dot8_i32_i4 v35, v38, v75, 0
	v_dot8_i32_i4 v35, v39, v108, v35
	s_waitcnt vmcnt(19)
	v_dot8_i32_i4 v38, v26, v75, 0
	v_dot8_i32_i4 v38, v27, v108, v38
	v_lshl_add_u32 v31, v31, 4, v35
	v_dot8_i32_i4 v35, v26, v73, 0
	v_dot8_i32_i4 v35, v27, v77, v35
	s_waitcnt vmcnt(18)
	v_dot8_i32_i4 v27, v20, v73, 0
	v_dot8_i32_i4 v27, v21, v77, v27
	v_lshl_add_u32 v26, v35, 4, v38
	v_dot8_i32_i4 v35, v20, v75, 0
	v_dot8_i32_i4 v35, v21, v108, v35
	s_waitcnt vmcnt(17)
	v_dot8_i32_i4 v21, v16, v73, 0
	v_cvt_f32_i32_e32 v5, v5
	v_lshl_add_u32 v20, v27, 4, v35
	v_dot8_i32_i4 v27, v16, v75, 0
	v_cvt_f32_i32_e32 v9, v9
	v_cvt_f32_i32_e32 v11, v11
	v_cvt_f32_i32_e32 v13, v13
	v_dot8_i32_i4 v21, v17, v77, v21
	v_dot8_i32_i4 v27, v17, v108, v27
	s_waitcnt vmcnt(16)
	v_dot8_i32_i4 v17, v22, v73, 0
	v_dot8_i32_i4 v17, v23, v77, v17
	v_lshl_add_u32 v16, v21, 4, v27
	v_dot8_i32_i4 v21, v22, v75, 0
	v_dot8_i32_i4 v21, v23, v108, v21
	v_lshl_add_u32 v19, v19, 4, v78
	v_cvt_f32_i32_e32 v18, v18
	v_cvt_f32_i32_e32 v19, v19
	v_lshl_add_u32 v17, v17, 4, v21
	v_cndmask_b32_e64 v21, v9, v5, s[40:41]
	v_cndmask_b32_e64 v5, v5, v9, s[40:41]
	v_cndmask_b32_e64 v9, v13, v11, s[40:41]
	v_cndmask_b32_e64 v11, v11, v13, s[40:41]
	ds_swizzle_b32 v11, v11 offset:swizzle(SWAP,1)
	v_cvt_f32_i32_e32 v48, v48
	v_cvt_f32_i32_e32 v49, v49
	v_cvt_f32_i32_e32 v42, v42
	v_cvt_f32_i32_e32 v34, v34
	ds_swizzle_b32 v5, v5 offset:swizzle(SWAP,1)
	v_cvt_f32_i32_e32 v30, v30
	v_cvt_f32_i32_e32 v31, v31
	v_cndmask_b32_e64 v13, v18, v19, s[40:41]
	s_waitcnt lgkmcnt(1)
	v_add_f32_e32 v9, v9, v11
	v_cndmask_b32_e64 v11, v19, v18, s[40:41]
	ds_swizzle_b32 v13, v13 offset:swizzle(SWAP,1)
	v_cndmask_b32_e64 v18, v48, v49, s[40:41]
	ds_swizzle_b32 v18, v18 offset:swizzle(SWAP,1)
	v_cndmask_b32_e64 v19, v42, v34, s[40:41]
	s_waitcnt lgkmcnt(2)
	v_add_f32_e32 v5, v21, v5
	ds_swizzle_b32 v19, v19 offset:swizzle(SWAP,1)
	v_cndmask_b32_e64 v21, v30, v31, s[40:41]
	ds_swizzle_b32 v21, v21 offset:swizzle(SWAP,1)
	v_cvt_f32_i32_e32 v26, v26
	v_cvt_f32_i32_e32 v20, v20
	s_waitcnt lgkmcnt(3)
	v_add_f32_e32 v11, v11, v13
	v_cndmask_b32_e64 v13, v49, v48, s[40:41]
	s_waitcnt lgkmcnt(2)
	v_add_f32_e32 v13, v13, v18
	v_cndmask_b32_e64 v18, v34, v42, s[40:41]
	s_waitcnt lgkmcnt(1)
	v_add_f32_e32 v18, v18, v19
	v_cndmask_b32_e64 v19, v31, v30, s[40:41]
	s_waitcnt lgkmcnt(0)
	v_add_f32_e32 v19, v19, v21
	v_cndmask_b32_e64 v21, v20, v26, s[40:41]
	v_cndmask_b32_e64 v20, v26, v20, s[40:41]
	ds_swizzle_b32 v20, v20 offset:swizzle(SWAP,1)
	v_cvt_f32_i32_e32 v16, v16
	v_cvt_f32_i32_e32 v17, v17
	s_waitcnt lgkmcnt(0)
	v_add_f32_e32 v20, v21, v20
	v_cndmask_b32_e64 v21, v17, v16, s[40:41]
	v_cndmask_b32_e64 v16, v16, v17, s[40:41]
	v_cndmask_b32_e64 v17, v9, v5, s[42:43]
	v_cndmask_b32_e64 v5, v5, v9, s[42:43]
	v_cndmask_b32_e64 v9, v13, v11, s[42:43]
	v_cndmask_b32_e64 v11, v11, v13, s[42:43]
	ds_swizzle_b32 v16, v16 offset:swizzle(SWAP,1)
	ds_swizzle_b32 v11, v11 offset:swizzle(SWAP,2)
	v_cndmask_b32_e64 v13, v18, v19, s[42:43]
	ds_swizzle_b32 v13, v13 offset:swizzle(SWAP,2)
	ds_swizzle_b32 v5, v5 offset:swizzle(SWAP,2)
	s_waitcnt lgkmcnt(3)
	v_add_f32_e32 v16, v21, v16
	s_waitcnt lgkmcnt(2)
	v_add_f32_e32 v9, v9, v11
	v_cndmask_b32_e64 v11, v19, v18, s[42:43]
	s_waitcnt lgkmcnt(1)
	v_add_f32_e32 v11, v11, v13
	v_cndmask_b32_e64 v13, v16, v20, s[42:43]
	v_cndmask_b32_e64 v16, v20, v16, s[42:43]
	ds_swizzle_b32 v16, v16 offset:swizzle(SWAP,2)
	s_waitcnt lgkmcnt(1)
	v_add_f32_e32 v5, v17, v5
	s_waitcnt lgkmcnt(0)
	v_add_f32_e32 v13, v13, v16
	v_cndmask_b32_e64 v16, v9, v5, s[44:45]
	v_cndmask_b32_e64 v5, v5, v9, s[44:45]
	v_cndmask_b32_e64 v9, v13, v11, s[44:45]
	v_cndmask_b32_e64 v11, v11, v13, s[44:45]
	ds_swizzle_b32 v5, v5 offset:swizzle(SWAP,4)
	ds_swizzle_b32 v11, v11 offset:swizzle(SWAP,4)
	s_waitcnt lgkmcnt(1)
	v_add_f32_e32 v5, v16, v5
	s_waitcnt lgkmcnt(0)
	v_add_f32_e32 v9, v9, v11
	v_cndmask_b32_e64 v11, v9, v5, s[46:47]
	v_cndmask_b32_e64 v5, v5, v9, s[46:47]
	ds_swizzle_b32 v5, v5 offset:swizzle(SWAP,8)
	s_waitcnt lgkmcnt(0)
	v_add_f32_e32 v5, v11, v5
	ds_swizzle_b32 v9, v5 offset:swizzle(SWAP,16)
	s_waitcnt lgkmcnt(0)
	v_add_f32_e32 v5, v5, v9
	ds_bpermute_b32 v9, v0, v5
	s_and_saveexec_b64 s[0:1], s[48:49]
	s_cbranch_execz .LBB0_549
	v_ashrrev_i32_e32 v13, 31, v12
	v_lshlrev_b64 v[12:13], 2, v[12:13]
	v_lshl_add_u64 v[16:17], s[8:9], 0, v[12:13]
	global_load_dword v11, v[16:17], off
	v_lshl_add_u64 v[12:13], s[10:11], 0, v[12:13]
	global_load_dword v16, v[6:7], off offset:256
	s_nop 0
	global_load_dword v12, v[12:13], off
	s_waitcnt lgkmcnt(0)
	v_add_f32_e32 v5, v5, v9
	s_waitcnt vmcnt(2)
	v_mul_f32_e32 v5, v5, v11
	v_mul_f32_e32 v5, v3, v5
	v_mul_f32_e32 v11, 0x3d372713, v5
	v_mul_f32_e32 v11, v5, v11
	v_mul_f32_e32 v9, 0.5, v5
	v_fmac_f32_e32 v5, v5, v11
	v_mul_f32_e32 v5, 0x3f4c422a, v5
	v_add_f32_e32 v5, v5, v5
	v_mul_f32_e32 v5, 0x3fb8aa3b, v5
	v_exp_f32_e32 v5, v5
	s_nop 0
	v_add_f32_e32 v5, 1.0, v5
	v_rcp_f32_e32 v5, v5
	s_nop 0
	v_fma_f32 v5, v5, -2.0, 1.0
	v_add_f32_e32 v5, 1.0, v5
	v_mul_f32_e32 v5, v9, v5
	s_waitcnt vmcnt(1)
	v_mul_f32_e32 v5, v16, v5
	s_waitcnt vmcnt(0)
	v_mul_f32_e32 v5, v12, v5
	ds_write_b32 v109, v5 offset:256
.LBB0_549:
	s_or_b64 exec, exec, s[0:1]
	v_readlane_b32 s0, v8, 0
	s_lshl_b32 s0, s0, 9
	s_waitcnt lgkmcnt(0)
	s_waitcnt vmcnt(15)
	v_dot8_i32_i4 v5, v92, v73, 0
	v_dot8_i32_i4 v9, v92, v75, 0
	buffer_load_dwordx2 v[86:87], v192, s[52:55], s0 offen
	v_readlane_b32 s0, v8, 1
	s_lshl_b32 s0, s0, 9
	v_dot8_i32_i4 v5, v93, v77, v5
	v_dot8_i32_i4 v9, v93, v108, v9
	s_waitcnt vmcnt(15)
	v_dot8_i32_i4 v11, v96, v75, 0
	buffer_load_dwordx2 v[78:79], v192, s[52:55], s0 offen
	v_readlane_b32 s0, v8, 2
	s_lshl_b32 s0, s0, 9
	v_lshl_add_u32 v5, v5, 4, v9
	v_dot8_i32_i4 v9, v96, v73, 0
	v_dot8_i32_i4 v9, v97, v77, v9
	buffer_load_dwordx2 v[54:55], v192, s[52:55], s0 offen
	v_readlane_b32 s0, v8, 3
	s_lshl_b32 s0, s0, 9
	v_dot8_i32_i4 v11, v97, v108, v11
	s_waitcnt vmcnt(16)
	v_dot8_i32_i4 v90, v88, v75, 0
	v_dot8_i32_i4 v90, v89, v108, v90
	buffer_load_dwordx2 v[84:85], v192, s[52:55], s0 offen
	v_readlane_b32 s0, v8, 4
	s_lshl_b32 s0, s0, 9
	v_lshl_add_u32 v9, v9, 4, v11
	v_dot8_i32_i4 v11, v88, v73, 0
	v_dot8_i32_i4 v11, v89, v77, v11
	buffer_load_dwordx2 v[50:51], v192, s[52:55], s0 offen
	v_readlane_b32 s0, v8, 5
	s_lshl_b32 s0, s0, 9
	s_waitcnt vmcnt(17)
	v_dot8_i32_i4 v88, v98, v73, 0
	v_dot8_i32_i4 v89, v98, v75, 0
	buffer_load_dwordx2 v[42:43], v192, s[52:55], s0 offen
	v_readlane_b32 s0, v8, 6
	s_lshl_b32 s0, s0, 9
	v_dot8_i32_i4 v88, v99, v77, v88
	v_dot8_i32_i4 v89, v99, v108, v89
	v_lshl_add_u32 v11, v11, 4, v90
	buffer_load_dwordx2 v[38:39], v192, s[52:55], s0 offen
	v_readlane_b32 s0, v8, 7
	s_lshl_b32 s0, s0, 9
	v_lshl_add_u32 v88, v88, 4, v89
	s_waitcnt vmcnt(18)
	v_dot8_i32_i4 v89, v82, v73, 0
	v_dot8_i32_i4 v90, v82, v75, 0
	buffer_load_dwordx2 v[48:49], v192, s[52:55], s0 offen
	v_readlane_b32 s0, v8, 8
	s_lshl_b32 s0, s0, 9
	v_dot8_i32_i4 v89, v83, v77, v89
	v_dot8_i32_i4 v90, v83, v108, v90
	s_waitcnt vmcnt(18)
	v_dot8_i32_i4 v83, v56, v73, 0
	buffer_load_dwordx2 v[34:35], v192, s[52:55], s0 offen
	v_readlane_b32 s0, v8, 9
	s_lshl_b32 s0, s0, 9
	v_lshl_add_u32 v82, v89, 4, v90
	v_dot8_i32_i4 v89, v56, v75, 0
	v_dot8_i32_i4 v83, v57, v77, v83
	buffer_load_dwordx2 v[26:27], v192, s[52:55], s0 offen
	v_readlane_b32 s0, v8, 10
	s_lshl_b32 s0, s0, 9
	v_dot8_i32_i4 v89, v57, v108, v89
	s_waitcnt vmcnt(19)
	v_dot8_i32_i4 v57, v52, v73, 0
	v_dot8_i32_i4 v57, v53, v77, v57
	buffer_load_dwordx2 v[22:23], v192, s[52:55], s0 offen
	v_readlane_b32 s0, v8, 11
	s_lshl_b32 s0, s0, 9
	v_lshl_add_u32 v56, v83, 4, v89
	v_dot8_i32_i4 v83, v52, v75, 0
	v_dot8_i32_i4 v83, v53, v108, v83
	buffer_load_dwordx2 v[30:31], v192, s[52:55], s0 offen
	v_readlane_b32 s0, v8, 12
	s_lshl_b32 s0, s0, 9
	v_lshl_add_u32 v52, v57, 4, v83
	s_waitcnt vmcnt(20)
	v_dot8_i32_i4 v53, v80, v73, 0
	buffer_load_dwordx2 v[20:21], v192, s[52:55], s0 offen
	v_readlane_b32 s0, v8, 13
	s_lshl_b32 s0, s0, 9
	v_dot8_i32_i4 v57, v80, v75, 0
	v_dot8_i32_i4 v53, v81, v77, v53
	v_dot8_i32_i4 v57, v81, v108, v57
	buffer_load_dwordx2 v[16:17], v192, s[52:55], s0 offen
	v_readlane_b32 s0, v8, 14
	s_lshl_b32 s0, s0, 9
	v_lshl_add_u32 v53, v53, 4, v57
	s_waitcnt vmcnt(21)
	v_dot8_i32_i4 v57, v46, v73, 0
	v_dot8_i32_i4 v80, v46, v75, 0
	buffer_load_dwordx2 v[12:13], v192, s[52:55], s0 offen
	v_readlane_b32 s0, v8, 15
	s_lshl_b32 s0, s0, 9
	v_dot8_i32_i4 v57, v47, v77, v57
	v_dot8_i32_i4 v80, v47, v108, v80
	s_waitcnt vmcnt(21)
	v_dot8_i32_i4 v47, v40, v73, 0
	buffer_load_dwordx2 v[18:19], v192, s[52:55], s0 offen
	v_lshl_add_u32 v46, v57, 4, v80
	v_dot8_i32_i4 v57, v40, v75, 0
	v_dot8_i32_i4 v47, v41, v77, v47
	v_dot8_i32_i4 v57, v41, v108, v57
	s_waitcnt vmcnt(21)
	v_dot8_i32_i4 v41, v36, v73, 0
	v_dot8_i32_i4 v41, v37, v77, v41
	v_lshl_add_u32 v40, v47, 4, v57
	v_dot8_i32_i4 v47, v36, v75, 0
	v_dot8_i32_i4 v47, v37, v108, v47
	s_waitcnt vmcnt(20)
	v_dot8_i32_i4 v37, v44, v73, 0
	v_dot8_i32_i4 v37, v45, v77, v37
	v_lshl_add_u32 v36, v41, 4, v47
	v_dot8_i32_i4 v41, v44, v75, 0
	v_dot8_i32_i4 v41, v45, v108, v41
	s_waitcnt vmcnt(19)
	v_dot8_i32_i4 v44, v32, v75, 0
	v_dot8_i32_i4 v44, v33, v108, v44
	v_lshl_add_u32 v37, v37, 4, v41
	v_dot8_i32_i4 v41, v32, v73, 0
	v_dot8_i32_i4 v41, v33, v77, v41
	s_waitcnt vmcnt(18)
	v_dot8_i32_i4 v33, v24, v73, 0
	v_dot8_i32_i4 v33, v25, v77, v33
	v_lshl_add_u32 v32, v41, 4, v44
	v_dot8_i32_i4 v41, v24, v75, 0
	v_dot8_i32_i4 v41, v25, v108, v41
	s_waitcnt vmcnt(17)
	v_dot8_i32_i4 v25, v14, v73, 0
	v_cvt_f32_i32_e32 v5, v5
	v_lshl_add_u32 v24, v33, 4, v41
	v_dot8_i32_i4 v33, v14, v75, 0
	v_cvt_f32_i32_e32 v9, v9
	v_dot8_i32_i4 v25, v15, v77, v25
	v_dot8_i32_i4 v33, v15, v108, v33
	s_waitcnt vmcnt(16)
	v_dot8_i32_i4 v15, v28, v73, 0
	v_dot8_i32_i4 v15, v29, v77, v15
	v_lshl_add_u32 v14, v25, 4, v33
	v_dot8_i32_i4 v25, v28, v75, 0
	v_dot8_i32_i4 v25, v29, v108, v25
	v_cvt_f32_i32_e32 v11, v11
	v_cvt_f32_i32_e32 v88, v88
	v_cvt_f32_i32_e32 v82, v82
	v_lshl_add_u32 v15, v15, 4, v25
	v_cndmask_b32_e64 v25, v9, v5, s[40:41]
	v_cndmask_b32_e64 v5, v5, v9, s[40:41]
	ds_swizzle_b32 v5, v5 offset:swizzle(SWAP,1)
	v_cvt_f32_i32_e32 v56, v56
	v_cvt_f32_i32_e32 v52, v52
	v_cvt_f32_i32_e32 v53, v53
	v_cvt_f32_i32_e32 v46, v46
	v_cvt_f32_i32_e32 v40, v40
	v_cvt_f32_i32_e32 v36, v36
	v_cvt_f32_i32_e32 v37, v37
	v_cndmask_b32_e64 v9, v88, v11, s[40:41]
	v_cndmask_b32_e64 v11, v11, v88, s[40:41]
	s_waitcnt lgkmcnt(0)
	v_add_f32_e32 v5, v25, v5
	ds_swizzle_b32 v11, v11 offset:swizzle(SWAP,1)
	v_cndmask_b32_e64 v25, v82, v56, s[40:41]
	ds_swizzle_b32 v25, v25 offset:swizzle(SWAP,1)
	v_cndmask_b32_e64 v28, v52, v53, s[40:41]
	ds_swizzle_b32 v28, v28 offset:swizzle(SWAP,1)
	v_cndmask_b32_e64 v29, v46, v40, s[40:41]
	ds_swizzle_b32 v29, v29 offset:swizzle(SWAP,1)
	v_cndmask_b32_e64 v33, v36, v37, s[40:41]
	ds_swizzle_b32 v33, v33 offset:swizzle(SWAP,1)
	v_cvt_f32_i32_e32 v32, v32
	v_cvt_f32_i32_e32 v24, v24
	v_cvt_f32_i32_e32 v14, v14
	v_cvt_f32_i32_e32 v15, v15
	s_waitcnt lgkmcnt(4)
	v_add_f32_e32 v9, v9, v11
	v_cndmask_b32_e64 v11, v56, v82, s[40:41]
	s_waitcnt lgkmcnt(3)
	v_add_f32_e32 v11, v11, v25
	v_cndmask_b32_e64 v25, v53, v52, s[40:41]
	s_waitcnt lgkmcnt(2)
	v_add_f32_e32 v25, v25, v28
	v_cndmask_b32_e64 v28, v40, v46, s[40:41]
	s_waitcnt lgkmcnt(1)
	v_add_f32_e32 v28, v28, v29
	v_cndmask_b32_e64 v29, v37, v36, s[40:41]
	s_waitcnt lgkmcnt(0)
	v_add_f32_e32 v29, v29, v33
	v_cndmask_b32_e64 v33, v24, v32, s[40:41]
	v_cndmask_b32_e64 v24, v32, v24, s[40:41]
	v_cndmask_b32_e64 v32, v15, v14, s[40:41]
	v_cndmask_b32_e64 v14, v14, v15, s[40:41]
	v_cndmask_b32_e64 v15, v9, v5, s[42:43]
	v_cndmask_b32_e64 v5, v5, v9, s[42:43]
	ds_swizzle_b32 v5, v5 offset:swizzle(SWAP,2)
	v_cndmask_b32_e64 v9, v25, v11, s[42:43]
	v_cndmask_b32_e64 v11, v11, v25, s[42:43]
	ds_swizzle_b32 v24, v24 offset:swizzle(SWAP,1)
	ds_swizzle_b32 v14, v14 offset:swizzle(SWAP,1)
	s_waitcnt lgkmcnt(2)
	v_add_f32_e32 v5, v15, v5
	ds_swizzle_b32 v11, v11 offset:swizzle(SWAP,2)
	v_cndmask_b32_e64 v15, v28, v29, s[42:43]
	ds_swizzle_b32 v15, v15 offset:swizzle(SWAP,2)
	s_waitcnt lgkmcnt(3)
	v_add_f32_e32 v24, v33, v24
	s_waitcnt lgkmcnt(2)
	v_add_f32_e32 v14, v32, v14
	s_waitcnt lgkmcnt(1)
	v_add_f32_e32 v9, v9, v11
	v_cndmask_b32_e64 v11, v29, v28, s[42:43]
	s_waitcnt lgkmcnt(0)
	v_add_f32_e32 v11, v11, v15
	v_cndmask_b32_e64 v15, v14, v24, s[42:43]
	v_cndmask_b32_e64 v14, v24, v14, s[42:43]
	ds_swizzle_b32 v14, v14 offset:swizzle(SWAP,2)
	s_waitcnt lgkmcnt(0)
	v_add_f32_e32 v14, v15, v14
	v_cndmask_b32_e64 v15, v9, v5, s[44:45]
	v_cndmask_b32_e64 v5, v5, v9, s[44:45]
	v_cndmask_b32_e64 v9, v14, v11, s[44:45]
	v_cndmask_b32_e64 v11, v11, v14, s[44:45]
	ds_swizzle_b32 v5, v5 offset:swizzle(SWAP,4)
	ds_swizzle_b32 v11, v11 offset:swizzle(SWAP,4)
	s_waitcnt lgkmcnt(1)
	v_add_f32_e32 v5, v15, v5
	s_waitcnt lgkmcnt(0)
	v_add_f32_e32 v9, v9, v11
	v_cndmask_b32_e64 v11, v9, v5, s[46:47]
	v_cndmask_b32_e64 v5, v5, v9, s[46:47]
	ds_swizzle_b32 v5, v5 offset:swizzle(SWAP,8)
	s_waitcnt lgkmcnt(0)
	v_add_f32_e32 v5, v11, v5
	ds_swizzle_b32 v9, v5 offset:swizzle(SWAP,16)
	s_waitcnt lgkmcnt(0)
	v_add_f32_e32 v5, v5, v9
	ds_bpermute_b32 v9, v0, v5
	s_and_saveexec_b64 s[0:1], s[48:49]
	s_cbranch_execz .LBB0_551
	v_ashrrev_i32_e32 v11, 31, v10
	v_lshlrev_b64 v[10:11], 2, v[10:11]
	v_lshl_add_u64 v[14:15], s[8:9], 0, v[10:11]
	global_load_dword v14, v[14:15], off
	v_lshl_add_u64 v[10:11], s[10:11], 0, v[10:11]
	global_load_dword v15, v[6:7], off offset:320
	s_nop 0
	global_load_dword v10, v[10:11], off
	s_waitcnt lgkmcnt(0)
	v_add_f32_e32 v5, v5, v9
	s_waitcnt vmcnt(2)
	v_mul_f32_e32 v5, v5, v14
	v_mul_f32_e32 v5, v3, v5
	v_mul_f32_e32 v11, 0x3d372713, v5
	v_mul_f32_e32 v11, v5, v11
	v_mul_f32_e32 v9, 0.5, v5
	v_fmac_f32_e32 v5, v5, v11
	v_mul_f32_e32 v5, 0x3f4c422a, v5
	v_add_f32_e32 v5, v5, v5
	v_mul_f32_e32 v5, 0x3fb8aa3b, v5
	v_exp_f32_e32 v5, v5
	s_nop 0
	v_add_f32_e32 v5, 1.0, v5
	v_rcp_f32_e32 v5, v5
	s_nop 0
	v_fma_f32 v5, v5, -2.0, 1.0
	v_add_f32_e32 v5, 1.0, v5
	v_mul_f32_e32 v5, v9, v5
	s_waitcnt vmcnt(1)
	v_mul_f32_e32 v5, v15, v5
	s_waitcnt vmcnt(0)
	v_mul_f32_e32 v5, v10, v5
	ds_write_b32 v109, v5 offset:320
.LBB0_551:
	s_or_b64 exec, exec, s[0:1]
	s_waitcnt lgkmcnt(0)
	v_readlane_b32 s0, v4, 0
	s_waitcnt vmcnt(15)
	v_dot8_i32_i4 v5, v86, v73, 0
	v_dot8_i32_i4 v9, v86, v75, 0
	s_lshl_b32 s0, s0, 9
	v_dot8_i32_i4 v5, v87, v77, v5
	v_dot8_i32_i4 v9, v87, v108, v9
	buffer_load_dwordx2 v[88:89], v192, s[52:55], s0 offen
	v_readlane_b32 s0, v4, 1
	s_nop 0
	v_lshl_add_u32 v5, v5, 4, v9
	s_lshl_b32 s0, s0, 9
	s_waitcnt vmcnt(15)
	v_dot8_i32_i4 v9, v78, v73, 0
	v_dot8_i32_i4 v86, v78, v75, 0
	buffer_load_dwordx2 v[90:91], v192, s[52:55], s0 offen
	v_readlane_b32 s0, v4, 2
	v_dot8_i32_i4 v9, v79, v77, v9
	v_dot8_i32_i4 v86, v79, v108, v86
	s_lshl_b32 s0, s0, 9
	s_waitcnt vmcnt(15)
	v_dot8_i32_i4 v78, v54, v73, 0
	v_dot8_i32_i4 v79, v54, v75, 0
	buffer_load_dwordx2 v[82:83], v192, s[52:55], s0 offen
	v_readlane_b32 s0, v4, 3
	v_dot8_i32_i4 v78, v55, v77, v78
	v_dot8_i32_i4 v79, v55, v108, v79
	s_lshl_b32 s0, s0, 9
	s_waitcnt vmcnt(15)
	v_dot8_i32_i4 v55, v84, v73, 0
	v_lshl_add_u32 v54, v78, 4, v79
	buffer_load_dwordx2 v[92:93], v192, s[52:55], s0 offen
	v_readlane_b32 s0, v4, 4
	v_dot8_i32_i4 v78, v84, v75, 0
	s_lshl_b32 s0, s0, 9
	v_dot8_i32_i4 v55, v85, v77, v55
	v_dot8_i32_i4 v78, v85, v108, v78
	buffer_load_dwordx2 v[80:81], v192, s[52:55], s0 offen
	v_readlane_b32 s0, v4, 5
	s_nop 0
	v_lshl_add_u32 v55, v55, 4, v78
	s_lshl_b32 s0, s0, 9
	s_waitcnt vmcnt(16)
	v_dot8_i32_i4 v78, v50, v73, 0
	v_dot8_i32_i4 v79, v50, v75, 0
	buffer_load_dwordx2 v[52:53], v192, s[52:55], s0 offen
	v_readlane_b32 s0, v4, 6
	v_dot8_i32_i4 v78, v51, v77, v78
	v_dot8_i32_i4 v79, v51, v108, v79
	s_lshl_b32 s0, s0, 9
	s_waitcnt vmcnt(16)
	v_dot8_i32_i4 v51, v42, v73, 0
	v_lshl_add_u32 v50, v78, 4, v79
	buffer_load_dwordx2 v[46:47], v192, s[52:55], s0 offen
	v_readlane_b32 s0, v4, 7
	v_dot8_i32_i4 v78, v42, v75, 0
	s_lshl_b32 s0, s0, 9
	v_dot8_i32_i4 v51, v43, v77, v51
	v_dot8_i32_i4 v78, v43, v108, v78
	buffer_load_dwordx2 v[56:57], v192, s[52:55], s0 offen
	v_readlane_b32 s0, v4, 8
	s_nop 0
	v_lshl_add_u32 v42, v51, 4, v78
	s_lshl_b32 s0, s0, 9
	s_waitcnt vmcnt(17)
	v_dot8_i32_i4 v43, v38, v73, 0
	v_dot8_i32_i4 v51, v38, v75, 0
	buffer_load_dwordx2 v[44:45], v192, s[52:55], s0 offen
	v_readlane_b32 s0, v4, 9
	v_dot8_i32_i4 v43, v39, v77, v43
	v_dot8_i32_i4 v51, v39, v108, v51
	s_lshl_b32 s0, s0, 9
	s_waitcnt vmcnt(17)
	v_dot8_i32_i4 v39, v48, v73, 0
	v_lshl_add_u32 v38, v43, 4, v51
	buffer_load_dwordx2 v[36:37], v192, s[52:55], s0 offen
	v_readlane_b32 s0, v4, 10
	v_dot8_i32_i4 v43, v48, v75, 0
	s_lshl_b32 s0, s0, 9
	v_dot8_i32_i4 v39, v49, v77, v39
	v_dot8_i32_i4 v43, v49, v108, v43
	buffer_load_dwordx2 v[32:33], v192, s[52:55], s0 offen
	v_readlane_b32 s0, v4, 11
	s_nop 0
	v_lshl_add_u32 v39, v39, 4, v43
	s_lshl_b32 s0, s0, 9
	s_waitcnt vmcnt(18)
	v_dot8_i32_i4 v43, v34, v73, 0
	v_dot8_i32_i4 v48, v34, v75, 0
	buffer_load_dwordx2 v[40:41], v192, s[52:55], s0 offen
	v_readlane_b32 s0, v4, 12
	v_dot8_i32_i4 v43, v35, v77, v43
	v_dot8_i32_i4 v48, v35, v108, v48
	s_lshl_b32 s0, s0, 9
	s_waitcnt vmcnt(18)
	v_dot8_i32_i4 v35, v26, v73, 0
	v_lshl_add_u32 v34, v43, 4, v48
	buffer_load_dwordx2 v[28:29], v192, s[52:55], s0 offen
	v_readlane_b32 s0, v4, 13
	v_dot8_i32_i4 v43, v26, v75, 0
	s_lshl_b32 s0, s0, 9
	v_dot8_i32_i4 v35, v27, v77, v35
	v_dot8_i32_i4 v43, v27, v108, v43
	buffer_load_dwordx2 v[14:15], v192, s[52:55], s0 offen
	v_readlane_b32 s0, v4, 14
	s_nop 0
	v_lshl_add_u32 v26, v35, 4, v43
	s_lshl_b32 s0, s0, 9
	s_waitcnt vmcnt(19)
	v_dot8_i32_i4 v27, v22, v73, 0
	v_dot8_i32_i4 v35, v22, v75, 0
	buffer_load_dwordx2 v[10:11], v192, s[52:55], s0 offen
	v_readlane_b32 s0, v4, 15
	v_dot8_i32_i4 v27, v23, v77, v27
	v_dot8_i32_i4 v35, v23, v108, v35
	s_lshl_b32 s0, s0, 9
	s_waitcnt vmcnt(19)
	v_dot8_i32_i4 v23, v30, v73, 0
	v_lshl_add_u32 v22, v27, 4, v35
	buffer_load_dwordx2 v[24:25], v192, s[52:55], s0 offen
	v_dot8_i32_i4 v27, v30, v75, 0
	v_dot8_i32_i4 v23, v31, v77, v23
	v_dot8_i32_i4 v27, v31, v108, v27
	s_waitcnt vmcnt(19)
	v_dot8_i32_i4 v30, v20, v75, 0
	v_dot8_i32_i4 v30, v21, v108, v30
	v_lshl_add_u32 v23, v23, 4, v27
	v_dot8_i32_i4 v27, v20, v73, 0
	v_dot8_i32_i4 v27, v21, v77, v27
	s_waitcnt vmcnt(18)
	v_dot8_i32_i4 v21, v16, v73, 0
	v_dot8_i32_i4 v21, v17, v77, v21
	v_lshl_add_u32 v20, v27, 4, v30
	v_dot8_i32_i4 v27, v16, v75, 0
	v_dot8_i32_i4 v27, v17, v108, v27
	v_lshl_add_u32 v9, v9, 4, v86
	s_waitcnt vmcnt(17)
	v_dot8_i32_i4 v17, v12, v73, 0
	v_lshl_add_u32 v16, v21, 4, v27
	v_dot8_i32_i4 v21, v12, v75, 0
	v_cvt_f32_i32_e32 v5, v5
	v_cvt_f32_i32_e32 v9, v9
	v_dot8_i32_i4 v17, v13, v77, v17
	v_dot8_i32_i4 v21, v13, v108, v21
	s_waitcnt vmcnt(16)
	v_dot8_i32_i4 v13, v18, v73, 0
	v_dot8_i32_i4 v13, v19, v77, v13
	v_lshl_add_u32 v12, v17, 4, v21
	v_dot8_i32_i4 v17, v18, v75, 0
	v_dot8_i32_i4 v17, v19, v108, v17
	v_cvt_f32_i32_e32 v54, v54
	v_cvt_f32_i32_e32 v55, v55
	v_cvt_f32_i32_e32 v50, v50
	v_lshl_add_u32 v13, v13, 4, v17
	v_cndmask_b32_e64 v17, v9, v5, s[40:41]
	v_cndmask_b32_e64 v5, v5, v9, s[40:41]
	ds_swizzle_b32 v5, v5 offset:swizzle(SWAP,1)
	v_cvt_f32_i32_e32 v42, v42
	v_cvt_f32_i32_e32 v38, v38
	v_cvt_f32_i32_e32 v39, v39
	v_cvt_f32_i32_e32 v34, v34
	v_cvt_f32_i32_e32 v26, v26
	s_waitcnt lgkmcnt(0)
	v_add_f32_e32 v5, v17, v5
	v_cndmask_b32_e64 v17, v54, v55, s[40:41]
	ds_swizzle_b32 v17, v17 offset:swizzle(SWAP,1)
	v_cndmask_b32_e64 v18, v50, v42, s[40:41]
	ds_swizzle_b32 v18, v18 offset:swizzle(SWAP,1)
	v_cndmask_b32_e64 v19, v38, v39, s[40:41]
	ds_swizzle_b32 v19, v19 offset:swizzle(SWAP,1)
	v_cndmask_b32_e64 v21, v34, v26, s[40:41]
	ds_swizzle_b32 v21, v21 offset:swizzle(SWAP,1)
	v_cvt_f32_i32_e32 v22, v22
	v_cvt_f32_i32_e32 v23, v23
	v_cndmask_b32_e64 v9, v55, v54, s[40:41]
	s_waitcnt lgkmcnt(3)
	v_add_f32_e32 v9, v9, v17
	v_cndmask_b32_e64 v17, v42, v50, s[40:41]
	s_waitcnt lgkmcnt(2)
	v_add_f32_e32 v17, v17, v18
	v_cndmask_b32_e64 v18, v39, v38, s[40:41]
	s_waitcnt lgkmcnt(1)
	v_add_f32_e32 v18, v18, v19
	v_cndmask_b32_e64 v19, v26, v34, s[40:41]
	s_waitcnt lgkmcnt(0)
	v_add_f32_e32 v19, v19, v21
	v_cndmask_b32_e64 v21, v23, v22, s[40:41]
	v_cndmask_b32_e64 v22, v22, v23, s[40:41]
	ds_swizzle_b32 v22, v22 offset:swizzle(SWAP,1)
	v_cvt_f32_i32_e32 v20, v20
	v_cvt_f32_i32_e32 v16, v16
	v_cvt_f32_i32_e32 v12, v12
	v_cvt_f32_i32_e32 v13, v13
	s_waitcnt lgkmcnt(0)
	v_add_f32_e32 v21, v21, v22
	v_cndmask_b32_e64 v22, v16, v20, s[40:41]
	v_cndmask_b32_e64 v16, v20, v16, s[40:41]
	v_cndmask_b32_e64 v20, v13, v12, s[40:41]
	v_cndmask_b32_e64 v12, v12, v13, s[40:41]
	v_cndmask_b32_e64 v13, v9, v5, s[42:43]
	v_cndmask_b32_e64 v5, v5, v9, s[42:43]
	ds_swizzle_b32 v5, v5 offset:swizzle(SWAP,2)
	ds_swizzle_b32 v16, v16 offset:swizzle(SWAP,1)
	ds_swizzle_b32 v12, v12 offset:swizzle(SWAP,1)
	v_cndmask_b32_e64 v9, v18, v17, s[42:43]
	s_waitcnt lgkmcnt(2)
	v_add_f32_e32 v5, v13, v5
	v_cndmask_b32_e64 v13, v17, v18, s[42:43]
	ds_swizzle_b32 v13, v13 offset:swizzle(SWAP,2)
	v_cndmask_b32_e64 v17, v19, v21, s[42:43]
	ds_swizzle_b32 v17, v17 offset:swizzle(SWAP,2)
	s_waitcnt lgkmcnt(3)
	v_add_f32_e32 v16, v22, v16
	s_waitcnt lgkmcnt(2)
	v_add_f32_e32 v12, v20, v12
	s_waitcnt lgkmcnt(1)
	v_add_f32_e32 v9, v9, v13
	v_cndmask_b32_e64 v13, v21, v19, s[42:43]
	s_waitcnt lgkmcnt(0)
	v_add_f32_e32 v13, v13, v17
	v_cndmask_b32_e64 v17, v12, v16, s[42:43]
	v_cndmask_b32_e64 v12, v16, v12, s[42:43]
	ds_swizzle_b32 v12, v12 offset:swizzle(SWAP,2)
	v_cndmask_b32_e64 v16, v9, v5, s[44:45]
	v_cndmask_b32_e64 v5, v5, v9, s[44:45]
	ds_swizzle_b32 v5, v5 offset:swizzle(SWAP,4)
	s_waitcnt lgkmcnt(1)
	v_add_f32_e32 v12, v17, v12
	v_cndmask_b32_e64 v9, v12, v13, s[44:45]
	v_cndmask_b32_e64 v12, v13, v12, s[44:45]
	ds_swizzle_b32 v12, v12 offset:swizzle(SWAP,4)
	s_waitcnt lgkmcnt(1)
	v_add_f32_e32 v5, v16, v5
	s_waitcnt lgkmcnt(0)
	v_add_f32_e32 v9, v9, v12
	v_cndmask_b32_e64 v12, v9, v5, s[46:47]
	v_cndmask_b32_e64 v5, v5, v9, s[46:47]
	ds_swizzle_b32 v5, v5 offset:swizzle(SWAP,8)
	s_waitcnt lgkmcnt(0)
	v_add_f32_e32 v5, v12, v5
	ds_swizzle_b32 v9, v5 offset:swizzle(SWAP,16)
	s_waitcnt lgkmcnt(0)
	v_add_f32_e32 v5, v5, v9
	ds_bpermute_b32 v12, v0, v5
	s_and_saveexec_b64 s[0:1], s[48:49]
	s_cbranch_execz .LBB0_553
	v_ashrrev_i32_e32 v9, 31, v8
	v_lshlrev_b64 v[8:9], 2, v[8:9]
	v_lshl_add_u64 v[16:17], s[8:9], 0, v[8:9]
	global_load_dword v13, v[16:17], off
	v_lshl_add_u64 v[8:9], s[10:11], 0, v[8:9]
	global_load_dword v16, v[6:7], off offset:384
	s_nop 0
	global_load_dword v8, v[8:9], off
	s_waitcnt lgkmcnt(0)
	v_add_f32_e32 v5, v5, v12
	s_waitcnt vmcnt(2)
	v_mul_f32_e32 v5, v5, v13
	v_mul_f32_e32 v5, v3, v5
	v_mul_f32_e32 v12, 0x3d372713, v5
	v_mul_f32_e32 v12, v5, v12
	v_mul_f32_e32 v9, 0.5, v5
	v_fmac_f32_e32 v5, v5, v12
	v_mul_f32_e32 v5, 0x3f4c422a, v5
	v_add_f32_e32 v5, v5, v5
	v_mul_f32_e32 v5, 0x3fb8aa3b, v5
	v_exp_f32_e32 v5, v5
	s_nop 0
	v_add_f32_e32 v5, 1.0, v5
	v_rcp_f32_e32 v5, v5
	s_nop 0
	v_fma_f32 v5, v5, -2.0, 1.0
	v_add_f32_e32 v5, 1.0, v5
	v_mul_f32_e32 v5, v9, v5
	s_waitcnt vmcnt(1)
	v_mul_f32_e32 v5, v16, v5
	s_waitcnt vmcnt(0)
	v_mul_f32_e32 v5, v8, v5
	ds_write_b32 v109, v5 offset:384
.LBB0_553:
	s_or_b64 exec, exec, s[0:1]
	s_waitcnt vmcnt(15)
	v_dot8_i32_i4 v5, v88, v73, 0
	v_dot8_i32_i4 v8, v88, v75, 0
	v_dot8_i32_i4 v5, v89, v77, v5
	v_dot8_i32_i4 v8, v89, v108, v8
	s_waitcnt vmcnt(14)
	v_dot8_i32_i4 v9, v90, v75, 0
	v_dot8_i32_i4 v9, v91, v108, v9
	v_lshl_add_u32 v5, v5, 4, v8
	v_dot8_i32_i4 v8, v90, v73, 0
	v_dot8_i32_i4 v8, v91, v77, v8
	s_waitcnt lgkmcnt(0)
	s_waitcnt vmcnt(13)
	v_dot8_i32_i4 v12, v82, v75, 0
	v_dot8_i32_i4 v12, v83, v108, v12
	v_lshl_add_u32 v8, v8, 4, v9
	v_dot8_i32_i4 v9, v82, v73, 0
	v_dot8_i32_i4 v9, v83, v77, v9
	s_waitcnt vmcnt(12)
	v_dot8_i32_i4 v13, v92, v75, 0
	v_dot8_i32_i4 v13, v93, v108, v13
	v_lshl_add_u32 v9, v9, 4, v12
	v_dot8_i32_i4 v12, v92, v73, 0
	v_dot8_i32_i4 v12, v93, v77, v12
	s_waitcnt vmcnt(11)
	v_dot8_i32_i4 v16, v80, v75, 0
	v_dot8_i32_i4 v16, v81, v108, v16
	v_lshl_add_u32 v12, v12, 4, v13
	v_dot8_i32_i4 v13, v80, v73, 0
	v_dot8_i32_i4 v13, v81, v77, v13
	s_waitcnt vmcnt(10)
	v_dot8_i32_i4 v17, v52, v75, 0
	v_dot8_i32_i4 v17, v53, v108, v17
	v_lshl_add_u32 v13, v13, 4, v16
	v_dot8_i32_i4 v16, v52, v73, 0
	v_dot8_i32_i4 v16, v53, v77, v16
	s_waitcnt vmcnt(9)
	v_dot8_i32_i4 v18, v46, v75, 0
	v_dot8_i32_i4 v18, v47, v108, v18
	v_lshl_add_u32 v16, v16, 4, v17
	v_dot8_i32_i4 v17, v46, v73, 0
	v_dot8_i32_i4 v17, v47, v77, v17
	s_waitcnt vmcnt(8)
	v_dot8_i32_i4 v19, v56, v75, 0
	v_dot8_i32_i4 v19, v57, v108, v19
	v_lshl_add_u32 v17, v17, 4, v18
	v_dot8_i32_i4 v18, v56, v73, 0
	v_dot8_i32_i4 v18, v57, v77, v18
	s_waitcnt vmcnt(7)
	v_dot8_i32_i4 v20, v44, v75, 0
	v_dot8_i32_i4 v20, v45, v108, v20
	v_lshl_add_u32 v18, v18, 4, v19
	v_dot8_i32_i4 v19, v44, v73, 0
	v_dot8_i32_i4 v19, v45, v77, v19
	s_waitcnt vmcnt(6)
	v_dot8_i32_i4 v21, v36, v75, 0
	v_dot8_i32_i4 v21, v37, v108, v21
	v_lshl_add_u32 v19, v19, 4, v20
	v_dot8_i32_i4 v20, v36, v73, 0
	v_dot8_i32_i4 v20, v37, v77, v20
	s_waitcnt vmcnt(5)
	v_dot8_i32_i4 v22, v32, v75, 0
	v_dot8_i32_i4 v22, v33, v108, v22
	v_lshl_add_u32 v20, v20, 4, v21
	v_dot8_i32_i4 v21, v32, v73, 0
	v_dot8_i32_i4 v21, v33, v77, v21
	s_waitcnt vmcnt(4)
	v_dot8_i32_i4 v23, v40, v75, 0
	v_dot8_i32_i4 v23, v41, v108, v23
	v_lshl_add_u32 v21, v21, 4, v22
	v_dot8_i32_i4 v22, v40, v73, 0
	v_dot8_i32_i4 v22, v41, v77, v22
	s_waitcnt vmcnt(3)
	v_dot8_i32_i4 v26, v28, v75, 0
	v_dot8_i32_i4 v26, v29, v108, v26
	v_lshl_add_u32 v22, v22, 4, v23
	v_dot8_i32_i4 v23, v28, v73, 0
	v_dot8_i32_i4 v23, v29, v77, v23
	s_waitcnt vmcnt(2)
	v_dot8_i32_i4 v27, v14, v75, 0
	v_dot8_i32_i4 v27, v15, v108, v27
	v_lshl_add_u32 v23, v23, 4, v26
	v_dot8_i32_i4 v26, v14, v73, 0
	v_dot8_i32_i4 v26, v15, v77, v26
	s_waitcnt vmcnt(1)
	v_dot8_i32_i4 v15, v10, v73, 0
	v_cvt_f32_i32_e32 v5, v5
	v_lshl_add_u32 v14, v26, 4, v27
	v_dot8_i32_i4 v26, v10, v75, 0
	v_cvt_f32_i32_e32 v8, v8
	v_cvt_f32_i32_e32 v9, v9
	v_cvt_f32_i32_e32 v12, v12
	v_dot8_i32_i4 v15, v11, v77, v15
	v_dot8_i32_i4 v26, v11, v108, v26
	s_waitcnt vmcnt(0)
	v_dot8_i32_i4 v11, v24, v73, 0
	v_dot8_i32_i4 v11, v25, v77, v11
	v_lshl_add_u32 v10, v15, 4, v26
	v_dot8_i32_i4 v15, v24, v75, 0
	v_dot8_i32_i4 v15, v25, v108, v15
	v_cvt_f32_i32_e32 v13, v13
	v_cvt_f32_i32_e32 v16, v16
	v_cvt_f32_i32_e32 v17, v17
	v_lshl_add_u32 v11, v11, 4, v15
	v_cndmask_b32_e64 v15, v8, v5, s[40:41]
	v_cndmask_b32_e64 v5, v5, v8, s[40:41]
	v_cndmask_b32_e64 v8, v9, v12, s[40:41]
	ds_swizzle_b32 v8, v8 offset:swizzle(SWAP,1)
	v_cvt_f32_i32_e32 v18, v18
	ds_swizzle_b32 v5, v5 offset:swizzle(SWAP,1)
	v_cvt_f32_i32_e32 v19, v19
	v_cvt_f32_i32_e32 v20, v20
	v_cvt_f32_i32_e32 v21, v21
	v_cvt_f32_i32_e32 v22, v22
	v_cndmask_b32_e64 v9, v12, v9, s[40:41]
	v_cndmask_b32_e64 v24, v13, v16, s[40:41]
	s_waitcnt lgkmcnt(1)
	v_add_f32_e32 v8, v9, v8
	v_cndmask_b32_e64 v9, v16, v13, s[40:41]
	v_cndmask_b32_e64 v13, v17, v18, s[40:41]
	s_waitcnt lgkmcnt(0)
	v_add_f32_e32 v5, v15, v5
	ds_swizzle_b32 v13, v13 offset:swizzle(SWAP,1)
	v_cndmask_b32_e64 v15, v19, v20, s[40:41]
	ds_swizzle_b32 v15, v15 offset:swizzle(SWAP,1)
	v_cndmask_b32_e64 v16, v21, v22, s[40:41]
	ds_swizzle_b32 v16, v16 offset:swizzle(SWAP,1)
	v_cvt_f32_i32_e32 v23, v23
	v_cvt_f32_i32_e32 v14, v14
	v_cvt_f32_i32_e32 v10, v10
	v_cvt_f32_i32_e32 v11, v11
	v_cndmask_b32_e64 v12, v18, v17, s[40:41]
	s_waitcnt lgkmcnt(2)
	v_add_f32_e32 v12, v12, v13
	v_cndmask_b32_e64 v13, v20, v19, s[40:41]
	s_waitcnt lgkmcnt(1)
	v_add_f32_e32 v13, v13, v15
	v_cndmask_b32_e64 v15, v22, v21, s[40:41]
	ds_swizzle_b32 v24, v24 offset:swizzle(SWAP,1)
	s_waitcnt lgkmcnt(1)
	v_add_f32_e32 v15, v15, v16
	v_cndmask_b32_e64 v16, v14, v23, s[40:41]
	v_cndmask_b32_e64 v14, v23, v14, s[40:41]
	v_cndmask_b32_e64 v17, v10, v11, s[40:41]
	ds_swizzle_b32 v14, v14 offset:swizzle(SWAP,1)
	ds_swizzle_b32 v17, v17 offset:swizzle(SWAP,1)
	s_waitcnt lgkmcnt(2)
	v_add_f32_e32 v9, v9, v24
	v_cndmask_b32_e64 v10, v11, v10, s[40:41]
	v_cndmask_b32_e64 v18, v5, v8, s[42:43]
	s_waitcnt lgkmcnt(1)
	v_add_f32_e32 v14, v16, v14
	s_waitcnt lgkmcnt(0)
	v_add_f32_e32 v10, v10, v17
	v_cndmask_b32_e64 v5, v8, v5, s[42:43]
	v_cndmask_b32_e64 v8, v12, v9, s[42:43]
	v_cndmask_b32_e64 v9, v9, v12, s[42:43]
	ds_swizzle_b32 v9, v9 offset:swizzle(SWAP,2)
	v_cndmask_b32_e64 v11, v13, v15, s[42:43]
	v_cndmask_b32_e64 v12, v14, v10, s[42:43]
	ds_swizzle_b32 v18, v18 offset:swizzle(SWAP,2)
	ds_swizzle_b32 v11, v11 offset:swizzle(SWAP,2)
	ds_swizzle_b32 v12, v12 offset:swizzle(SWAP,2)
	s_waitcnt lgkmcnt(3)
	v_add_f32_e32 v8, v8, v9
	v_cndmask_b32_e64 v9, v15, v13, s[42:43]
	v_cndmask_b32_e64 v10, v10, v14, s[42:43]
	s_waitcnt lgkmcnt(2)
	v_add_f32_e32 v5, v5, v18
	s_waitcnt lgkmcnt(1)
	v_add_f32_e32 v9, v9, v11
	s_waitcnt lgkmcnt(0)
	v_add_f32_e32 v10, v10, v12
	v_cndmask_b32_e64 v11, v5, v8, s[44:45]
	v_cndmask_b32_e64 v12, v9, v10, s[44:45]
	ds_swizzle_b32 v11, v11 offset:swizzle(SWAP,4)
	ds_swizzle_b32 v12, v12 offset:swizzle(SWAP,4)
	v_cndmask_b32_e64 v5, v8, v5, s[44:45]
	v_cndmask_b32_e64 v8, v10, v9, s[44:45]
	s_waitcnt lgkmcnt(1)
	v_add_f32_e32 v5, v5, v11
	s_waitcnt lgkmcnt(0)
	v_add_f32_e32 v8, v8, v12
	v_cndmask_b32_e64 v9, v5, v8, s[46:47]
	ds_swizzle_b32 v9, v9 offset:swizzle(SWAP,8)
	v_cndmask_b32_e64 v5, v8, v5, s[46:47]
	s_waitcnt lgkmcnt(0)
	v_add_f32_e32 v5, v5, v9
	ds_swizzle_b32 v8, v5 offset:swizzle(SWAP,16)
	s_waitcnt lgkmcnt(0)
	v_add_f32_e32 v8, v5, v8
	ds_bpermute_b32 v0, v0, v8
	s_and_saveexec_b64 s[0:1], s[48:49]
	s_cbranch_execz .LBB0_536
	v_ashrrev_i32_e32 v5, 31, v4
	v_lshlrev_b64 v[4:5], 2, v[4:5]
	v_lshl_add_u64 v[10:11], s[8:9], 0, v[4:5]
	global_load_dword v9, v[10:11], off
	v_lshl_add_u64 v[4:5], s[10:11], 0, v[4:5]
	global_load_dword v6, v[6:7], off offset:448
	s_nop 0
	global_load_dword v4, v[4:5], off
	s_waitcnt lgkmcnt(0)
	v_add_f32_e32 v0, v8, v0
	s_waitcnt vmcnt(2)
	v_mul_f32_e32 v0, v0, v9
	v_mul_f32_e32 v0, v3, v0
	v_mul_f32_e32 v5, 0x3d372713, v0
	v_mul_f32_e32 v5, v0, v5
	v_mul_f32_e32 v3, 0.5, v0
	v_fmac_f32_e32 v0, v0, v5
	v_mul_f32_e32 v0, 0x3f4c422a, v0
	v_add_f32_e32 v0, v0, v0
	v_mul_f32_e32 v0, 0x3fb8aa3b, v0
	v_exp_f32_e32 v0, v0
	s_nop 0
	v_add_f32_e32 v0, 1.0, v0
	v_rcp_f32_e32 v0, v0
	s_nop 0
	v_fma_f32 v0, v0, -2.0, 1.0
	v_add_f32_e32 v0, 1.0, v0
	v_mul_f32_e32 v0, v3, v0
	s_waitcnt vmcnt(1)
	v_mul_f32_e32 v0, v6, v0
	s_waitcnt vmcnt(0)
	v_mul_f32_e32 v0, v4, v0
	ds_write_b32 v109, v0 offset:448
	s_branch .LBB0_536
